# speedup vs baseline: 1.0101x; 1.0073x over previous
; #define WAIT_V(n) asm volatile("s_waitcnt vmcnt(" #n ")" ::: "memory")
; #define BAR __builtin_amdgcn_s_barrier()
; template <int MODE>
; __device__ __forceinline__ void gemm_tile(const int ph, const int which, const int pm, const int pn) {
;     ...
;   const int wid = gtid >> 6, lane = gtid & 63, wr = wid >> 2, wc = wid & 3, fr = lane & 15,
;             fq = lane >> 4;
;   __amdgpu_buffer_rsrc_t RA = __builtin_amdgcn_make_buffer_rsrc((void*)A, 0, 0x7ffffff0, 0x00020000);
;   __amdgpu_buffer_rsrc_t RB = __builtin_amdgcn_make_buffer_rsrc((void*)Bt, 0, 0x7ffffff0, 0x00020000);
;   int voff;
;   {
;     int _r, _c;
;     stage_rc(gtid * 16, _r, _c);
;     voff = (_r * K + _c) * 2;
;   }
;   f32x4 acc[2][2][4][2] = {};
;   bf16x8 At[4][2], B0[2][2], B1[2][2];
;   const int nt = K / BK;
;   const int brow = browA;
;   STAGE(SB(0, 0), RB, bcol, 0);
;   STAGE(SA(0, 0), RA, brow, 0);
;   STAGE(SB(0, 1), RB, bcolB, 0);
;   STAGE(SA(0, 1), RA, brow + HALF, 0);
;   if (wr == 1) BAR;
;   WAIT_V(4);
;   BAR;
;   STAGE(SB(1, 0), RB, bcol, 1);
;   STAGE(SA(1, 0), RA, brow, 1);
;   STAGE(SB(1, 1), RB, bcolB, 1);
;   WAIT_V(6);
;   BAR;
.LBB0_130:
	s_or_b64 exec, exec, s[2:3]
	v_add_u32_e32 v149, 0x18000, v139
	v_add_u32_e32 v150, 0x1a000, v139
	v_readfirstlane_b32 s6, v149
	s_or_b32 s3, s19, 0x80
	s_mov_b32 m0, s6
	v_readfirstlane_b32 s6, v150
	v_add_u32_e32 v151, 0x8000, v139
	s_waitcnt vmcnt(4)
	s_barrier
	buffer_load_dwordx4 v138, s[68:71], s3 offen lds
	s_add_i32 s3, s3, s10
	s_mov_b32 m0, s6
	v_readfirstlane_b32 s12, v151
	v_add_u32_e32 v152, 0xa000, v139
	buffer_load_dwordx4 v138, s[68:71], s3 offen lds
	s_or_b32 s3, s17, 0x80
	s_mov_b32 s6, s70
	s_mov_b32 s7, s71
	s_mov_b32 m0, s12
	v_readfirstlane_b32 s12, v152
	v_add_u32_e32 v154, 0x1c000, v139
	buffer_load_dwordx4 v138, s[4:7], s3 offen lds
	s_add_i32 s3, s3, s10
	s_mov_b32 m0, s12
	v_readfirstlane_b32 s12, v154
	v_add_u32_e32 v156, 0x1e000, v139
	buffer_load_dwordx4 v138, s[4:7], s3 offen lds
	s_or_b32 s3, s16, 0x80
	s_mov_b32 m0, s12
	v_readfirstlane_b32 s12, v156
	buffer_load_dwordx4 v138, s[68:71], s3 offen lds
	s_add_i32 s3, s3, s10
	s_mov_b32 m0, s12
	v_and_b32_e32 v3, 15, v0
	buffer_load_dwordx4 v138, s[68:71], s3 offen lds
	v_bfe_u32 v132, v0, 4, 2
	v_lshlrev_b32_e32 v5, 4, v132
	v_lshlrev_b32_e32 v6, 6, v3
	v_lshlrev_b32_e32 v8, 2, v0
	v_or_b32_e32 v7, v5, v6
	v_and_b32_e32 v8, 32, v8
	s_mov_b32 s3, 0x10000
	v_bitop3_b32 v9, v7, s3, v8 bitop3:0xde
	s_mov_b32 s3, 0x14000
	v_bitop3_b32 v10, v7, s3, v8 bitop3:0xde
	s_mov_b32 s3, 0x18000
	v_bitop3_b32 v11, v7, s3, v8 bitop3:0xde
	s_mov_b32 s3, 0x1c000
	s_lshl_b32 s12, s22, 1
	v_bitop3_b32 v7, v7, s3, v8 bitop3:0xde
	v_lshl_or_b32 v133, v2, 6, v3
	v_lshlrev_b32_e32 v3, 13, v2
	v_lshlrev_b32_e32 v2, 6, v0
	s_add_i32 s3, s12, 0x180
	s_addk_i32 s12, 0x80
	v_bfe_u32 v131, v0, 6, 2
	v_and_b32_e32 v2, 0x3c0, v2
	s_lshl_b32 s17, s18, 1
	s_mul_i32 s19, s26, s12
	s_lshl_b32 s12, s24, 1
	s_lshr_b32 s2, s26, 6
	v_lshlrev_b32_e32 v4, 12, v131
	v_bitop3_b32 v6, v5, v8, v6 bitop3:0x36
	v_bitop3_b32 v5, v2, v8, v5 bitop3:0x36
	v_or_b32_e32 v8, 0x800, v3
	v_or_b32_e32 v12, 0x1000, v3
	v_or_b32_e32 v13, 0x1800, v3
	s_lshl_b32 s13, s26, 1
	s_add_i32 s16, s22, 0x80
	s_addk_i32 s17, 0x80
	s_addk_i32 s12, 0x80
	v_mov_b32_e32 v2, 0
	v_lshrrev_b32_e32 v130, 4, v0
	s_add_i32 s2, s2, -2
	v_add_u32_e32 v155, 0xc000, v139
	v_add_u32_e32 v153, 0xe000, v139
	s_mul_i32 s3, s26, s3
	s_mul_i32 s16, s13, s16
	s_mul_i32 s17, s26, s17
	s_mul_i32 s18, s13, s18
	s_mul_i32 s22, s13, s22
	s_mul_i32 s23, s26, s12
	s_mul_i32 s24, s13, s24
	s_mov_b32 s25, 0
	v_add_u32_e32 v158, v9, v4
	v_add_u32_e32 v137, v6, v3
	v_add_u32_e32 v136, v5, v8
	v_add_u32_e32 v135, v5, v12
	v_add_u32_e32 v134, v5, v13
	v_add_u32_e32 v157, v10, v4
	v_add_u32_e32 v146, v11, v4
	v_add_u32_e32 v140, v7, v4
	s_mov_b32 s27, 0
	v_mov_b32_e32 v3, v2
	v_mov_b32_e32 v4, v2
	v_mov_b32_e32 v5, v2
	v_mov_b32_e32 v6, v2
	v_mov_b32_e32 v7, v2
	v_mov_b32_e32 v8, v2
	v_mov_b32_e32 v9, v2
	v_mov_b32_e32 v10, v2
	v_mov_b32_e32 v11, v2
	v_mov_b32_e32 v12, v2
	v_mov_b32_e32 v13, v2
	v_mov_b32_e32 v14, v2
	v_mov_b32_e32 v15, v2
	v_mov_b32_e32 v16, v2
	v_mov_b32_e32 v17, v2
	v_mov_b32_e32 v18, v2
	v_mov_b32_e32 v19, v2
	v_mov_b32_e32 v20, v2
	v_mov_b32_e32 v21, v2
	v_mov_b32_e32 v22, v2
	v_mov_b32_e32 v23, v2
	v_mov_b32_e32 v24, v2
	v_mov_b32_e32 v25, v2
	v_mov_b32_e32 v26, v2
	v_mov_b32_e32 v27, v2
	v_mov_b32_e32 v28, v2
	v_mov_b32_e32 v29, v2
	v_mov_b32_e32 v30, v2
	v_mov_b32_e32 v31, v2
	v_mov_b32_e32 v32, v2
	v_mov_b32_e32 v33, v2
	v_mov_b32_e32 v34, v2
	v_mov_b32_e32 v35, v2
	v_mov_b32_e32 v36, v2
	v_mov_b32_e32 v37, v2
	v_mov_b32_e32 v38, v2
	v_mov_b32_e32 v39, v2
	v_mov_b32_e32 v40, v2
	v_mov_b32_e32 v41, v2
	v_mov_b32_e32 v42, v2
	v_mov_b32_e32 v43, v2
	v_mov_b32_e32 v44, v2
	v_mov_b32_e32 v45, v2
	v_mov_b32_e32 v46, v2
	v_mov_b32_e32 v47, v2
	v_mov_b32_e32 v48, v2
	v_mov_b32_e32 v49, v2
	v_mov_b32_e32 v50, v2
	v_mov_b32_e32 v51, v2
	v_mov_b32_e32 v52, v2
	v_mov_b32_e32 v53, v2
	v_mov_b32_e32 v54, v2
	v_mov_b32_e32 v55, v2
	v_mov_b32_e32 v56, v2
	v_mov_b32_e32 v57, v2
	v_mov_b32_e32 v58, v2
	v_mov_b32_e32 v59, v2
	v_mov_b32_e32 v60, v2
	v_mov_b32_e32 v61, v2
	v_mov_b32_e32 v62, v2
	v_mov_b32_e32 v63, v2
	v_mov_b32_e32 v64, v2
	v_mov_b32_e32 v65, v2
	v_mov_b32_e32 v66, v2
	v_mov_b32_e32 v67, v2
	v_mov_b32_e32 v68, v2
	v_mov_b32_e32 v69, v2
	v_mov_b32_e32 v70, v2
	v_mov_b32_e32 v71, v2
	v_mov_b32_e32 v72, v2
	v_mov_b32_e32 v73, v2
	v_mov_b32_e32 v74, v2
	v_mov_b32_e32 v75, v2
	v_mov_b32_e32 v76, v2
	v_mov_b32_e32 v77, v2
	v_mov_b32_e32 v78, v2
	v_mov_b32_e32 v79, v2
	v_mov_b32_e32 v80, v2
	v_mov_b32_e32 v81, v2
	v_mov_b32_e32 v82, v2
	v_mov_b32_e32 v83, v2
	v_mov_b32_e32 v84, v2
	v_mov_b32_e32 v85, v2
	v_mov_b32_e32 v86, v2
	v_mov_b32_e32 v87, v2
	v_mov_b32_e32 v88, v2
	v_mov_b32_e32 v89, v2
	v_mov_b32_e32 v90, v2
	v_mov_b32_e32 v91, v2
	v_mov_b32_e32 v92, v2
	v_mov_b32_e32 v93, v2
	v_mov_b32_e32 v94, v2
	v_mov_b32_e32 v95, v2
	v_mov_b32_e32 v96, v2
	v_mov_b32_e32 v97, v2
	v_mov_b32_e32 v98, v2
	v_mov_b32_e32 v99, v2
	v_mov_b32_e32 v100, v2
	v_mov_b32_e32 v101, v2
	v_mov_b32_e32 v102, v2
	v_mov_b32_e32 v103, v2
	v_mov_b32_e32 v104, v2
	v_mov_b32_e32 v105, v2
	v_mov_b32_e32 v106, v2
	v_mov_b32_e32 v107, v2
	v_mov_b32_e32 v108, v2
	v_mov_b32_e32 v109, v2
	v_mov_b32_e32 v110, v2
	v_mov_b32_e32 v111, v2
	v_mov_b32_e32 v112, v2
	v_mov_b32_e32 v113, v2
	v_mov_b32_e32 v114, v2
	v_mov_b32_e32 v115, v2
	v_mov_b32_e32 v116, v2
	v_mov_b32_e32 v117, v2
	v_mov_b32_e32 v118, v2
	v_mov_b32_e32 v119, v2
	v_mov_b32_e32 v120, v2
	v_mov_b32_e32 v121, v2
	v_mov_b32_e32 v122, v2
	v_mov_b32_e32 v123, v2
	v_mov_b32_e32 v124, v2
	v_mov_b32_e32 v125, v2
	v_mov_b32_e32 v126, v2
	v_mov_b32_e32 v127, v2
	v_mov_b32_e32 v128, v2
	v_mov_b32_e32 v129, v2
	s_waitcnt vmcnt(6)

; #define WAIT_V(n) asm volatile("s_waitcnt vmcnt(" #n ")" ::: "memory")
; #define WAIT_L(n) asm volatile("s_waitcnt lgkmcnt(" #n ")" ::: "memory")
; #define BAR __builtin_amdgcn_s_barrier()
; #define SCHED __builtin_amdgcn_sched_barrier(0)
; template <int MODE>
; __device__ __forceinline__ void gemm_tile(const int ph, const int which, const int pm, const int pn) {
;     ...
;   for (int t = 0; t < nt - 2; t += 2) {
;     LDB(B0, 0, 0); SCHED; LDA(At, 0, 0); STAGE(SA(1, 1), RA, brow + HALF, t + 1);
;     WAIT_L(8); BAR; WAIT_L(0); MMA(0, 0, At, B0); BAR; SCHED;
;     LDB(B1, 0, 1); STAGE(SB(0, 0), RB, bcol, t + 2);
;     BAR; WAIT_L(0); MMA(0, 1, At, B1); BAR;
;     LDA(At, 0, 1); STAGE(SA(0, 0), RA, brow, t + 2);
;     BAR; WAIT_L(0); MMA(1, 0, At, B0); BAR; SCHED;
;     STAGE(SB(0, 1), RB, bcolB, t + 2);
;     WAIT_V(6); BAR; MMA(1, 1, At, B1); BAR;
.LBB0_131:
	ds_read_b128 v[160:163], v158
	ds_read_b128 v[164:167], v158 offset:1024
	ds_read_b128 v[168:171], v158 offset:2048
	ds_read_b128 v[172:175], v158 offset:3072
	s_add_i32 s12, s16, s25
	v_readfirstlane_b32 s28, v155
	s_add_i32 s13, s12, 0x80
	s_mov_b32 m0, s28
	ds_read_b128 v[176:179], v137
	ds_read_b128 v[180:183], v137 offset:1024
	ds_read_b128 v[184:187], v136
	ds_read_b128 v[188:191], v136 offset:1024
	ds_read_b128 v[192:195], v135
	ds_read_b128 v[196:199], v135 offset:1024
	ds_read_b128 v[200:203], v134
	ds_read_b128 v[204:207], v134 offset:1024
	buffer_load_dwordx4 v138, s[4:7], s13 offen lds
	s_add_i32 s13, s3, s25
	v_readfirstlane_b32 s29, v153
	s_add_i32 s28, s13, 0x80
	s_mov_b32 m0, s29
	s_nop 0
	buffer_load_dwordx4 v138, s[4:7], s28 offen lds
	s_waitcnt lgkmcnt(8)
	s_barrier
	s_waitcnt lgkmcnt(0)
	s_setprio 1
	s_waitcnt lgkmcnt(7)
	v_mfma_f32_16x16x32_bf16 v[126:129], v[160:163], v[176:179], v[126:129]
	v_mfma_f32_16x16x32_bf16 v[122:125], v[168:171], v[176:179], v[122:125]
	s_waitcnt lgkmcnt(5)
	v_mfma_f32_16x16x32_bf16 v[118:121], v[160:163], v[184:187], v[118:121]
	v_mfma_f32_16x16x32_bf16 v[114:117], v[168:171], v[184:187], v[114:117]
	s_waitcnt lgkmcnt(3)
	v_mfma_f32_16x16x32_bf16 v[110:113], v[160:163], v[192:195], v[110:113]
	v_mfma_f32_16x16x32_bf16 v[106:109], v[168:171], v[192:195], v[106:109]
	s_waitcnt lgkmcnt(1)
	v_mfma_f32_16x16x32_bf16 v[102:105], v[160:163], v[200:203], v[102:105]
	v_mfma_f32_16x16x32_bf16 v[98:101], v[168:171], v[200:203], v[98:101]
	v_mfma_f32_16x16x32_bf16 v[126:129], v[164:167], v[180:183], v[126:129]
	v_mfma_f32_16x16x32_bf16 v[122:125], v[172:175], v[180:183], v[122:125]
	v_mfma_f32_16x16x32_bf16 v[118:121], v[164:167], v[188:191], v[118:121]
	v_mfma_f32_16x16x32_bf16 v[114:117], v[172:175], v[188:191], v[114:117]
	v_mfma_f32_16x16x32_bf16 v[110:113], v[164:167], v[196:199], v[110:113]
	v_mfma_f32_16x16x32_bf16 v[106:109], v[172:175], v[196:199], v[106:109]
	s_waitcnt lgkmcnt(0)
	v_mfma_f32_16x16x32_bf16 v[102:105], v[164:167], v[204:207], v[102:105]
	v_mfma_f32_16x16x32_bf16 v[98:101], v[172:175], v[204:207], v[98:101]
	s_setprio 0
	s_barrier
	s_add_i32 s28, s24, s25
	v_readfirstlane_b32 s38, v141
	s_add_i32 s29, s28, 0x100
	s_mov_b32 m0, s38
	ds_read_b128 v[236:239], v157
	ds_read_b128 v[240:243], v157 offset:1024
	ds_read_b128 v[244:247], v157 offset:2048
	ds_read_b128 v[248:251], v157 offset:3072
	buffer_load_dwordx4 v138, s[68:71], s29 offen lds
	s_add_i32 s29, s23, s25
	v_readfirstlane_b32 s43, v142
	s_add_i32 s38, s29, 0x100
	s_mov_b32 m0, s43
	s_add_i32 s27, s27, 2
	buffer_load_dwordx4 v138, s[68:71], s38 offen lds
	s_barrier
	s_waitcnt lgkmcnt(0)
	s_setprio 1
	s_waitcnt lgkmcnt(3)
	v_mfma_f32_16x16x32_bf16 v[94:97], v[236:239], v[176:179], v[94:97]
	s_waitcnt lgkmcnt(1)
	v_mfma_f32_16x16x32_bf16 v[90:93], v[244:247], v[176:179], v[90:93]
	v_mfma_f32_16x16x32_bf16 v[86:89], v[236:239], v[184:187], v[86:89]
	v_mfma_f32_16x16x32_bf16 v[82:85], v[244:247], v[184:187], v[82:85]
	v_mfma_f32_16x16x32_bf16 v[78:81], v[236:239], v[192:195], v[78:81]
	v_mfma_f32_16x16x32_bf16 v[74:77], v[244:247], v[192:195], v[74:77]
	v_mfma_f32_16x16x32_bf16 v[70:73], v[236:239], v[200:203], v[70:73]
	v_mfma_f32_16x16x32_bf16 v[66:69], v[244:247], v[200:203], v[66:69]
	v_mfma_f32_16x16x32_bf16 v[94:97], v[240:243], v[180:183], v[94:97]
	s_waitcnt lgkmcnt(0)
	v_mfma_f32_16x16x32_bf16 v[90:93], v[248:251], v[180:183], v[90:93]
	v_mfma_f32_16x16x32_bf16 v[86:89], v[240:243], v[188:191], v[86:89]
	v_mfma_f32_16x16x32_bf16 v[82:85], v[248:251], v[188:191], v[82:85]
	v_mfma_f32_16x16x32_bf16 v[78:81], v[240:243], v[196:199], v[78:81]
	v_mfma_f32_16x16x32_bf16 v[74:77], v[248:251], v[196:199], v[74:77]
	v_mfma_f32_16x16x32_bf16 v[70:73], v[240:243], v[204:207], v[70:73]
	v_mfma_f32_16x16x32_bf16 v[66:69], v[248:251], v[204:207], v[66:69]
	s_setprio 0
	s_add_i32 s38, s22, s25
	v_readfirstlane_b32 s50, v139
	s_add_i32 s43, s38, 0x100
	s_mov_b32 m0, s50
	s_barrier
	ds_read_b128 v[176:179], v137 offset:16384
	ds_read_b128 v[180:183], v137 offset:17408
	ds_read_b128 v[184:187], v136 offset:16384
	ds_read_b128 v[188:191], v136 offset:17408
	ds_read_b128 v[192:195], v135 offset:16384
	ds_read_b128 v[196:199], v135 offset:17408
	ds_read_b128 v[200:203], v134 offset:16384
	ds_read_b128 v[204:207], v134 offset:17408
	buffer_load_dwordx4 v138, s[4:7], s43 offen lds
	s_add_i32 s43, s19, s25
	v_readfirstlane_b32 s51, v143
	s_add_i32 s50, s43, 0x100
	s_mov_b32 m0, s51
	s_nop 0
	buffer_load_dwordx4 v138, s[4:7], s50 offen lds
	s_barrier
	s_waitcnt lgkmcnt(0)
	s_setprio 1
	s_waitcnt lgkmcnt(7)
	v_mfma_f32_16x16x32_bf16 v[62:65], v[160:163], v[176:179], v[62:65]
	v_mfma_f32_16x16x32_bf16 v[58:61], v[168:171], v[176:179], v[58:61]
	s_waitcnt lgkmcnt(5)
	v_mfma_f32_16x16x32_bf16 v[54:57], v[160:163], v[184:187], v[54:57]
	v_mfma_f32_16x16x32_bf16 v[50:53], v[168:171], v[184:187], v[50:53]
	s_waitcnt lgkmcnt(3)
	v_mfma_f32_16x16x32_bf16 v[46:49], v[160:163], v[192:195], v[46:49]
	v_mfma_f32_16x16x32_bf16 v[42:45], v[168:171], v[192:195], v[42:45]
	s_waitcnt lgkmcnt(1)
	v_mfma_f32_16x16x32_bf16 v[38:41], v[160:163], v[200:203], v[38:41]
	v_mfma_f32_16x16x32_bf16 v[34:37], v[168:171], v[200:203], v[34:37]
	v_mfma_f32_16x16x32_bf16 v[62:65], v[164:167], v[180:183], v[62:65]
	v_mfma_f32_16x16x32_bf16 v[58:61], v[172:175], v[180:183], v[58:61]
	v_mfma_f32_16x16x32_bf16 v[54:57], v[164:167], v[188:191], v[54:57]
	v_mfma_f32_16x16x32_bf16 v[50:53], v[172:175], v[188:191], v[50:53]
	v_mfma_f32_16x16x32_bf16 v[46:49], v[164:167], v[196:199], v[46:49]
	v_mfma_f32_16x16x32_bf16 v[42:45], v[172:175], v[196:199], v[42:45]
	s_waitcnt lgkmcnt(0)
	v_mfma_f32_16x16x32_bf16 v[38:41], v[164:167], v[204:207], v[38:41]
	v_mfma_f32_16x16x32_bf16 v[34:37], v[172:175], v[204:207], v[34:37]
	s_setprio 0
	s_barrier
; #define WAIT_V(n) asm volatile("s_waitcnt vmcnt(" #n ")" ::: "memory")
; #define WAIT_L(n) asm volatile("s_waitcnt lgkmcnt(" #n ")" ::: "memory")
; #define BAR __builtin_amdgcn_s_barrier()
; #define SCHED __builtin_amdgcn_sched_barrier(0)
; template <int MODE>
; __device__ __forceinline__ void gemm_tile(const int ph, const int which, const int pm, const int pn) {
;     ...
;     STAGE(SB(0, 1), RB, bcolB, t + 2);
;     WAIT_V(6); BAR; MMA(1, 1, At, B1); BAR;
;     LDB(B0, 1, 0); SCHED; LDA(At, 1, 0); STAGE(SA(0, 1), RA, brow + HALF, t + 2);
;     WAIT_L(8); BAR; WAIT_L(0); MMA(0, 0, At, B0); BAR; SCHED;
;     LDB(B1, 1, 1); STAGE(SB(1, 0), RB, bcol, t + 3);
;     BAR; WAIT_L(0); MMA(0, 1, At, B1); BAR;
;     LDA(At, 1, 1); STAGE(SA(1, 0), RA, brow, t + 3);
;     BAR; WAIT_L(0); MMA(1, 0, At, B0); BAR; SCHED;
	s_add_i32 s50, s18, s25
	v_readfirstlane_b32 s72, v144
	s_add_i32 s51, s50, 0x100
	s_mov_b32 m0, s72
	v_readfirstlane_b32 s73, v145
	buffer_load_dwordx4 v138, s[68:71], s51 offen lds
	s_add_i32 s51, s17, s25
	s_add_i32 s72, s51, 0x100
	s_mov_b32 m0, s73
	s_nop 0
	buffer_load_dwordx4 v138, s[68:71], s72 offen lds
	s_waitcnt vmcnt(6)
	s_barrier
	s_setprio 1
	v_mfma_f32_16x16x32_bf16 v[30:33], v[236:239], v[176:179], v[30:33]
	v_mfma_f32_16x16x32_bf16 v[26:29], v[244:247], v[176:179], v[26:29]
	v_mfma_f32_16x16x32_bf16 v[22:25], v[236:239], v[184:187], v[22:25]
	v_mfma_f32_16x16x32_bf16 v[18:21], v[244:247], v[184:187], v[18:21]
	v_mfma_f32_16x16x32_bf16 v[14:17], v[236:239], v[192:195], v[14:17]
	v_mfma_f32_16x16x32_bf16 v[10:13], v[244:247], v[192:195], v[10:13]
	v_mfma_f32_16x16x32_bf16 v[6:9], v[236:239], v[200:203], v[6:9]
	v_mfma_f32_16x16x32_bf16 v[2:5], v[244:247], v[200:203], v[2:5]
	v_mfma_f32_16x16x32_bf16 v[30:33], v[240:243], v[180:183], v[30:33]
	v_mfma_f32_16x16x32_bf16 v[26:29], v[248:251], v[180:183], v[26:29]
	v_mfma_f32_16x16x32_bf16 v[22:25], v[240:243], v[188:191], v[22:25]
	v_mfma_f32_16x16x32_bf16 v[18:21], v[248:251], v[188:191], v[18:21]
	v_mfma_f32_16x16x32_bf16 v[14:17], v[240:243], v[196:199], v[14:17]
	v_mfma_f32_16x16x32_bf16 v[10:13], v[248:251], v[196:199], v[10:13]
	v_mfma_f32_16x16x32_bf16 v[6:9], v[240:243], v[204:207], v[6:9]
	v_mfma_f32_16x16x32_bf16 v[2:5], v[248:251], v[204:207], v[2:5]
	s_setprio 0
	s_barrier
	ds_read_b128 v[160:163], v146
	ds_read_b128 v[164:167], v146 offset:1024
	ds_read_b128 v[168:171], v146 offset:2048
	ds_read_b128 v[172:175], v146 offset:3072
	v_readfirstlane_b32 s72, v147
	s_addk_i32 s12, 0x100
	s_mov_b32 m0, s72
	ds_read_b128 v[176:179], v137 offset:32768
	ds_read_b128 v[180:183], v137 offset:33792
	ds_read_b128 v[184:187], v136 offset:32768
	ds_read_b128 v[188:191], v136 offset:33792
	ds_read_b128 v[192:195], v135 offset:32768
	ds_read_b128 v[196:199], v135 offset:33792
	ds_read_b128 v[200:203], v134 offset:32768
	ds_read_b128 v[204:207], v134 offset:33792
	buffer_load_dwordx4 v138, s[4:7], s12 offen lds
	v_readfirstlane_b32 s12, v148
	s_addk_i32 s13, 0x100
	s_mov_b32 m0, s12
	s_nop 0
	buffer_load_dwordx4 v138, s[4:7], s13 offen lds
	s_waitcnt lgkmcnt(8)
	s_barrier
	s_waitcnt lgkmcnt(0)
	s_setprio 1
	s_waitcnt lgkmcnt(7)
	v_mfma_f32_16x16x32_bf16 v[126:129], v[160:163], v[176:179], v[126:129]
	v_mfma_f32_16x16x32_bf16 v[122:125], v[168:171], v[176:179], v[122:125]
	s_waitcnt lgkmcnt(5)
	v_mfma_f32_16x16x32_bf16 v[118:121], v[160:163], v[184:187], v[118:121]
	v_mfma_f32_16x16x32_bf16 v[114:117], v[168:171], v[184:187], v[114:117]
	s_waitcnt lgkmcnt(3)
	v_mfma_f32_16x16x32_bf16 v[110:113], v[160:163], v[192:195], v[110:113]
	v_mfma_f32_16x16x32_bf16 v[106:109], v[168:171], v[192:195], v[106:109]
	s_waitcnt lgkmcnt(1)
	v_mfma_f32_16x16x32_bf16 v[102:105], v[160:163], v[200:203], v[102:105]
	v_mfma_f32_16x16x32_bf16 v[98:101], v[168:171], v[200:203], v[98:101]
	v_mfma_f32_16x16x32_bf16 v[126:129], v[164:167], v[180:183], v[126:129]
	v_mfma_f32_16x16x32_bf16 v[122:125], v[172:175], v[180:183], v[122:125]
	v_mfma_f32_16x16x32_bf16 v[118:121], v[164:167], v[188:191], v[118:121]
	v_mfma_f32_16x16x32_bf16 v[114:117], v[172:175], v[188:191], v[114:117]
	v_mfma_f32_16x16x32_bf16 v[110:113], v[164:167], v[196:199], v[110:113]
	v_mfma_f32_16x16x32_bf16 v[106:109], v[172:175], v[196:199], v[106:109]
	s_waitcnt lgkmcnt(0)
	v_mfma_f32_16x16x32_bf16 v[102:105], v[164:167], v[204:207], v[102:105]
	v_mfma_f32_16x16x32_bf16 v[98:101], v[172:175], v[204:207], v[98:101]
	s_setprio 0
	s_barrier
	v_readfirstlane_b32 s12, v149
	s_addk_i32 s28, 0x180
	s_mov_b32 m0, s12
	v_readfirstlane_b32 s12, v150
	ds_read_b128 v[236:239], v140
	ds_read_b128 v[240:243], v140 offset:1024
	ds_read_b128 v[244:247], v140 offset:2048
	ds_read_b128 v[248:251], v140 offset:3072
	buffer_load_dwordx4 v138, s[68:71], s28 offen lds
	s_addk_i32 s29, 0x180
	s_mov_b32 m0, s12
	s_nop 0
	buffer_load_dwordx4 v138, s[68:71], s29 offen lds
	s_barrier
	s_waitcnt lgkmcnt(0)
	s_setprio 1
	s_waitcnt lgkmcnt(3)
	v_mfma_f32_16x16x32_bf16 v[94:97], v[236:239], v[176:179], v[94:97]
	s_waitcnt lgkmcnt(1)
	v_mfma_f32_16x16x32_bf16 v[90:93], v[244:247], v[176:179], v[90:93]
	v_mfma_f32_16x16x32_bf16 v[86:89], v[236:239], v[184:187], v[86:89]
	v_mfma_f32_16x16x32_bf16 v[82:85], v[244:247], v[184:187], v[82:85]
	v_mfma_f32_16x16x32_bf16 v[78:81], v[236:239], v[192:195], v[78:81]
	v_mfma_f32_16x16x32_bf16 v[74:77], v[244:247], v[192:195], v[74:77]
	v_mfma_f32_16x16x32_bf16 v[70:73], v[236:239], v[200:203], v[70:73]
	v_mfma_f32_16x16x32_bf16 v[66:69], v[244:247], v[200:203], v[66:69]
	v_mfma_f32_16x16x32_bf16 v[94:97], v[240:243], v[180:183], v[94:97]
	s_waitcnt lgkmcnt(0)
	v_mfma_f32_16x16x32_bf16 v[90:93], v[248:251], v[180:183], v[90:93]
	v_mfma_f32_16x16x32_bf16 v[86:89], v[240:243], v[188:191], v[86:89]
	v_mfma_f32_16x16x32_bf16 v[82:85], v[248:251], v[188:191], v[82:85]
	v_mfma_f32_16x16x32_bf16 v[78:81], v[240:243], v[196:199], v[78:81]
	v_mfma_f32_16x16x32_bf16 v[74:77], v[248:251], v[196:199], v[74:77]
	v_mfma_f32_16x16x32_bf16 v[70:73], v[240:243], v[204:207], v[70:73]
	v_mfma_f32_16x16x32_bf16 v[66:69], v[248:251], v[204:207], v[66:69]
	s_setprio 0
	v_readfirstlane_b32 s12, v151
	s_addk_i32 s38, 0x180
	s_mov_b32 m0, s12
	v_readfirstlane_b32 s12, v152
	s_barrier
	ds_read_b128 v[176:179], v137 offset:49152
	ds_read_b128 v[180:183], v137 offset:50176
	ds_read_b128 v[184:187], v136 offset:49152
	ds_read_b128 v[188:191], v136 offset:50176
	ds_read_b128 v[192:195], v135 offset:49152
	ds_read_b128 v[196:199], v135 offset:50176
	ds_read_b128 v[200:203], v134 offset:49152
	ds_read_b128 v[204:207], v134 offset:50176
	buffer_load_dwordx4 v138, s[4:7], s38 offen lds
	s_addk_i32 s43, 0x180
	s_mov_b32 m0, s12
	s_nop 0
	buffer_load_dwordx4 v138, s[4:7], s43 offen lds
	s_barrier
; #define WAIT_V(n) asm volatile("s_waitcnt vmcnt(" #n ")" ::: "memory")
; #define WAIT_L(n) asm volatile("s_waitcnt lgkmcnt(" #n ")" ::: "memory")
; #define BAR __builtin_amdgcn_s_barrier()
; #define SCHED __builtin_amdgcn_sched_barrier(0)
; template <int MODE>
; __device__ __forceinline__ void gemm_tile(const int ph, const int which, const int pm, const int pn) {
;     ...
;     LDA(At, 1, 1); STAGE(SA(1, 0), RA, brow, t + 3);
;     BAR; WAIT_L(0); MMA(1, 0, At, B0); BAR; SCHED;
;     STAGE(SB(1, 1), RB, bcolB, t + 3);
;     WAIT_V(6); BAR; MMA(1, 1, At, B1); BAR;
;   }
;   {
;     LDB(B0, 0, 0); LDA(At, 0, 0); STAGE(SA(1, 1), RA, brow + HALF, nt - 1);
;     BAR; WAIT_L(0); MMA(0, 0, At, B0); BAR;
;     LDB(B1, 0, 1); BAR; WAIT_L(0); MMA(0, 1, At, B1); BAR;
	s_waitcnt lgkmcnt(0)
	s_setprio 1
	s_waitcnt lgkmcnt(7)
	v_mfma_f32_16x16x32_bf16 v[62:65], v[160:163], v[176:179], v[62:65]
	v_mfma_f32_16x16x32_bf16 v[58:61], v[168:171], v[176:179], v[58:61]
	s_waitcnt lgkmcnt(5)
	v_mfma_f32_16x16x32_bf16 v[54:57], v[160:163], v[184:187], v[54:57]
	v_mfma_f32_16x16x32_bf16 v[50:53], v[168:171], v[184:187], v[50:53]
	s_waitcnt lgkmcnt(3)
	v_mfma_f32_16x16x32_bf16 v[46:49], v[160:163], v[192:195], v[46:49]
	v_mfma_f32_16x16x32_bf16 v[42:45], v[168:171], v[192:195], v[42:45]
	s_waitcnt lgkmcnt(1)
	v_mfma_f32_16x16x32_bf16 v[38:41], v[160:163], v[200:203], v[38:41]
	v_mfma_f32_16x16x32_bf16 v[34:37], v[168:171], v[200:203], v[34:37]
	v_mfma_f32_16x16x32_bf16 v[62:65], v[164:167], v[180:183], v[62:65]
	v_mfma_f32_16x16x32_bf16 v[58:61], v[172:175], v[180:183], v[58:61]
	v_mfma_f32_16x16x32_bf16 v[54:57], v[164:167], v[188:191], v[54:57]
	v_mfma_f32_16x16x32_bf16 v[50:53], v[172:175], v[188:191], v[50:53]
	v_mfma_f32_16x16x32_bf16 v[46:49], v[164:167], v[196:199], v[46:49]
	v_mfma_f32_16x16x32_bf16 v[42:45], v[172:175], v[196:199], v[42:45]
	s_waitcnt lgkmcnt(0)
	v_mfma_f32_16x16x32_bf16 v[38:41], v[164:167], v[204:207], v[38:41]
	v_mfma_f32_16x16x32_bf16 v[34:37], v[172:175], v[204:207], v[34:37]
	s_setprio 0
	s_barrier
	v_readfirstlane_b32 s12, v154
	s_addk_i32 s50, 0x180
	s_mov_b32 m0, s12
	v_readfirstlane_b32 s12, v156
	buffer_load_dwordx4 v138, s[68:71], s50 offen lds
	s_addk_i32 s51, 0x180
	s_mov_b32 m0, s12
	s_nop 0
	buffer_load_dwordx4 v138, s[68:71], s51 offen lds
	s_waitcnt vmcnt(6)
	s_barrier
	s_setprio 1
	v_mfma_f32_16x16x32_bf16 v[30:33], v[236:239], v[176:179], v[30:33]
	v_mfma_f32_16x16x32_bf16 v[26:29], v[244:247], v[176:179], v[26:29]
	v_mfma_f32_16x16x32_bf16 v[22:25], v[236:239], v[184:187], v[22:25]
	v_mfma_f32_16x16x32_bf16 v[18:21], v[244:247], v[184:187], v[18:21]
	v_mfma_f32_16x16x32_bf16 v[14:17], v[236:239], v[192:195], v[14:17]
	v_mfma_f32_16x16x32_bf16 v[10:13], v[244:247], v[192:195], v[10:13]
	v_mfma_f32_16x16x32_bf16 v[6:9], v[236:239], v[200:203], v[6:9]
	v_mfma_f32_16x16x32_bf16 v[2:5], v[244:247], v[200:203], v[2:5]
	v_mfma_f32_16x16x32_bf16 v[30:33], v[240:243], v[180:183], v[30:33]
	v_mfma_f32_16x16x32_bf16 v[26:29], v[248:251], v[180:183], v[26:29]
	v_mfma_f32_16x16x32_bf16 v[22:25], v[240:243], v[188:191], v[22:25]
	v_mfma_f32_16x16x32_bf16 v[18:21], v[248:251], v[188:191], v[18:21]
	v_mfma_f32_16x16x32_bf16 v[14:17], v[240:243], v[196:199], v[14:17]
	v_mfma_f32_16x16x32_bf16 v[10:13], v[248:251], v[196:199], v[10:13]
	v_mfma_f32_16x16x32_bf16 v[6:9], v[240:243], v[204:207], v[6:9]
	v_mfma_f32_16x16x32_bf16 v[2:5], v[248:251], v[204:207], v[2:5]
	s_setprio 0
	s_addk_i32 s25, 0x100
	s_cmp_lt_u32 s27, s2
	s_cbranch_scc1 .Lgemm_head_131
	s_barrier
	s_add_i32 s2, s26, s11
	s_lshl_b32 s2, s2, 1
	v_readfirstlane_b32 s3, v155
	s_addk_i32 s2, 0xff80
	s_mov_b32 s6, s70
	s_mov_b32 s7, s71
	s_mov_b32 m0, s3
	v_readfirstlane_b32 s3, v153
	ds_read_b128 v[142:145], v158
	ds_read_b128 v[148:151], v158 offset:1024
	ds_read_b128 v[160:163], v158 offset:2048
	ds_read_b128 v[164:167], v158 offset:3072
	ds_read_b128 v[168:171], v137
	ds_read_b128 v[172:175], v137 offset:1024
	ds_read_b128 v[176:179], v136
	ds_read_b128 v[180:183], v136 offset:1024
	ds_read_b128 v[184:187], v135
	ds_read_b128 v[188:191], v135 offset:1024
	ds_read_b128 v[192:195], v134
	ds_read_b128 v[196:199], v134 offset:1024
	buffer_load_dwordx4 v138, s[4:7], s2 offen lds
	s_add_i32 s2, s2, s10
	s_mov_b32 m0, s3
	s_nop 0
	buffer_load_dwordx4 v138, s[4:7], s2 offen lds
	s_barrier
	s_waitcnt lgkmcnt(0)
	s_setprio 1
	s_waitcnt lgkmcnt(7)
	v_mfma_f32_16x16x32_bf16 v[126:129], v[142:145], v[168:171], v[126:129]
	v_mfma_f32_16x16x32_bf16 v[122:125], v[160:163], v[168:171], v[122:125]
	s_waitcnt lgkmcnt(5)
	v_mfma_f32_16x16x32_bf16 v[118:121], v[142:145], v[176:179], v[118:121]
	v_mfma_f32_16x16x32_bf16 v[114:117], v[160:163], v[176:179], v[114:117]
	s_waitcnt lgkmcnt(1)
	v_mfma_f32_16x16x32_bf16 v[102:105], v[142:145], v[192:195], v[102:105]
	v_mfma_f32_16x16x32_bf16 v[98:101], v[160:163], v[192:195], v[98:101]
	v_mfma_f32_16x16x32_bf16 v[126:129], v[148:151], v[172:175], v[126:129]
	v_mfma_f32_16x16x32_bf16 v[122:125], v[164:167], v[172:175], v[122:125]
	v_mfma_f32_16x16x32_bf16 v[118:121], v[148:151], v[180:183], v[118:121]
	v_mfma_f32_16x16x32_bf16 v[114:117], v[164:167], v[180:183], v[114:117]
	v_mfma_f32_16x16x32_bf16 v[110:113], v[142:145], v[184:187], v[110:113]
	v_mfma_f32_16x16x32_bf16 v[106:109], v[160:163], v[184:187], v[106:109]
	s_waitcnt lgkmcnt(0)
	v_mfma_f32_16x16x32_bf16 v[102:105], v[148:151], v[196:199], v[102:105]
	v_mfma_f32_16x16x32_bf16 v[98:101], v[164:167], v[196:199], v[98:101]
	v_mfma_f32_16x16x32_bf16 v[152:155], v[148:151], v[188:191], v[110:113]
	v_mfma_f32_16x16x32_bf16 v[200:203], v[164:167], v[188:191], v[106:109]
	s_setprio 0
	s_barrier
	s_nop 0
	ds_read_b128 v[106:109], v157
	ds_read_b128 v[110:113], v157 offset:1024
	ds_read_b128 v[204:207], v157 offset:2048
	ds_read_b128 v[156:159], v157 offset:3072
	s_barrier
; #define WAIT_V(n) asm volatile("s_waitcnt vmcnt(" #n ")" ::: "memory")
; #define WAIT_L(n) asm volatile("s_waitcnt lgkmcnt(" #n ")" ::: "memory")
; #define BAR __builtin_amdgcn_s_barrier()
; template <int MODE>
; __device__ __forceinline__ void gemm_tile(const int ph, const int which, const int pm, const int pn) {
;     ...
;     BAR; WAIT_L(0); MMA(0, 0, At, B0); BAR;
;     LDB(B1, 0, 1); BAR; WAIT_L(0); MMA(0, 1, At, B1); BAR;
;     LDA(At, 0, 1); WAIT_V(4); BAR; WAIT_L(0); MMA(1, 0, At, B0); MMA(1, 1, At, B1); BAR;
;   }
;   {
;     LDB(B0, 1, 0); LDA(At, 1, 0); WAIT_V(2); BAR; WAIT_L(0); MMA(0, 0, At, B0); BAR;
	s_waitcnt lgkmcnt(0)
	s_setprio 1
	s_waitcnt lgkmcnt(3)
	v_mfma_f32_16x16x32_bf16 v[86:89], v[106:109], v[176:179], v[86:89]
	s_waitcnt lgkmcnt(1)
	v_mfma_f32_16x16x32_bf16 v[82:85], v[204:207], v[176:179], v[82:85]
	v_mfma_f32_16x16x32_bf16 v[70:73], v[106:109], v[192:195], v[70:73]
	v_mfma_f32_16x16x32_bf16 v[66:69], v[204:207], v[192:195], v[66:69]
	v_mfma_f32_16x16x32_bf16 v[94:97], v[106:109], v[168:171], v[94:97]
	v_mfma_f32_16x16x32_bf16 v[90:93], v[204:207], v[168:171], v[90:93]
	v_mfma_f32_16x16x32_bf16 v[86:89], v[110:113], v[180:183], v[86:89]
	s_waitcnt lgkmcnt(0)
	v_mfma_f32_16x16x32_bf16 v[82:85], v[156:159], v[180:183], v[82:85]
	v_mfma_f32_16x16x32_bf16 v[78:81], v[106:109], v[184:187], v[78:81]
	v_mfma_f32_16x16x32_bf16 v[74:77], v[204:207], v[184:187], v[74:77]
	v_mfma_f32_16x16x32_bf16 v[70:73], v[110:113], v[196:199], v[70:73]
	v_mfma_f32_16x16x32_bf16 v[66:69], v[156:159], v[196:199], v[66:69]
	v_mfma_f32_16x16x32_bf16 v[236:239], v[110:113], v[172:175], v[94:97]
	v_mfma_f32_16x16x32_bf16 v[168:171], v[156:159], v[172:175], v[90:93]
	v_mfma_f32_16x16x32_bf16 v[172:175], v[110:113], v[188:191], v[78:81]
	v_mfma_f32_16x16x32_bf16 v[176:179], v[156:159], v[188:191], v[74:77]
	s_setprio 0
	s_barrier
	s_nop 0
	ds_read_b128 v[74:77], v137 offset:16384
	ds_read_b128 v[78:81], v137 offset:17408
	ds_read_b128 v[90:93], v136 offset:16384
	ds_read_b128 v[94:97], v136 offset:17408
	ds_read_b128 v[180:183], v135 offset:16384
	ds_read_b128 v[184:187], v135 offset:17408
	ds_read_b128 v[188:191], v134 offset:16384
	ds_read_b128 v[192:195], v134 offset:17408
	s_waitcnt vmcnt(4)
	s_barrier
	s_waitcnt lgkmcnt(0)
	s_setprio 1
	s_waitcnt lgkmcnt(7)
	v_mfma_f32_16x16x32_bf16 v[62:65], v[142:145], v[74:77], v[62:65]
	v_mfma_f32_16x16x32_bf16 v[58:61], v[160:163], v[74:77], v[58:61]
	s_waitcnt lgkmcnt(5)
	v_mfma_f32_16x16x32_bf16 v[54:57], v[142:145], v[90:93], v[54:57]
	v_mfma_f32_16x16x32_bf16 v[50:53], v[160:163], v[90:93], v[50:53]
	s_waitcnt lgkmcnt(1)
	v_mfma_f32_16x16x32_bf16 v[38:41], v[142:145], v[188:191], v[38:41]
	v_mfma_f32_16x16x32_bf16 v[34:37], v[160:163], v[188:191], v[34:37]
	v_mfma_f32_16x16x32_bf16 v[62:65], v[148:151], v[78:81], v[62:65]
	v_mfma_f32_16x16x32_bf16 v[58:61], v[164:167], v[78:81], v[58:61]
	v_mfma_f32_16x16x32_bf16 v[54:57], v[148:151], v[94:97], v[54:57]
	v_mfma_f32_16x16x32_bf16 v[50:53], v[164:167], v[94:97], v[50:53]
	v_mfma_f32_16x16x32_bf16 v[46:49], v[142:145], v[180:183], v[46:49]
	v_mfma_f32_16x16x32_bf16 v[42:45], v[160:163], v[180:183], v[42:45]
	s_waitcnt lgkmcnt(0)
	v_mfma_f32_16x16x32_bf16 v[38:41], v[148:151], v[192:195], v[38:41]
	v_mfma_f32_16x16x32_bf16 v[34:37], v[164:167], v[192:195], v[34:37]
	v_mfma_f32_16x16x32_bf16 v[196:199], v[148:151], v[184:187], v[46:49]
	v_mfma_f32_16x16x32_bf16 v[240:243], v[164:167], v[184:187], v[42:45]
	s_setprio 0
	s_setprio 1
	v_mfma_f32_16x16x32_bf16 v[22:25], v[106:109], v[90:93], v[22:25]
	v_mfma_f32_16x16x32_bf16 v[18:21], v[204:207], v[90:93], v[18:21]
	v_mfma_f32_16x16x32_bf16 v[6:9], v[106:109], v[188:191], v[6:9]
	v_mfma_f32_16x16x32_bf16 v[2:5], v[204:207], v[188:191], v[2:5]
	v_mfma_f32_16x16x32_bf16 v[30:33], v[106:109], v[74:77], v[30:33]
	v_mfma_f32_16x16x32_bf16 v[26:29], v[204:207], v[74:77], v[26:29]
	v_mfma_f32_16x16x32_bf16 v[22:25], v[110:113], v[94:97], v[22:25]
	v_mfma_f32_16x16x32_bf16 v[18:21], v[156:159], v[94:97], v[18:21]
	v_mfma_f32_16x16x32_bf16 v[14:17], v[106:109], v[180:183], v[14:17]
	v_mfma_f32_16x16x32_bf16 v[10:13], v[204:207], v[180:183], v[10:13]
	v_mfma_f32_16x16x32_bf16 v[6:9], v[110:113], v[192:195], v[6:9]
	v_mfma_f32_16x16x32_bf16 v[2:5], v[156:159], v[192:195], v[2:5]
	v_mfma_f32_16x16x32_bf16 v[142:145], v[110:113], v[78:81], v[30:33]
	v_mfma_f32_16x16x32_bf16 v[148:151], v[156:159], v[78:81], v[26:29]
	v_mfma_f32_16x16x32_bf16 v[160:163], v[110:113], v[184:187], v[14:17]
	v_mfma_f32_16x16x32_bf16 v[164:167], v[156:159], v[184:187], v[10:13]
	s_setprio 0
	s_barrier
	s_nop 0
	ds_read_b128 v[10:13], v146
	ds_read_b128 v[14:17], v146 offset:1024
	ds_read_b128 v[156:159], v146 offset:2048
	ds_read_b128 v[180:183], v146 offset:3072
	ds_read_b128 v[26:29], v137 offset:32768
	ds_read_b128 v[30:33], v137 offset:33792
	ds_read_b128 v[42:45], v136 offset:32768
	ds_read_b128 v[46:49], v136 offset:33792
	ds_read_b128 v[184:187], v135 offset:32768
	ds_read_b128 v[188:191], v135 offset:33792
	ds_read_b128 v[192:195], v134 offset:32768
	ds_read_b128 v[204:207], v134 offset:33792
	s_waitcnt vmcnt(2)
	s_barrier
; #define WAIT_V(n) asm volatile("s_waitcnt vmcnt(" #n ")" ::: "memory")
; #define WAIT_L(n) asm volatile("s_waitcnt lgkmcnt(" #n ")" ::: "memory")
; #define BAR __builtin_amdgcn_s_barrier()
; template <int MODE>
; __device__ __forceinline__ void gemm_tile(const int ph, const int which, const int pm, const int pn) {
;     ...
;     LDB(B0, 1, 0); LDA(At, 1, 0); WAIT_V(2); BAR; WAIT_L(0); MMA(0, 0, At, B0); BAR;
;     LDB(B1, 1, 1); WAIT_V(0); BAR; WAIT_L(0); MMA(0, 1, At, B1); BAR;
;     LDA(At, 1, 1); BAR; WAIT_L(0); MMA(1, 0, At, B0); MMA(1, 1, At, B1); BAR;
;   }
;   if (wr == 0) BAR;
	s_waitcnt lgkmcnt(0)
	s_setprio 1
	s_waitcnt lgkmcnt(7)
	v_mfma_f32_16x16x32_bf16 v[74:77], v[10:13], v[26:29], v[126:129]
	s_waitcnt lgkmcnt(6)
	v_mfma_f32_16x16x32_bf16 v[126:129], v[14:17], v[30:33], v[74:77]
	v_mfma_f32_16x16x32_bf16 v[74:77], v[156:159], v[26:29], v[122:125]
	v_mfma_f32_16x16x32_bf16 v[122:125], v[180:183], v[30:33], v[74:77]
	s_waitcnt lgkmcnt(5)
	v_mfma_f32_16x16x32_bf16 v[74:77], v[10:13], v[42:45], v[118:121]
	s_waitcnt lgkmcnt(4)
	v_mfma_f32_16x16x32_bf16 v[110:113], v[14:17], v[46:49], v[74:77]
	v_mfma_f32_16x16x32_bf16 v[74:77], v[156:159], v[42:45], v[114:117]
	v_mfma_f32_16x16x32_bf16 v[106:109], v[180:183], v[46:49], v[74:77]
	s_waitcnt lgkmcnt(3)
	v_mfma_f32_16x16x32_bf16 v[74:77], v[10:13], v[184:187], v[152:155]
	s_waitcnt lgkmcnt(2)
	v_mfma_f32_16x16x32_bf16 v[94:97], v[14:17], v[188:191], v[74:77]
	v_mfma_f32_16x16x32_bf16 v[74:77], v[156:159], v[184:187], v[200:203]
	v_mfma_f32_16x16x32_bf16 v[90:93], v[180:183], v[188:191], v[74:77]
	s_waitcnt lgkmcnt(1)
	v_mfma_f32_16x16x32_bf16 v[74:77], v[10:13], v[192:195], v[102:105]
	s_waitcnt lgkmcnt(0)
	v_mfma_f32_16x16x32_bf16 v[78:81], v[14:17], v[204:207], v[74:77]
	v_mfma_f32_16x16x32_bf16 v[74:77], v[156:159], v[192:195], v[98:101]
	v_mfma_f32_16x16x32_bf16 v[74:77], v[180:183], v[204:207], v[74:77]
	s_setprio 0
	s_barrier
	ds_read_b128 v[152:155], v140
	ds_read_b128 v[200:203], v140 offset:1024
	ds_read_b128 v[244:247], v140 offset:2048
	ds_read_b128 v[138:141], v140 offset:3072
	s_waitcnt vmcnt(0)
	s_barrier
	s_waitcnt lgkmcnt(0)
	s_setprio 1
	s_waitcnt lgkmcnt(3)
	v_mfma_f32_16x16x32_bf16 v[98:101], v[152:155], v[26:29], v[236:239]
	s_waitcnt lgkmcnt(1)
	v_mfma_f32_16x16x32_bf16 v[26:29], v[244:247], v[26:29], v[168:171]
	s_waitcnt lgkmcnt(0)
	v_mfma_f32_16x16x32_bf16 v[114:117], v[138:141], v[30:33], v[26:29]
	v_mfma_f32_16x16x32_bf16 v[26:29], v[152:155], v[42:45], v[86:89]
	v_mfma_f32_16x16x32_bf16 v[102:105], v[200:203], v[46:49], v[26:29]
	v_mfma_f32_16x16x32_bf16 v[26:29], v[244:247], v[42:45], v[82:85]
	v_mfma_f32_16x16x32_bf16 v[118:121], v[200:203], v[30:33], v[98:101]
	v_mfma_f32_16x16x32_bf16 v[98:101], v[138:141], v[46:49], v[26:29]
	v_mfma_f32_16x16x32_bf16 v[26:29], v[152:155], v[184:187], v[172:175]
	v_mfma_f32_16x16x32_bf16 v[86:89], v[200:203], v[188:191], v[26:29]
	v_mfma_f32_16x16x32_bf16 v[26:29], v[244:247], v[184:187], v[176:179]
	v_mfma_f32_16x16x32_bf16 v[82:85], v[138:141], v[188:191], v[26:29]
	v_mfma_f32_16x16x32_bf16 v[26:29], v[152:155], v[192:195], v[70:73]
	v_mfma_f32_16x16x32_bf16 v[70:73], v[200:203], v[204:207], v[26:29]
	v_mfma_f32_16x16x32_bf16 v[26:29], v[244:247], v[192:195], v[66:69]
	v_mfma_f32_16x16x32_bf16 v[66:69], v[138:141], v[204:207], v[26:29]
	s_setprio 0
	s_barrier
	ds_read_b128 v[168:171], v137 offset:49152
	ds_read_b128 v[172:175], v137 offset:50176
	ds_read_b128 v[176:179], v136 offset:49152
	ds_read_b128 v[184:187], v136 offset:50176
	ds_read_b128 v[188:191], v135 offset:49152
	ds_read_b128 v[192:195], v135 offset:50176
	ds_read_b128 v[204:207], v134 offset:49152
	ds_read_b128 v[134:137], v134 offset:50176
	s_barrier
	s_waitcnt lgkmcnt(0)
	s_setprio 1
	s_waitcnt lgkmcnt(7)
	v_mfma_f32_16x16x32_bf16 v[26:29], v[10:13], v[168:171], v[62:65]
	s_waitcnt lgkmcnt(6)
	v_mfma_f32_16x16x32_bf16 v[62:65], v[14:17], v[172:175], v[26:29]
	v_mfma_f32_16x16x32_bf16 v[26:29], v[156:159], v[168:171], v[58:61]
	v_mfma_f32_16x16x32_bf16 v[58:61], v[180:183], v[172:175], v[26:29]
	s_waitcnt lgkmcnt(5)
	v_mfma_f32_16x16x32_bf16 v[26:29], v[10:13], v[176:179], v[54:57]
	s_waitcnt lgkmcnt(4)
	v_mfma_f32_16x16x32_bf16 v[46:49], v[14:17], v[184:187], v[26:29]
	v_mfma_f32_16x16x32_bf16 v[26:29], v[156:159], v[176:179], v[50:53]
	v_mfma_f32_16x16x32_bf16 v[42:45], v[180:183], v[184:187], v[26:29]
	s_waitcnt lgkmcnt(3)
	v_mfma_f32_16x16x32_bf16 v[26:29], v[10:13], v[188:191], v[196:199]
	s_waitcnt lgkmcnt(1)
	v_mfma_f32_16x16x32_bf16 v[10:13], v[10:13], v[204:207], v[38:41]
	v_mfma_f32_16x16x32_bf16 v[30:33], v[14:17], v[192:195], v[26:29]
	v_mfma_f32_16x16x32_bf16 v[26:29], v[156:159], v[188:191], v[240:243]
	s_waitcnt lgkmcnt(0)
	v_mfma_f32_16x16x32_bf16 v[14:17], v[14:17], v[134:137], v[10:13]
	v_mfma_f32_16x16x32_bf16 v[10:13], v[156:159], v[204:207], v[34:37]
	v_mfma_f32_16x16x32_bf16 v[26:29], v[180:183], v[192:195], v[26:29]
	v_mfma_f32_16x16x32_bf16 v[10:13], v[180:183], v[134:137], v[10:13]
	s_setprio 0
	s_setprio 1
	v_mfma_f32_16x16x32_bf16 v[34:37], v[152:155], v[168:171], v[142:145]
	v_mfma_f32_16x16x32_bf16 v[54:57], v[200:203], v[172:175], v[34:37]
	v_mfma_f32_16x16x32_bf16 v[34:37], v[244:247], v[168:171], v[148:151]
	v_mfma_f32_16x16x32_bf16 v[18:21], v[244:247], v[176:179], v[18:21]
	v_mfma_f32_16x16x32_bf16 v[50:53], v[138:141], v[172:175], v[34:37]
	v_mfma_f32_16x16x32_bf16 v[22:25], v[152:155], v[176:179], v[22:25]
	v_mfma_f32_16x16x32_bf16 v[34:37], v[138:141], v[184:187], v[18:21]
	v_mfma_f32_16x16x32_bf16 v[18:21], v[152:155], v[188:191], v[160:163]
	v_mfma_f32_16x16x32_bf16 v[38:41], v[200:203], v[184:187], v[22:25]
	v_mfma_f32_16x16x32_bf16 v[22:25], v[200:203], v[192:195], v[18:21]
	v_mfma_f32_16x16x32_bf16 v[18:21], v[244:247], v[188:191], v[164:167]
	v_mfma_f32_16x16x32_bf16 v[6:9], v[152:155], v[204:207], v[6:9]
	v_mfma_f32_16x16x32_bf16 v[2:5], v[244:247], v[204:207], v[2:5]
	v_mfma_f32_16x16x32_bf16 v[18:21], v[138:141], v[192:195], v[18:21]
	v_mfma_f32_16x16x32_bf16 v[6:9], v[200:203], v[134:137], v[6:9]
	v_mfma_f32_16x16x32_bf16 v[2:5], v[138:141], v[134:137], v[2:5]
	s_setprio 0
	s_movk_i32 s2, 0x100
	v_cmp_gt_u32_e32 vcc, s2, v0
	s_barrier
	s_and_saveexec_b64 s[2:3], vcc
	s_cbranch_execz .LBB0_134
	s_barrier

; #define WAIT_V(n) asm volatile("s_waitcnt vmcnt(" #n ")" ::: "memory")
; #define BAR __builtin_amdgcn_s_barrier()
; template <int MODE>
; __device__ __forceinline__ void gemm_tile(const int ph, const int which, const int pm, const int pn) {
;     ...
;   const int wid = gtid >> 6, lane = gtid & 63, wr = wid >> 2, wc = wid & 3, fr = lane & 15,
;             fq = lane >> 4;
;   __amdgpu_buffer_rsrc_t RA = __builtin_amdgcn_make_buffer_rsrc((void*)A, 0, 0x7ffffff0, 0x00020000);
;   __amdgpu_buffer_rsrc_t RB = __builtin_amdgcn_make_buffer_rsrc((void*)Bt, 0, 0x7ffffff0, 0x00020000);
;   int voff;
;   {
;     int _r, _c;
;     stage_rc(gtid * 16, _r, _c);
;     voff = (_r * K + _c) * 2;
;   }
;   f32x4 acc[2][2][4][2] = {};
;   bf16x8 At[4][2], B0[2][2], B1[2][2];
;   const int nt = K / BK;
;   const int brow = browA;
;   STAGE(SB(0, 0), RB, bcol, 0);
;   STAGE(SA(0, 0), RA, brow, 0);
;   STAGE(SB(0, 1), RB, bcolB, 0);
;   STAGE(SA(0, 1), RA, brow + HALF, 0);
;   if (wr == 1) BAR;
;   WAIT_V(4);
;   BAR;
;   STAGE(SB(1, 0), RB, bcol, 1);
;   STAGE(SA(1, 0), RA, brow, 1);
;   STAGE(SB(1, 1), RB, bcolB, 1);
;   WAIT_V(6);
;   BAR;
.LBB0_217:
	s_or_b64 exec, exec, s[6:7]
	v_add_u32_e32 v147, 0x18000, v136
	v_add_u32_e32 v148, 0x1a000, v136
	v_readfirstlane_b32 s7, v147
	s_or_b32 s6, s18, 0x80
	s_mov_b32 m0, s7
	v_readfirstlane_b32 s7, v148
	v_add_u32_e32 v149, 0x8000, v136
	s_waitcnt vmcnt(4)
	s_barrier
	buffer_load_dwordx4 v135, s[68:71], s6 offen lds
	s_add_i32 s6, s6, s10
	s_mov_b32 m0, s7
	s_or_b32 s13, s17, 0x80
	v_readfirstlane_b32 s17, v149
	v_add_u32_e32 v150, 0xa000, v136
	buffer_load_dwordx4 v135, s[68:71], s6 offen lds
	s_mov_b32 s6, s70
	s_mov_b32 s7, s71
	s_mov_b32 m0, s17
	v_readfirstlane_b32 s17, v150
	buffer_load_dwordx4 v135, s[4:7], s13 offen lds
	s_add_i32 s13, s13, s10
	s_mov_b32 m0, s17
	v_add_u32_e32 v152, 0x1c000, v136
	buffer_load_dwordx4 v135, s[4:7], s13 offen lds
	s_or_b32 s13, s16, 0x80
	v_readfirstlane_b32 s16, v152
	v_add_u32_e32 v154, 0x1e000, v136
	s_mov_b32 m0, s16
	v_readfirstlane_b32 s16, v154
	buffer_load_dwordx4 v135, s[68:71], s13 offen lds
	s_add_i32 s13, s13, s10
	s_mov_b32 m0, s16
	v_and_b32_e32 v3, 15, v0
	buffer_load_dwordx4 v135, s[68:71], s13 offen lds
	s_lshr_b32 s12, s28, 6
	v_and_b32_e32 v5, 48, v0
	v_lshlrev_b32_e32 v6, 6, v3
	v_lshlrev_b32_e32 v8, 2, v0
	s_add_i32 s16, s12, -2
	v_or_b32_e32 v7, v6, v5
	v_and_b32_e32 v8, 32, v8
	s_mov_b32 s12, 0x10000
	v_bitop3_b32 v9, v7, s12, v8 bitop3:0xde
	s_mov_b32 s12, 0x14000
	v_bitop3_b32 v10, v7, s12, v8 bitop3:0xde
	s_mov_b32 s12, 0x18000
	v_bitop3_b32 v11, v7, s12, v8 bitop3:0xde
	s_mov_b32 s12, 0x1c000
	v_bitop3_b32 v7, v7, s12, v8 bitop3:0xde
	s_lshl_b32 s12, s22, 1
	v_lshl_or_b32 v130, v2, 6, v3
	v_lshlrev_b32_e32 v3, 13, v2
	v_lshlrev_b32_e32 v2, 6, v0
	s_add_i32 s13, s12, 0x180
	s_addk_i32 s12, 0x80
	v_bfe_u32 v138, v0, 6, 2
	v_and_b32_e32 v2, 0x3c0, v2
	s_lshl_b32 s19, s20, 1
	s_mul_i32 s21, s28, s12
	s_lshl_b32 s12, s26, 1
	v_lshlrev_b32_e32 v4, 12, v138
	v_bitop3_b32 v6, v6, v8, v5 bitop3:0x36
	v_bitop3_b32 v5, v2, v8, v5 bitop3:0x36
	v_or_b32_e32 v8, 0x800, v3
	v_or_b32_e32 v12, 0x1000, v3
	v_or_b32_e32 v13, 0x1800, v3
	s_mul_i32 s17, s28, s13
	s_lshl_b32 s13, s28, 1
	s_add_i32 s18, s22, 0x80
	s_addk_i32 s19, 0x80
	s_addk_i32 s12, 0x80
	v_mov_b32_e32 v2, 0
	v_add_u32_e32 v153, 0xc000, v136
	v_add_u32_e32 v151, 0xe000, v136
	s_mul_i32 s18, s13, s18
	s_mul_i32 s19, s28, s19
	s_mul_i32 s20, s13, s20
	s_mul_i32 s22, s13, s22
	s_mul_i32 s25, s28, s12
	s_mul_i32 s26, s13, s26
	s_mov_b32 s27, 0
	v_add_u32_e32 v156, v9, v4
	v_add_u32_e32 v134, v6, v3
	v_add_u32_e32 v133, v5, v8
	v_add_u32_e32 v132, v5, v12
	v_add_u32_e32 v131, v5, v13
	v_add_u32_e32 v155, v10, v4
	v_add_u32_e32 v144, v11, v4
	v_add_u32_e32 v137, v7, v4
	s_mov_b32 vcc_lo, 0
	v_mov_b32_e32 v3, v2
	v_mov_b32_e32 v4, v2
	v_mov_b32_e32 v5, v2
	v_mov_b32_e32 v6, v2
	v_mov_b32_e32 v7, v2
	v_mov_b32_e32 v8, v2
	v_mov_b32_e32 v9, v2
	v_mov_b32_e32 v10, v2
	v_mov_b32_e32 v11, v2
	v_mov_b32_e32 v12, v2
	v_mov_b32_e32 v13, v2
	v_mov_b32_e32 v14, v2
	v_mov_b32_e32 v15, v2
	v_mov_b32_e32 v16, v2
	v_mov_b32_e32 v17, v2
	v_mov_b32_e32 v18, v2
	v_mov_b32_e32 v19, v2
	v_mov_b32_e32 v20, v2
	v_mov_b32_e32 v21, v2
	v_mov_b32_e32 v22, v2
	v_mov_b32_e32 v23, v2
	v_mov_b32_e32 v24, v2
	v_mov_b32_e32 v25, v2
	v_mov_b32_e32 v26, v2
	v_mov_b32_e32 v27, v2
	v_mov_b32_e32 v28, v2
	v_mov_b32_e32 v29, v2
	v_mov_b32_e32 v30, v2
	v_mov_b32_e32 v31, v2
	v_mov_b32_e32 v32, v2
	v_mov_b32_e32 v33, v2
	v_mov_b32_e32 v34, v2
	v_mov_b32_e32 v35, v2
	v_mov_b32_e32 v36, v2
	v_mov_b32_e32 v37, v2
	v_mov_b32_e32 v38, v2
	v_mov_b32_e32 v39, v2
	v_mov_b32_e32 v40, v2
	v_mov_b32_e32 v41, v2
	v_mov_b32_e32 v42, v2
	v_mov_b32_e32 v43, v2
	v_mov_b32_e32 v44, v2
	v_mov_b32_e32 v45, v2
	v_mov_b32_e32 v46, v2
	v_mov_b32_e32 v47, v2
	v_mov_b32_e32 v48, v2
	v_mov_b32_e32 v49, v2
	v_mov_b32_e32 v50, v2
	v_mov_b32_e32 v51, v2
	v_mov_b32_e32 v52, v2
	v_mov_b32_e32 v53, v2
	v_mov_b32_e32 v54, v2
	v_mov_b32_e32 v55, v2
	v_mov_b32_e32 v56, v2
	v_mov_b32_e32 v57, v2
	v_mov_b32_e32 v58, v2
	v_mov_b32_e32 v59, v2
	v_mov_b32_e32 v60, v2
	v_mov_b32_e32 v61, v2
	v_mov_b32_e32 v62, v2
	v_mov_b32_e32 v63, v2
	v_mov_b32_e32 v64, v2
	v_mov_b32_e32 v65, v2
	v_mov_b32_e32 v66, v2
	v_mov_b32_e32 v67, v2
	v_mov_b32_e32 v68, v2
	v_mov_b32_e32 v69, v2
	v_mov_b32_e32 v70, v2
	v_mov_b32_e32 v71, v2
	v_mov_b32_e32 v72, v2
	v_mov_b32_e32 v73, v2
	v_mov_b32_e32 v74, v2
	v_mov_b32_e32 v75, v2
	v_mov_b32_e32 v76, v2
	v_mov_b32_e32 v77, v2
	v_mov_b32_e32 v78, v2
	v_mov_b32_e32 v79, v2
	v_mov_b32_e32 v80, v2
	v_mov_b32_e32 v81, v2
	v_mov_b32_e32 v82, v2
	v_mov_b32_e32 v83, v2
	v_mov_b32_e32 v84, v2
	v_mov_b32_e32 v85, v2
	v_mov_b32_e32 v86, v2
	v_mov_b32_e32 v87, v2
	v_mov_b32_e32 v88, v2
	v_mov_b32_e32 v89, v2
	v_mov_b32_e32 v90, v2
	v_mov_b32_e32 v91, v2
	v_mov_b32_e32 v92, v2
	v_mov_b32_e32 v93, v2
	v_mov_b32_e32 v94, v2
	v_mov_b32_e32 v95, v2
	v_mov_b32_e32 v96, v2
	v_mov_b32_e32 v97, v2
	v_mov_b32_e32 v98, v2
	v_mov_b32_e32 v99, v2
	v_mov_b32_e32 v100, v2
	v_mov_b32_e32 v101, v2
	v_mov_b32_e32 v102, v2
	v_mov_b32_e32 v103, v2
	v_mov_b32_e32 v104, v2
	v_mov_b32_e32 v105, v2
	v_mov_b32_e32 v106, v2
	v_mov_b32_e32 v107, v2
	v_mov_b32_e32 v108, v2
	v_mov_b32_e32 v109, v2
	v_mov_b32_e32 v110, v2
	v_mov_b32_e32 v111, v2
	v_mov_b32_e32 v112, v2
	v_mov_b32_e32 v113, v2
	v_mov_b32_e32 v114, v2
	v_mov_b32_e32 v115, v2
	v_mov_b32_e32 v116, v2
	v_mov_b32_e32 v117, v2
	v_mov_b32_e32 v118, v2
	v_mov_b32_e32 v119, v2
	v_mov_b32_e32 v120, v2
	v_mov_b32_e32 v121, v2
	v_mov_b32_e32 v122, v2
	v_mov_b32_e32 v123, v2
	v_mov_b32_e32 v124, v2
	v_mov_b32_e32 v125, v2
	v_mov_b32_e32 v126, v2
	v_mov_b32_e32 v127, v2
	v_mov_b32_e32 v128, v2
	v_mov_b32_e32 v129, v2
	s_waitcnt vmcnt(6)

; #define WAIT_V(n) asm volatile("s_waitcnt vmcnt(" #n ")" ::: "memory")
; #define WAIT_L(n) asm volatile("s_waitcnt lgkmcnt(" #n ")" ::: "memory")
; #define BAR __builtin_amdgcn_s_barrier()
; #define SCHED __builtin_amdgcn_sched_barrier(0)
; template <int MODE>
; __device__ __forceinline__ void gemm_tile(const int ph, const int which, const int pm, const int pn) {
;     ...
;   for (int t = 0; t < nt - 2; t += 2) {
;     LDB(B0, 0, 0); SCHED; LDA(At, 0, 0); STAGE(SA(1, 1), RA, brow + HALF, t + 1);
;     WAIT_L(8); BAR; WAIT_L(0); MMA(0, 0, At, B0); BAR; SCHED;
;     LDB(B1, 0, 1); STAGE(SB(0, 0), RB, bcol, t + 2);
;     BAR; WAIT_L(0); MMA(0, 1, At, B1); BAR;
;     LDA(At, 0, 1); STAGE(SA(0, 0), RA, brow, t + 2);
;     BAR; WAIT_L(0); MMA(1, 0, At, B0); BAR; SCHED;
;     STAGE(SB(0, 1), RB, bcolB, t + 2);
;     WAIT_V(6); BAR; MMA(1, 1, At, B1); BAR;
.LBB0_218:
	ds_read_b128 v[158:161], v156
	ds_read_b128 v[162:165], v156 offset:1024
	ds_read_b128 v[166:169], v156 offset:2048
	ds_read_b128 v[170:173], v156 offset:3072
	s_add_i32 s12, s18, s27
	v_readfirstlane_b32 s29, v153
	s_add_i32 s13, s12, 0x80
	s_mov_b32 m0, s29
	ds_read_b128 v[174:177], v134
	ds_read_b128 v[178:181], v134 offset:1024
	ds_read_b128 v[182:185], v133
	ds_read_b128 v[186:189], v133 offset:1024
	ds_read_b128 v[190:193], v132
	ds_read_b128 v[194:197], v132 offset:1024
	ds_read_b128 v[198:201], v131
	ds_read_b128 v[202:205], v131 offset:1024
	buffer_load_dwordx4 v135, s[4:7], s13 offen lds
	s_add_i32 s13, s17, s27
	v_readfirstlane_b32 s38, v151
	s_add_i32 s29, s13, 0x80
	s_mov_b32 m0, s38
	s_nop 0
	buffer_load_dwordx4 v135, s[4:7], s29 offen lds
	s_waitcnt lgkmcnt(8)
	s_barrier
	s_waitcnt lgkmcnt(0)
	s_setprio 1
	s_waitcnt lgkmcnt(7)
	v_mfma_f32_16x16x32_bf16 v[126:129], v[158:161], v[174:177], v[126:129]
	v_mfma_f32_16x16x32_bf16 v[122:125], v[166:169], v[174:177], v[122:125]
	s_waitcnt lgkmcnt(5)
	v_mfma_f32_16x16x32_bf16 v[118:121], v[158:161], v[182:185], v[118:121]
	v_mfma_f32_16x16x32_bf16 v[114:117], v[166:169], v[182:185], v[114:117]
	s_waitcnt lgkmcnt(3)
	v_mfma_f32_16x16x32_bf16 v[110:113], v[158:161], v[190:193], v[110:113]
	v_mfma_f32_16x16x32_bf16 v[106:109], v[166:169], v[190:193], v[106:109]
	s_waitcnt lgkmcnt(1)
	v_mfma_f32_16x16x32_bf16 v[102:105], v[158:161], v[198:201], v[102:105]
	v_mfma_f32_16x16x32_bf16 v[98:101], v[166:169], v[198:201], v[98:101]
	v_mfma_f32_16x16x32_bf16 v[126:129], v[162:165], v[178:181], v[126:129]
	v_mfma_f32_16x16x32_bf16 v[122:125], v[170:173], v[178:181], v[122:125]
	v_mfma_f32_16x16x32_bf16 v[118:121], v[162:165], v[186:189], v[118:121]
	v_mfma_f32_16x16x32_bf16 v[114:117], v[170:173], v[186:189], v[114:117]
	v_mfma_f32_16x16x32_bf16 v[110:113], v[162:165], v[194:197], v[110:113]
	v_mfma_f32_16x16x32_bf16 v[106:109], v[170:173], v[194:197], v[106:109]
	s_waitcnt lgkmcnt(0)
	v_mfma_f32_16x16x32_bf16 v[102:105], v[162:165], v[202:205], v[102:105]
	v_mfma_f32_16x16x32_bf16 v[98:101], v[170:173], v[202:205], v[98:101]
	s_setprio 0
	s_barrier
	s_add_i32 s29, s26, s27
	v_readfirstlane_b32 s43, v139
	s_add_i32 s38, s29, 0x100
	s_mov_b32 m0, s43
	ds_read_b128 v[236:239], v155
	ds_read_b128 v[240:243], v155 offset:1024
	ds_read_b128 v[244:247], v155 offset:2048
	ds_read_b128 v[248:251], v155 offset:3072
	buffer_load_dwordx4 v135, s[68:71], s38 offen lds
	s_add_i32 s38, s25, s27
	v_readfirstlane_b32 s50, v140
	s_add_i32 s43, s38, 0x100
	s_mov_b32 m0, s50
	s_add_i32 vcc_lo, vcc_lo, 2
	buffer_load_dwordx4 v135, s[68:71], s43 offen lds
	s_barrier
	s_waitcnt lgkmcnt(0)
	s_setprio 1
	s_waitcnt lgkmcnt(3)
	v_mfma_f32_16x16x32_bf16 v[94:97], v[236:239], v[174:177], v[94:97]
	s_waitcnt lgkmcnt(1)
	v_mfma_f32_16x16x32_bf16 v[90:93], v[244:247], v[174:177], v[90:93]
	v_mfma_f32_16x16x32_bf16 v[86:89], v[236:239], v[182:185], v[86:89]
	v_mfma_f32_16x16x32_bf16 v[82:85], v[244:247], v[182:185], v[82:85]
	v_mfma_f32_16x16x32_bf16 v[78:81], v[236:239], v[190:193], v[78:81]
	v_mfma_f32_16x16x32_bf16 v[74:77], v[244:247], v[190:193], v[74:77]
	v_mfma_f32_16x16x32_bf16 v[70:73], v[236:239], v[198:201], v[70:73]
	v_mfma_f32_16x16x32_bf16 v[66:69], v[244:247], v[198:201], v[66:69]
	v_mfma_f32_16x16x32_bf16 v[94:97], v[240:243], v[178:181], v[94:97]
	s_waitcnt lgkmcnt(0)
	v_mfma_f32_16x16x32_bf16 v[90:93], v[248:251], v[178:181], v[90:93]
	v_mfma_f32_16x16x32_bf16 v[86:89], v[240:243], v[186:189], v[86:89]
	v_mfma_f32_16x16x32_bf16 v[82:85], v[248:251], v[186:189], v[82:85]
	v_mfma_f32_16x16x32_bf16 v[78:81], v[240:243], v[194:197], v[78:81]
	v_mfma_f32_16x16x32_bf16 v[74:77], v[248:251], v[194:197], v[74:77]
	v_mfma_f32_16x16x32_bf16 v[70:73], v[240:243], v[202:205], v[70:73]
	v_mfma_f32_16x16x32_bf16 v[66:69], v[248:251], v[202:205], v[66:69]
	s_setprio 0
	s_add_i32 s43, s22, s27
	v_readfirstlane_b32 s51, v136
	s_add_i32 s50, s43, 0x100
	s_mov_b32 m0, s51
	s_barrier
	ds_read_b128 v[174:177], v134 offset:16384
	ds_read_b128 v[178:181], v134 offset:17408
	ds_read_b128 v[182:185], v133 offset:16384
	ds_read_b128 v[186:189], v133 offset:17408
	ds_read_b128 v[190:193], v132 offset:16384
	ds_read_b128 v[194:197], v132 offset:17408
	ds_read_b128 v[198:201], v131 offset:16384
	ds_read_b128 v[202:205], v131 offset:17408
	buffer_load_dwordx4 v135, s[4:7], s50 offen lds
	s_add_i32 s50, s21, s27
	v_readfirstlane_b32 s72, v141
	s_add_i32 s51, s50, 0x100
	s_mov_b32 m0, s72
	s_nop 0
	buffer_load_dwordx4 v135, s[4:7], s51 offen lds
	s_barrier
	s_waitcnt lgkmcnt(0)
	s_setprio 1
	s_waitcnt lgkmcnt(7)
	v_mfma_f32_16x16x32_bf16 v[62:65], v[158:161], v[174:177], v[62:65]
	v_mfma_f32_16x16x32_bf16 v[58:61], v[166:169], v[174:177], v[58:61]
	s_waitcnt lgkmcnt(5)
	v_mfma_f32_16x16x32_bf16 v[54:57], v[158:161], v[182:185], v[54:57]
	v_mfma_f32_16x16x32_bf16 v[50:53], v[166:169], v[182:185], v[50:53]
	s_waitcnt lgkmcnt(3)
	v_mfma_f32_16x16x32_bf16 v[46:49], v[158:161], v[190:193], v[46:49]
	v_mfma_f32_16x16x32_bf16 v[42:45], v[166:169], v[190:193], v[42:45]
	s_waitcnt lgkmcnt(1)
	v_mfma_f32_16x16x32_bf16 v[38:41], v[158:161], v[198:201], v[38:41]
	v_mfma_f32_16x16x32_bf16 v[34:37], v[166:169], v[198:201], v[34:37]
	v_mfma_f32_16x16x32_bf16 v[62:65], v[162:165], v[178:181], v[62:65]
	v_mfma_f32_16x16x32_bf16 v[58:61], v[170:173], v[178:181], v[58:61]
	v_mfma_f32_16x16x32_bf16 v[54:57], v[162:165], v[186:189], v[54:57]
	v_mfma_f32_16x16x32_bf16 v[50:53], v[170:173], v[186:189], v[50:53]
	v_mfma_f32_16x16x32_bf16 v[46:49], v[162:165], v[194:197], v[46:49]
	v_mfma_f32_16x16x32_bf16 v[42:45], v[170:173], v[194:197], v[42:45]
	s_waitcnt lgkmcnt(0)
	v_mfma_f32_16x16x32_bf16 v[38:41], v[162:165], v[202:205], v[38:41]
	v_mfma_f32_16x16x32_bf16 v[34:37], v[170:173], v[202:205], v[34:37]
	s_setprio 0
	s_barrier
; #define WAIT_V(n) asm volatile("s_waitcnt vmcnt(" #n ")" ::: "memory")
; #define WAIT_L(n) asm volatile("s_waitcnt lgkmcnt(" #n ")" ::: "memory")
; #define BAR __builtin_amdgcn_s_barrier()
; #define SCHED __builtin_amdgcn_sched_barrier(0)
; template <int MODE>
; __device__ __forceinline__ void gemm_tile(const int ph, const int which, const int pm, const int pn) {
;     ...
;     STAGE(SB(0, 1), RB, bcolB, t + 2);
;     WAIT_V(6); BAR; MMA(1, 1, At, B1); BAR;
;     LDB(B0, 1, 0); SCHED; LDA(At, 1, 0); STAGE(SA(0, 1), RA, brow + HALF, t + 2);
;     WAIT_L(8); BAR; WAIT_L(0); MMA(0, 0, At, B0); BAR; SCHED;
;     LDB(B1, 1, 1); STAGE(SB(1, 0), RB, bcol, t + 3);
;     BAR; WAIT_L(0); MMA(0, 1, At, B1); BAR;
;     LDA(At, 1, 1); STAGE(SA(1, 0), RA, brow, t + 3);
;     BAR; WAIT_L(0); MMA(1, 0, At, B0); BAR; SCHED;
	s_add_i32 s51, s20, s27
	v_readfirstlane_b32 s73, v142
	s_add_i32 s72, s51, 0x100
	s_mov_b32 m0, s73
	v_readfirstlane_b32 s86, v143
	buffer_load_dwordx4 v135, s[68:71], s72 offen lds
	s_add_i32 s72, s19, s27
	s_add_i32 s73, s72, 0x100
	s_mov_b32 m0, s86
	s_nop 0
	buffer_load_dwordx4 v135, s[68:71], s73 offen lds
	s_waitcnt vmcnt(6)
	s_barrier
	s_setprio 1
	v_mfma_f32_16x16x32_bf16 v[30:33], v[236:239], v[174:177], v[30:33]
	v_mfma_f32_16x16x32_bf16 v[26:29], v[244:247], v[174:177], v[26:29]
	v_mfma_f32_16x16x32_bf16 v[22:25], v[236:239], v[182:185], v[22:25]
	v_mfma_f32_16x16x32_bf16 v[18:21], v[244:247], v[182:185], v[18:21]
	v_mfma_f32_16x16x32_bf16 v[14:17], v[236:239], v[190:193], v[14:17]
	v_mfma_f32_16x16x32_bf16 v[10:13], v[244:247], v[190:193], v[10:13]
	v_mfma_f32_16x16x32_bf16 v[6:9], v[236:239], v[198:201], v[6:9]
	v_mfma_f32_16x16x32_bf16 v[2:5], v[244:247], v[198:201], v[2:5]
	v_mfma_f32_16x16x32_bf16 v[30:33], v[240:243], v[178:181], v[30:33]
	v_mfma_f32_16x16x32_bf16 v[26:29], v[248:251], v[178:181], v[26:29]
	v_mfma_f32_16x16x32_bf16 v[22:25], v[240:243], v[186:189], v[22:25]
	v_mfma_f32_16x16x32_bf16 v[18:21], v[248:251], v[186:189], v[18:21]
	v_mfma_f32_16x16x32_bf16 v[14:17], v[240:243], v[194:197], v[14:17]
	v_mfma_f32_16x16x32_bf16 v[10:13], v[248:251], v[194:197], v[10:13]
	v_mfma_f32_16x16x32_bf16 v[6:9], v[240:243], v[202:205], v[6:9]
	v_mfma_f32_16x16x32_bf16 v[2:5], v[248:251], v[202:205], v[2:5]
	s_setprio 0
	s_barrier
	ds_read_b128 v[158:161], v144
	ds_read_b128 v[162:165], v144 offset:1024
	ds_read_b128 v[166:169], v144 offset:2048
	ds_read_b128 v[170:173], v144 offset:3072
	v_readfirstlane_b32 s73, v145
	s_addk_i32 s12, 0x100
	s_mov_b32 m0, s73
	ds_read_b128 v[174:177], v134 offset:32768
	ds_read_b128 v[178:181], v134 offset:33792
	ds_read_b128 v[182:185], v133 offset:32768
	ds_read_b128 v[186:189], v133 offset:33792
	ds_read_b128 v[190:193], v132 offset:32768
	ds_read_b128 v[194:197], v132 offset:33792
	ds_read_b128 v[198:201], v131 offset:32768
	ds_read_b128 v[202:205], v131 offset:33792
	buffer_load_dwordx4 v135, s[4:7], s12 offen lds
	v_readfirstlane_b32 s12, v146
	s_addk_i32 s13, 0x100
	s_mov_b32 m0, s12
	s_nop 0
	buffer_load_dwordx4 v135, s[4:7], s13 offen lds
	s_waitcnt lgkmcnt(8)
	s_barrier
	s_waitcnt lgkmcnt(0)
	s_setprio 1
	s_waitcnt lgkmcnt(7)
	v_mfma_f32_16x16x32_bf16 v[126:129], v[158:161], v[174:177], v[126:129]
	v_mfma_f32_16x16x32_bf16 v[122:125], v[166:169], v[174:177], v[122:125]
	s_waitcnt lgkmcnt(5)
	v_mfma_f32_16x16x32_bf16 v[118:121], v[158:161], v[182:185], v[118:121]
	v_mfma_f32_16x16x32_bf16 v[114:117], v[166:169], v[182:185], v[114:117]
	s_waitcnt lgkmcnt(3)
	v_mfma_f32_16x16x32_bf16 v[110:113], v[158:161], v[190:193], v[110:113]
	v_mfma_f32_16x16x32_bf16 v[106:109], v[166:169], v[190:193], v[106:109]
	s_waitcnt lgkmcnt(1)
	v_mfma_f32_16x16x32_bf16 v[102:105], v[158:161], v[198:201], v[102:105]
	v_mfma_f32_16x16x32_bf16 v[98:101], v[166:169], v[198:201], v[98:101]
	v_mfma_f32_16x16x32_bf16 v[126:129], v[162:165], v[178:181], v[126:129]
	v_mfma_f32_16x16x32_bf16 v[122:125], v[170:173], v[178:181], v[122:125]
	v_mfma_f32_16x16x32_bf16 v[118:121], v[162:165], v[186:189], v[118:121]
	v_mfma_f32_16x16x32_bf16 v[114:117], v[170:173], v[186:189], v[114:117]
	v_mfma_f32_16x16x32_bf16 v[110:113], v[162:165], v[194:197], v[110:113]
	v_mfma_f32_16x16x32_bf16 v[106:109], v[170:173], v[194:197], v[106:109]
	s_waitcnt lgkmcnt(0)
	v_mfma_f32_16x16x32_bf16 v[102:105], v[162:165], v[202:205], v[102:105]
	v_mfma_f32_16x16x32_bf16 v[98:101], v[170:173], v[202:205], v[98:101]
	s_setprio 0
	s_barrier
	v_readfirstlane_b32 s12, v147
	s_addk_i32 s29, 0x180
	s_mov_b32 m0, s12
	v_readfirstlane_b32 s12, v148
	ds_read_b128 v[236:239], v137
	ds_read_b128 v[240:243], v137 offset:1024
	ds_read_b128 v[244:247], v137 offset:2048
	ds_read_b128 v[248:251], v137 offset:3072
	buffer_load_dwordx4 v135, s[68:71], s29 offen lds
	s_addk_i32 s38, 0x180
	s_mov_b32 m0, s12
	s_nop 0
	buffer_load_dwordx4 v135, s[68:71], s38 offen lds
	s_barrier
	s_waitcnt lgkmcnt(0)
	s_setprio 1
	s_waitcnt lgkmcnt(3)
	v_mfma_f32_16x16x32_bf16 v[94:97], v[236:239], v[174:177], v[94:97]
	s_waitcnt lgkmcnt(1)
	v_mfma_f32_16x16x32_bf16 v[90:93], v[244:247], v[174:177], v[90:93]
	v_mfma_f32_16x16x32_bf16 v[86:89], v[236:239], v[182:185], v[86:89]
	v_mfma_f32_16x16x32_bf16 v[82:85], v[244:247], v[182:185], v[82:85]
	v_mfma_f32_16x16x32_bf16 v[78:81], v[236:239], v[190:193], v[78:81]
	v_mfma_f32_16x16x32_bf16 v[74:77], v[244:247], v[190:193], v[74:77]
	v_mfma_f32_16x16x32_bf16 v[70:73], v[236:239], v[198:201], v[70:73]
	v_mfma_f32_16x16x32_bf16 v[66:69], v[244:247], v[198:201], v[66:69]
	v_mfma_f32_16x16x32_bf16 v[94:97], v[240:243], v[178:181], v[94:97]
	s_waitcnt lgkmcnt(0)
	v_mfma_f32_16x16x32_bf16 v[90:93], v[248:251], v[178:181], v[90:93]
	v_mfma_f32_16x16x32_bf16 v[86:89], v[240:243], v[186:189], v[86:89]
	v_mfma_f32_16x16x32_bf16 v[82:85], v[248:251], v[186:189], v[82:85]
	v_mfma_f32_16x16x32_bf16 v[78:81], v[240:243], v[194:197], v[78:81]
	v_mfma_f32_16x16x32_bf16 v[74:77], v[248:251], v[194:197], v[74:77]
	v_mfma_f32_16x16x32_bf16 v[70:73], v[240:243], v[202:205], v[70:73]
	v_mfma_f32_16x16x32_bf16 v[66:69], v[248:251], v[202:205], v[66:69]
	s_setprio 0
	v_readfirstlane_b32 s12, v149
	s_addk_i32 s43, 0x180
	s_mov_b32 m0, s12
	v_readfirstlane_b32 s12, v150
	s_barrier
	ds_read_b128 v[174:177], v134 offset:49152
	ds_read_b128 v[178:181], v134 offset:50176
	ds_read_b128 v[182:185], v133 offset:49152
	ds_read_b128 v[186:189], v133 offset:50176
	ds_read_b128 v[190:193], v132 offset:49152
	ds_read_b128 v[194:197], v132 offset:50176
	ds_read_b128 v[198:201], v131 offset:49152
	ds_read_b128 v[202:205], v131 offset:50176
	buffer_load_dwordx4 v135, s[4:7], s43 offen lds
	s_addk_i32 s50, 0x180
	s_mov_b32 m0, s12
	s_nop 0
	buffer_load_dwordx4 v135, s[4:7], s50 offen lds
	s_barrier
; #define WAIT_V(n) asm volatile("s_waitcnt vmcnt(" #n ")" ::: "memory")
; #define WAIT_L(n) asm volatile("s_waitcnt lgkmcnt(" #n ")" ::: "memory")
; #define BAR __builtin_amdgcn_s_barrier()
; #define SCHED __builtin_amdgcn_sched_barrier(0)
; template <int MODE>
; __device__ __forceinline__ void gemm_tile(const int ph, const int which, const int pm, const int pn) {
;     ...
;     LDA(At, 1, 1); STAGE(SA(1, 0), RA, brow, t + 3);
;     BAR; WAIT_L(0); MMA(1, 0, At, B0); BAR; SCHED;
;     STAGE(SB(1, 1), RB, bcolB, t + 3);
;     WAIT_V(6); BAR; MMA(1, 1, At, B1); BAR;
;   }
;   {
;     LDB(B0, 0, 0); LDA(At, 0, 0); STAGE(SA(1, 1), RA, brow + HALF, nt - 1);
;     BAR; WAIT_L(0); MMA(0, 0, At, B0); BAR;
;     LDB(B1, 0, 1); BAR; WAIT_L(0); MMA(0, 1, At, B1); BAR;
	s_waitcnt lgkmcnt(0)
	s_setprio 1
	s_waitcnt lgkmcnt(7)
	v_mfma_f32_16x16x32_bf16 v[62:65], v[158:161], v[174:177], v[62:65]
	v_mfma_f32_16x16x32_bf16 v[58:61], v[166:169], v[174:177], v[58:61]
	s_waitcnt lgkmcnt(5)
	v_mfma_f32_16x16x32_bf16 v[54:57], v[158:161], v[182:185], v[54:57]
	v_mfma_f32_16x16x32_bf16 v[50:53], v[166:169], v[182:185], v[50:53]
	s_waitcnt lgkmcnt(3)
	v_mfma_f32_16x16x32_bf16 v[46:49], v[158:161], v[190:193], v[46:49]
	v_mfma_f32_16x16x32_bf16 v[42:45], v[166:169], v[190:193], v[42:45]
	s_waitcnt lgkmcnt(1)
	v_mfma_f32_16x16x32_bf16 v[38:41], v[158:161], v[198:201], v[38:41]
	v_mfma_f32_16x16x32_bf16 v[34:37], v[166:169], v[198:201], v[34:37]
	v_mfma_f32_16x16x32_bf16 v[62:65], v[162:165], v[178:181], v[62:65]
	v_mfma_f32_16x16x32_bf16 v[58:61], v[170:173], v[178:181], v[58:61]
	v_mfma_f32_16x16x32_bf16 v[54:57], v[162:165], v[186:189], v[54:57]
	v_mfma_f32_16x16x32_bf16 v[50:53], v[170:173], v[186:189], v[50:53]
	v_mfma_f32_16x16x32_bf16 v[46:49], v[162:165], v[194:197], v[46:49]
	v_mfma_f32_16x16x32_bf16 v[42:45], v[170:173], v[194:197], v[42:45]
	s_waitcnt lgkmcnt(0)
	v_mfma_f32_16x16x32_bf16 v[38:41], v[162:165], v[202:205], v[38:41]
	v_mfma_f32_16x16x32_bf16 v[34:37], v[170:173], v[202:205], v[34:37]
	s_setprio 0
	s_barrier
	v_readfirstlane_b32 s12, v152
	s_addk_i32 s51, 0x180
	s_mov_b32 m0, s12
	v_readfirstlane_b32 s12, v154
	buffer_load_dwordx4 v135, s[68:71], s51 offen lds
	s_addk_i32 s72, 0x180
	s_mov_b32 m0, s12
	s_nop 0
	buffer_load_dwordx4 v135, s[68:71], s72 offen lds
	s_waitcnt vmcnt(6)
	s_barrier
	s_setprio 1
	v_mfma_f32_16x16x32_bf16 v[30:33], v[236:239], v[174:177], v[30:33]
	v_mfma_f32_16x16x32_bf16 v[26:29], v[244:247], v[174:177], v[26:29]
	v_mfma_f32_16x16x32_bf16 v[22:25], v[236:239], v[182:185], v[22:25]
	v_mfma_f32_16x16x32_bf16 v[18:21], v[244:247], v[182:185], v[18:21]
	v_mfma_f32_16x16x32_bf16 v[14:17], v[236:239], v[190:193], v[14:17]
	v_mfma_f32_16x16x32_bf16 v[10:13], v[244:247], v[190:193], v[10:13]
	v_mfma_f32_16x16x32_bf16 v[6:9], v[236:239], v[198:201], v[6:9]
	v_mfma_f32_16x16x32_bf16 v[2:5], v[244:247], v[198:201], v[2:5]
	v_mfma_f32_16x16x32_bf16 v[30:33], v[240:243], v[178:181], v[30:33]
	v_mfma_f32_16x16x32_bf16 v[26:29], v[248:251], v[178:181], v[26:29]
	v_mfma_f32_16x16x32_bf16 v[22:25], v[240:243], v[186:189], v[22:25]
	v_mfma_f32_16x16x32_bf16 v[18:21], v[248:251], v[186:189], v[18:21]
	v_mfma_f32_16x16x32_bf16 v[14:17], v[240:243], v[194:197], v[14:17]
	v_mfma_f32_16x16x32_bf16 v[10:13], v[248:251], v[194:197], v[10:13]
	v_mfma_f32_16x16x32_bf16 v[6:9], v[240:243], v[202:205], v[6:9]
	v_mfma_f32_16x16x32_bf16 v[2:5], v[248:251], v[202:205], v[2:5]
	s_setprio 0
	s_addk_i32 s27, 0x100
	s_cmp_lt_u32 vcc_lo, s16
	s_cbranch_scc1 .Lgemm_head_218
	s_barrier
	s_add_i32 s6, s28, s11
	s_lshl_b32 s6, s6, 1
	v_readfirstlane_b32 s12, v153
	s_add_i32 s11, s6, 0xffffff80
	s_mov_b32 s6, s70
	s_mov_b32 s7, s71
	s_mov_b32 m0, s12
	ds_read_b128 v[140:143], v156
	ds_read_b128 v[146:149], v156 offset:1024
	ds_read_b128 v[158:161], v156 offset:2048
	ds_read_b128 v[162:165], v156 offset:3072
	ds_read_b128 v[166:169], v134
	ds_read_b128 v[170:173], v134 offset:1024
	ds_read_b128 v[174:177], v133
	ds_read_b128 v[178:181], v133 offset:1024
	ds_read_b128 v[182:185], v132
	ds_read_b128 v[186:189], v132 offset:1024
	ds_read_b128 v[190:193], v131
	ds_read_b128 v[194:197], v131 offset:1024
	buffer_load_dwordx4 v135, s[4:7], s11 offen lds
	s_add_i32 s11, s11, s10
	v_readfirstlane_b32 s10, v151
	s_mov_b32 m0, s10
	s_nop 0
	buffer_load_dwordx4 v135, s[4:7], s11 offen lds
	s_barrier
	s_waitcnt lgkmcnt(0)
	s_setprio 1
	s_waitcnt lgkmcnt(7)
	v_mfma_f32_16x16x32_bf16 v[126:129], v[140:143], v[166:169], v[126:129]
	v_mfma_f32_16x16x32_bf16 v[122:125], v[158:161], v[166:169], v[122:125]
	s_waitcnt lgkmcnt(5)
	v_mfma_f32_16x16x32_bf16 v[118:121], v[140:143], v[174:177], v[118:121]
	v_mfma_f32_16x16x32_bf16 v[114:117], v[158:161], v[174:177], v[114:117]
	s_waitcnt lgkmcnt(1)
	v_mfma_f32_16x16x32_bf16 v[102:105], v[140:143], v[190:193], v[102:105]
	v_mfma_f32_16x16x32_bf16 v[98:101], v[158:161], v[190:193], v[98:101]
	v_mfma_f32_16x16x32_bf16 v[126:129], v[146:149], v[170:173], v[126:129]
	v_mfma_f32_16x16x32_bf16 v[122:125], v[162:165], v[170:173], v[122:125]
	v_mfma_f32_16x16x32_bf16 v[118:121], v[146:149], v[178:181], v[118:121]
	v_mfma_f32_16x16x32_bf16 v[114:117], v[162:165], v[178:181], v[114:117]
	v_mfma_f32_16x16x32_bf16 v[110:113], v[140:143], v[182:185], v[110:113]
	v_mfma_f32_16x16x32_bf16 v[106:109], v[158:161], v[182:185], v[106:109]
	s_waitcnt lgkmcnt(0)
	v_mfma_f32_16x16x32_bf16 v[102:105], v[146:149], v[194:197], v[102:105]
	v_mfma_f32_16x16x32_bf16 v[98:101], v[162:165], v[194:197], v[98:101]
	v_mfma_f32_16x16x32_bf16 v[150:153], v[146:149], v[186:189], v[110:113]
	v_mfma_f32_16x16x32_bf16 v[198:201], v[162:165], v[186:189], v[106:109]
	s_setprio 0
	s_barrier
	s_nop 0
	ds_read_b128 v[106:109], v155
	ds_read_b128 v[110:113], v155 offset:1024
	ds_read_b128 v[202:205], v155 offset:2048
	ds_read_b128 v[154:157], v155 offset:3072
	s_barrier
; #define WAIT_V(n) asm volatile("s_waitcnt vmcnt(" #n ")" ::: "memory")
; #define WAIT_L(n) asm volatile("s_waitcnt lgkmcnt(" #n ")" ::: "memory")
; #define BAR __builtin_amdgcn_s_barrier()
; template <int MODE>
; __device__ __forceinline__ void gemm_tile(const int ph, const int which, const int pm, const int pn) {
;     ...
;     LDB(B1, 0, 1); BAR; WAIT_L(0); MMA(0, 1, At, B1); BAR;
;     LDA(At, 0, 1); WAIT_V(4); BAR; WAIT_L(0); MMA(1, 0, At, B0); MMA(1, 1, At, B1); BAR;
;   }
;   {
;     LDB(B0, 1, 0); LDA(At, 1, 0); WAIT_V(2); BAR; WAIT_L(0); MMA(0, 0, At, B0); BAR;
	s_waitcnt lgkmcnt(0)
	s_setprio 1
	s_waitcnt lgkmcnt(3)
	v_mfma_f32_16x16x32_bf16 v[86:89], v[106:109], v[174:177], v[86:89]
	s_waitcnt lgkmcnt(1)
	v_mfma_f32_16x16x32_bf16 v[82:85], v[202:205], v[174:177], v[82:85]
	v_mfma_f32_16x16x32_bf16 v[70:73], v[106:109], v[190:193], v[70:73]
	v_mfma_f32_16x16x32_bf16 v[66:69], v[202:205], v[190:193], v[66:69]
	v_mfma_f32_16x16x32_bf16 v[94:97], v[106:109], v[166:169], v[94:97]
	v_mfma_f32_16x16x32_bf16 v[90:93], v[202:205], v[166:169], v[90:93]
	v_mfma_f32_16x16x32_bf16 v[86:89], v[110:113], v[178:181], v[86:89]
	s_waitcnt lgkmcnt(0)
	v_mfma_f32_16x16x32_bf16 v[82:85], v[154:157], v[178:181], v[82:85]
	v_mfma_f32_16x16x32_bf16 v[78:81], v[106:109], v[182:185], v[78:81]
	v_mfma_f32_16x16x32_bf16 v[74:77], v[202:205], v[182:185], v[74:77]
	v_mfma_f32_16x16x32_bf16 v[70:73], v[110:113], v[194:197], v[70:73]
	v_mfma_f32_16x16x32_bf16 v[66:69], v[154:157], v[194:197], v[66:69]
	v_mfma_f32_16x16x32_bf16 v[236:239], v[110:113], v[170:173], v[94:97]
	v_mfma_f32_16x16x32_bf16 v[166:169], v[154:157], v[170:173], v[90:93]
	v_mfma_f32_16x16x32_bf16 v[170:173], v[110:113], v[186:189], v[78:81]
	v_mfma_f32_16x16x32_bf16 v[174:177], v[154:157], v[186:189], v[74:77]
	s_setprio 0
	s_barrier
	s_nop 0
	ds_read_b128 v[74:77], v134 offset:16384
	ds_read_b128 v[78:81], v134 offset:17408
	ds_read_b128 v[90:93], v133 offset:16384
	ds_read_b128 v[94:97], v133 offset:17408
	ds_read_b128 v[178:181], v132 offset:16384
	ds_read_b128 v[182:185], v132 offset:17408
	ds_read_b128 v[186:189], v131 offset:16384
	ds_read_b128 v[190:193], v131 offset:17408
	s_waitcnt vmcnt(4)
	s_barrier
	s_waitcnt lgkmcnt(0)
	s_setprio 1
	s_waitcnt lgkmcnt(7)
	v_mfma_f32_16x16x32_bf16 v[62:65], v[140:143], v[74:77], v[62:65]
	v_mfma_f32_16x16x32_bf16 v[58:61], v[158:161], v[74:77], v[58:61]
	s_waitcnt lgkmcnt(5)
	v_mfma_f32_16x16x32_bf16 v[54:57], v[140:143], v[90:93], v[54:57]
	v_mfma_f32_16x16x32_bf16 v[50:53], v[158:161], v[90:93], v[50:53]
	s_waitcnt lgkmcnt(1)
	v_mfma_f32_16x16x32_bf16 v[38:41], v[140:143], v[186:189], v[38:41]
	v_mfma_f32_16x16x32_bf16 v[34:37], v[158:161], v[186:189], v[34:37]
	v_mfma_f32_16x16x32_bf16 v[62:65], v[146:149], v[78:81], v[62:65]
	v_mfma_f32_16x16x32_bf16 v[58:61], v[162:165], v[78:81], v[58:61]
	v_mfma_f32_16x16x32_bf16 v[54:57], v[146:149], v[94:97], v[54:57]
	v_mfma_f32_16x16x32_bf16 v[50:53], v[162:165], v[94:97], v[50:53]
	v_mfma_f32_16x16x32_bf16 v[46:49], v[140:143], v[178:181], v[46:49]
	v_mfma_f32_16x16x32_bf16 v[42:45], v[158:161], v[178:181], v[42:45]
	s_waitcnt lgkmcnt(0)
	v_mfma_f32_16x16x32_bf16 v[38:41], v[146:149], v[190:193], v[38:41]
	v_mfma_f32_16x16x32_bf16 v[34:37], v[162:165], v[190:193], v[34:37]
	v_mfma_f32_16x16x32_bf16 v[194:197], v[146:149], v[182:185], v[46:49]
	v_mfma_f32_16x16x32_bf16 v[240:243], v[162:165], v[182:185], v[42:45]
	s_setprio 0
	s_setprio 1
	v_mfma_f32_16x16x32_bf16 v[22:25], v[106:109], v[90:93], v[22:25]
	v_mfma_f32_16x16x32_bf16 v[18:21], v[202:205], v[90:93], v[18:21]
	v_mfma_f32_16x16x32_bf16 v[6:9], v[106:109], v[186:189], v[6:9]
	v_mfma_f32_16x16x32_bf16 v[2:5], v[202:205], v[186:189], v[2:5]
	v_mfma_f32_16x16x32_bf16 v[30:33], v[106:109], v[74:77], v[30:33]
	v_mfma_f32_16x16x32_bf16 v[26:29], v[202:205], v[74:77], v[26:29]
	v_mfma_f32_16x16x32_bf16 v[22:25], v[110:113], v[94:97], v[22:25]
	v_mfma_f32_16x16x32_bf16 v[18:21], v[154:157], v[94:97], v[18:21]
	v_mfma_f32_16x16x32_bf16 v[14:17], v[106:109], v[178:181], v[14:17]
	v_mfma_f32_16x16x32_bf16 v[10:13], v[202:205], v[178:181], v[10:13]
	v_mfma_f32_16x16x32_bf16 v[6:9], v[110:113], v[190:193], v[6:9]
	v_mfma_f32_16x16x32_bf16 v[2:5], v[154:157], v[190:193], v[2:5]
	v_mfma_f32_16x16x32_bf16 v[140:143], v[110:113], v[78:81], v[30:33]
	v_mfma_f32_16x16x32_bf16 v[146:149], v[154:157], v[78:81], v[26:29]
	v_mfma_f32_16x16x32_bf16 v[158:161], v[110:113], v[182:185], v[14:17]
	v_mfma_f32_16x16x32_bf16 v[162:165], v[154:157], v[182:185], v[10:13]
	s_setprio 0
	s_barrier
	s_nop 0
	ds_read_b128 v[10:13], v144
	ds_read_b128 v[14:17], v144 offset:1024
	ds_read_b128 v[154:157], v144 offset:2048
	ds_read_b128 v[178:181], v144 offset:3072
	ds_read_b128 v[26:29], v134 offset:32768
	ds_read_b128 v[30:33], v134 offset:33792
	ds_read_b128 v[42:45], v133 offset:32768
	ds_read_b128 v[46:49], v133 offset:33792
	ds_read_b128 v[182:185], v132 offset:32768
	ds_read_b128 v[186:189], v132 offset:33792
	ds_read_b128 v[190:193], v131 offset:32768
	ds_read_b128 v[202:205], v131 offset:33792
	s_waitcnt vmcnt(2)
	s_barrier
; #define WAIT_V(n) asm volatile("s_waitcnt vmcnt(" #n ")" ::: "memory")
; #define WAIT_L(n) asm volatile("s_waitcnt lgkmcnt(" #n ")" ::: "memory")
; #define BAR __builtin_amdgcn_s_barrier()
; template <int MODE>
; __device__ __forceinline__ void gemm_tile(const int ph, const int which, const int pm, const int pn) {
;     ...
;     LDB(B0, 1, 0); LDA(At, 1, 0); WAIT_V(2); BAR; WAIT_L(0); MMA(0, 0, At, B0); BAR;
;     LDB(B1, 1, 1); WAIT_V(0); BAR; WAIT_L(0); MMA(0, 1, At, B1); BAR;
;     LDA(At, 1, 1); BAR; WAIT_L(0); MMA(1, 0, At, B0); MMA(1, 1, At, B1); BAR;
;   }
;   if (wr == 0) BAR;
	s_waitcnt lgkmcnt(0)
	s_setprio 1
	s_waitcnt lgkmcnt(7)
	v_mfma_f32_16x16x32_bf16 v[74:77], v[10:13], v[26:29], v[126:129]
	s_waitcnt lgkmcnt(6)
	v_mfma_f32_16x16x32_bf16 v[126:129], v[14:17], v[30:33], v[74:77]
	v_mfma_f32_16x16x32_bf16 v[74:77], v[154:157], v[26:29], v[122:125]
	v_mfma_f32_16x16x32_bf16 v[122:125], v[178:181], v[30:33], v[74:77]
	s_waitcnt lgkmcnt(5)
	v_mfma_f32_16x16x32_bf16 v[74:77], v[10:13], v[42:45], v[118:121]
	s_waitcnt lgkmcnt(4)
	v_mfma_f32_16x16x32_bf16 v[110:113], v[14:17], v[46:49], v[74:77]
	v_mfma_f32_16x16x32_bf16 v[74:77], v[154:157], v[42:45], v[114:117]
	v_mfma_f32_16x16x32_bf16 v[106:109], v[178:181], v[46:49], v[74:77]
	s_waitcnt lgkmcnt(3)
	v_mfma_f32_16x16x32_bf16 v[74:77], v[10:13], v[182:185], v[150:153]
	s_waitcnt lgkmcnt(2)
	v_mfma_f32_16x16x32_bf16 v[94:97], v[14:17], v[186:189], v[74:77]
	v_mfma_f32_16x16x32_bf16 v[74:77], v[154:157], v[182:185], v[198:201]
	v_mfma_f32_16x16x32_bf16 v[90:93], v[178:181], v[186:189], v[74:77]
	s_waitcnt lgkmcnt(1)
	v_mfma_f32_16x16x32_bf16 v[74:77], v[10:13], v[190:193], v[102:105]
	s_waitcnt lgkmcnt(0)
	v_mfma_f32_16x16x32_bf16 v[78:81], v[14:17], v[202:205], v[74:77]
	v_mfma_f32_16x16x32_bf16 v[74:77], v[154:157], v[190:193], v[98:101]
	v_mfma_f32_16x16x32_bf16 v[74:77], v[178:181], v[202:205], v[74:77]
	s_setprio 0
	s_barrier
	ds_read_b128 v[150:153], v137
	ds_read_b128 v[198:201], v137 offset:1024
	ds_read_b128 v[244:247], v137 offset:2048
	ds_read_b128 v[248:251], v137 offset:3072
	s_waitcnt vmcnt(0)
	s_barrier
	s_waitcnt lgkmcnt(0)
	s_setprio 1
	s_waitcnt lgkmcnt(3)
	v_mfma_f32_16x16x32_bf16 v[98:101], v[150:153], v[26:29], v[236:239]
	s_waitcnt lgkmcnt(1)
	v_mfma_f32_16x16x32_bf16 v[26:29], v[244:247], v[26:29], v[166:169]
	s_waitcnt lgkmcnt(0)
	v_mfma_f32_16x16x32_bf16 v[114:117], v[248:251], v[30:33], v[26:29]
	v_mfma_f32_16x16x32_bf16 v[26:29], v[150:153], v[42:45], v[86:89]
	v_mfma_f32_16x16x32_bf16 v[102:105], v[198:201], v[46:49], v[26:29]
	v_mfma_f32_16x16x32_bf16 v[26:29], v[244:247], v[42:45], v[82:85]
	v_mfma_f32_16x16x32_bf16 v[118:121], v[198:201], v[30:33], v[98:101]
	v_mfma_f32_16x16x32_bf16 v[98:101], v[248:251], v[46:49], v[26:29]
	v_mfma_f32_16x16x32_bf16 v[26:29], v[150:153], v[182:185], v[170:173]
	v_mfma_f32_16x16x32_bf16 v[86:89], v[198:201], v[186:189], v[26:29]
	v_mfma_f32_16x16x32_bf16 v[26:29], v[244:247], v[182:185], v[174:177]
	v_mfma_f32_16x16x32_bf16 v[82:85], v[248:251], v[186:189], v[26:29]
	v_mfma_f32_16x16x32_bf16 v[26:29], v[150:153], v[190:193], v[70:73]
	v_mfma_f32_16x16x32_bf16 v[70:73], v[198:201], v[202:205], v[26:29]
	v_mfma_f32_16x16x32_bf16 v[26:29], v[244:247], v[190:193], v[66:69]
	v_mfma_f32_16x16x32_bf16 v[66:69], v[248:251], v[202:205], v[26:29]
	s_setprio 0
	s_barrier
	ds_read_b128 v[166:169], v134 offset:49152
	ds_read_b128 v[134:137], v134 offset:50176
	ds_read_b128 v[170:173], v133 offset:49152
	ds_read_b128 v[174:177], v133 offset:50176
	ds_read_b128 v[182:185], v132 offset:49152
	ds_read_b128 v[186:189], v132 offset:50176
	ds_read_b128 v[190:193], v131 offset:49152
	ds_read_b128 v[202:205], v131 offset:50176
	s_barrier
	s_waitcnt lgkmcnt(0)
	s_setprio 1
	s_waitcnt lgkmcnt(7)
	v_mfma_f32_16x16x32_bf16 v[26:29], v[10:13], v[166:169], v[62:65]
	s_waitcnt lgkmcnt(6)
	v_mfma_f32_16x16x32_bf16 v[62:65], v[14:17], v[134:137], v[26:29]
	v_mfma_f32_16x16x32_bf16 v[26:29], v[154:157], v[166:169], v[58:61]
	v_mfma_f32_16x16x32_bf16 v[58:61], v[178:181], v[134:137], v[26:29]
	s_waitcnt lgkmcnt(5)
	v_mfma_f32_16x16x32_bf16 v[26:29], v[10:13], v[170:173], v[54:57]
	s_waitcnt lgkmcnt(4)
	v_mfma_f32_16x16x32_bf16 v[46:49], v[14:17], v[174:177], v[26:29]
	v_mfma_f32_16x16x32_bf16 v[26:29], v[154:157], v[170:173], v[50:53]
	v_mfma_f32_16x16x32_bf16 v[42:45], v[178:181], v[174:177], v[26:29]
	s_waitcnt lgkmcnt(3)
	v_mfma_f32_16x16x32_bf16 v[26:29], v[10:13], v[182:185], v[194:197]
	s_waitcnt lgkmcnt(1)
	v_mfma_f32_16x16x32_bf16 v[10:13], v[10:13], v[190:193], v[38:41]
	v_mfma_f32_16x16x32_bf16 v[30:33], v[14:17], v[186:189], v[26:29]
	v_mfma_f32_16x16x32_bf16 v[26:29], v[154:157], v[182:185], v[240:243]
	s_waitcnt lgkmcnt(0)
	v_mfma_f32_16x16x32_bf16 v[14:17], v[14:17], v[202:205], v[10:13]
	v_mfma_f32_16x16x32_bf16 v[10:13], v[154:157], v[190:193], v[34:37]
	v_mfma_f32_16x16x32_bf16 v[26:29], v[178:181], v[186:189], v[26:29]
	v_mfma_f32_16x16x32_bf16 v[10:13], v[178:181], v[202:205], v[10:13]
	s_setprio 0
	s_setprio 1
	v_mfma_f32_16x16x32_bf16 v[34:37], v[150:153], v[166:169], v[140:143]
	v_mfma_f32_16x16x32_bf16 v[54:57], v[198:201], v[134:137], v[34:37]
	v_mfma_f32_16x16x32_bf16 v[34:37], v[244:247], v[166:169], v[146:149]
	v_mfma_f32_16x16x32_bf16 v[18:21], v[244:247], v[170:173], v[18:21]
	v_mfma_f32_16x16x32_bf16 v[50:53], v[248:251], v[134:137], v[34:37]
	v_mfma_f32_16x16x32_bf16 v[22:25], v[150:153], v[170:173], v[22:25]
	v_mfma_f32_16x16x32_bf16 v[34:37], v[248:251], v[174:177], v[18:21]
	v_mfma_f32_16x16x32_bf16 v[18:21], v[150:153], v[182:185], v[158:161]
	v_mfma_f32_16x16x32_bf16 v[38:41], v[198:201], v[174:177], v[22:25]
	v_mfma_f32_16x16x32_bf16 v[22:25], v[198:201], v[186:189], v[18:21]
	v_mfma_f32_16x16x32_bf16 v[18:21], v[244:247], v[182:185], v[162:165]
	v_mfma_f32_16x16x32_bf16 v[6:9], v[150:153], v[190:193], v[6:9]
	v_mfma_f32_16x16x32_bf16 v[2:5], v[244:247], v[190:193], v[2:5]
	v_mfma_f32_16x16x32_bf16 v[18:21], v[248:251], v[186:189], v[18:21]
	v_mfma_f32_16x16x32_bf16 v[6:9], v[198:201], v[202:205], v[6:9]
	v_mfma_f32_16x16x32_bf16 v[2:5], v[248:251], v[202:205], v[2:5]
	s_setprio 0
	s_movk_i32 s4, 0x100
	v_cmp_gt_u32_e32 vcc, s4, v0
	s_barrier
	s_and_saveexec_b64 s[4:5], vcc
	s_cbranch_execz .LBB0_221
	s_barrier

; #define WAIT_V(n) asm volatile("s_waitcnt vmcnt(" #n ")" ::: "memory")
; #define BAR __builtin_amdgcn_s_barrier()
; template <int MODE>
; __device__ __forceinline__ void gemm_tile(const int ph, const int which, const int pm, const int pn) {
;     ...
;   f32x4 acc[2][2][4][2] = {};
;   bf16x8 At[4][2], B0[2][2], B1[2][2];
;   const int nt = K / BK;
;   const int brow = browA;
;   STAGE(SB(0, 0), RB, bcol, 0);
;   STAGE(SA(0, 0), RA, brow, 0);
;   STAGE(SB(0, 1), RB, bcolB, 0);
;   STAGE(SA(0, 1), RA, brow + HALF, 0);
;   if (wr == 1) BAR;
;   WAIT_V(4);
;   BAR;
;   STAGE(SB(1, 0), RB, bcol, 1);
;   STAGE(SA(1, 0), RA, brow, 1);
;   STAGE(SB(1, 1), RB, bcolB, 1);
;   WAIT_V(6);
;   BAR;
.LBB0_369:
	s_or_b64 exec, exec, s[2:3]
	v_add_u32_e32 v145, 0x18000, v131
	v_add_u32_e32 v146, 0x1a000, v131
	v_readfirstlane_b32 s6, v145
	s_or_b32 s3, s17, 0x80
	s_mov_b32 m0, s6
	v_readfirstlane_b32 s6, v146
	s_waitcnt vmcnt(4)
	s_barrier
	buffer_load_dwordx4 v130, s[68:71], s3 offen lds
	s_add_i32 s3, s3, s8
	s_mov_b32 m0, s6
	v_add_u32_e32 v147, 0x8000, v131
	buffer_load_dwordx4 v130, s[68:71], s3 offen lds
	s_or_b32 s3, s11, 0x80
	v_readfirstlane_b32 s11, v147
	v_add_u32_e32 v148, 0xa000, v131
	s_mov_b32 s6, s70
	s_mov_b32 s7, s71
	s_mov_b32 m0, s11
	v_readfirstlane_b32 s11, v148
	buffer_load_dwordx4 v130, s[4:7], s3 offen lds
	s_add_i32 s3, s3, s8
	s_mov_b32 m0, s11
	v_add_u32_e32 v150, 0x1c000, v131
	buffer_load_dwordx4 v130, s[4:7], s3 offen lds
	s_or_b32 s3, s10, 0x80
	v_readfirstlane_b32 s10, v150
	v_add_u32_e32 v152, 0x1e000, v131
	s_mov_b32 m0, s10
	v_readfirstlane_b32 s10, v152
	buffer_load_dwordx4 v130, s[68:71], s3 offen lds
	s_add_i32 s3, s3, s8
	s_mov_b32 m0, s10
	v_and_b32_e32 v2, 15, v164
	buffer_load_dwordx4 v130, s[68:71], s3 offen lds
	v_bfe_u32 v162, v164, 4, 2
	v_lshlrev_b32_e32 v4, 4, v162
	v_lshlrev_b32_e32 v5, 6, v2
	v_lshlrev_b32_e32 v7, 2, v164
	v_or_b32_e32 v6, v4, v5
	v_and_b32_e32 v7, 32, v7
	s_mov_b32 s3, 0x10000
	v_bitop3_b32 v8, v6, s3, v7 bitop3:0xde
	s_mov_b32 s3, 0x14000
	v_bitop3_b32 v9, v6, s3, v7 bitop3:0xde
	s_mov_b32 s3, 0x18000
	v_bitop3_b32 v10, v6, s3, v7 bitop3:0xde
	s_mov_b32 s3, 0x1c000
	s_lshl_b32 s12, s18, 1
	v_bitop3_b32 v6, v6, s3, v7 bitop3:0xde
	v_lshl_or_b32 v163, v167, 6, v2
	v_lshlrev_b32_e32 v2, 6, v164
	s_add_i32 s3, s12, 0x180
	s_addk_i32 s12, 0x80
	v_bfe_u32 v0, v164, 6, 2
	v_lshlrev_b32_e32 v11, 13, v167
	v_and_b32_e32 v2, 0x3c0, v2
	s_lshl_b32 s11, s16, 1
	s_mul_i32 s17, s26, s12
	s_lshl_b32 s12, s20, 1
	s_lshr_b32 s2, s26, 6
	v_lshlrev_b32_e32 v3, 12, v0
	v_bitop3_b32 v5, v4, v7, v5 bitop3:0x36
	v_bitop3_b32 v4, v2, v7, v4 bitop3:0x36
	v_or_b32_e32 v7, 0x800, v11
	v_or_b32_e32 v12, 0x1000, v11
	v_or_b32_e32 v13, 0x1800, v11
	s_lshl_b32 s13, s26, 1
	s_add_i32 s10, s18, 0x80
	s_addk_i32 s11, 0x80
	s_addk_i32 s12, 0x80
	v_mov_b32_e32 v2, 0
	s_add_i32 s2, s2, -2
	v_add_u32_e32 v151, 0xc000, v131
	v_add_u32_e32 v149, 0xe000, v131
	s_mul_i32 s3, s26, s3
	s_mul_i32 s10, s13, s10
	s_mul_i32 s11, s26, s11
	s_mul_i32 s16, s13, s16
	s_mul_i32 s18, s13, s18
	s_mul_i32 s19, s26, s12
	s_mul_i32 s20, s13, s20
	s_mov_b32 s21, 0
	v_add_u32_e32 v154, v8, v3
	v_add_u32_e32 v141, v5, v11
	v_add_u32_e32 v140, v4, v7
	v_add_u32_e32 v139, v4, v12
	v_add_u32_e32 v138, v4, v13
	v_add_u32_e32 v153, v9, v3
	v_add_u32_e32 v137, v10, v3
	v_add_u32_e32 v142, v6, v3
	s_mov_b32 s22, 0
	v_mov_b32_e32 v3, v2
	v_mov_b32_e32 v4, v2
	v_mov_b32_e32 v5, v2
	v_mov_b32_e32 v6, v2
	v_mov_b32_e32 v7, v2
	v_mov_b32_e32 v8, v2
	v_mov_b32_e32 v9, v2
	v_mov_b32_e32 v18, v2
	v_mov_b32_e32 v19, v2
	v_mov_b32_e32 v20, v2
	v_mov_b32_e32 v21, v2
	v_mov_b32_e32 v30, v2
	v_mov_b32_e32 v31, v2
	v_mov_b32_e32 v32, v2
	v_mov_b32_e32 v33, v2
	v_mov_b32_e32 v42, v2
	v_mov_b32_e32 v43, v2
	v_mov_b32_e32 v44, v2
	v_mov_b32_e32 v45, v2
	v_mov_b32_e32 v54, v2
	v_mov_b32_e32 v55, v2
	v_mov_b32_e32 v56, v2
	v_mov_b32_e32 v57, v2
	v_mov_b32_e32 v66, v2
	v_mov_b32_e32 v67, v2
	v_mov_b32_e32 v68, v2
	v_mov_b32_e32 v69, v2
	v_mov_b32_e32 v78, v2
	v_mov_b32_e32 v79, v2
	v_mov_b32_e32 v80, v2
	v_mov_b32_e32 v81, v2
	v_mov_b32_e32 v10, v2
	v_mov_b32_e32 v11, v2
	v_mov_b32_e32 v12, v2
	v_mov_b32_e32 v13, v2
	v_mov_b32_e32 v22, v2
	v_mov_b32_e32 v23, v2
	v_mov_b32_e32 v24, v2
	v_mov_b32_e32 v25, v2
	v_mov_b32_e32 v34, v2
	v_mov_b32_e32 v35, v2
	v_mov_b32_e32 v36, v2
	v_mov_b32_e32 v37, v2
	v_mov_b32_e32 v46, v2
	v_mov_b32_e32 v47, v2
	v_mov_b32_e32 v48, v2
	v_mov_b32_e32 v49, v2
	v_mov_b32_e32 v58, v2
	v_mov_b32_e32 v59, v2
	v_mov_b32_e32 v60, v2
	v_mov_b32_e32 v61, v2
	v_mov_b32_e32 v70, v2
	v_mov_b32_e32 v71, v2
	v_mov_b32_e32 v72, v2
	v_mov_b32_e32 v73, v2
	v_mov_b32_e32 v82, v2
	v_mov_b32_e32 v83, v2
	v_mov_b32_e32 v84, v2
	v_mov_b32_e32 v85, v2
	v_mov_b32_e32 v94, v2
	v_mov_b32_e32 v95, v2
	v_mov_b32_e32 v96, v2
	v_mov_b32_e32 v97, v2
	v_mov_b32_e32 v14, v2
	v_mov_b32_e32 v15, v2
	v_mov_b32_e32 v16, v2
	v_mov_b32_e32 v17, v2
	v_mov_b32_e32 v26, v2
	v_mov_b32_e32 v27, v2
	v_mov_b32_e32 v28, v2
	v_mov_b32_e32 v29, v2
	v_mov_b32_e32 v38, v2
	v_mov_b32_e32 v39, v2
	v_mov_b32_e32 v40, v2
	v_mov_b32_e32 v41, v2
	v_mov_b32_e32 v50, v2
	v_mov_b32_e32 v51, v2
	v_mov_b32_e32 v52, v2
	v_mov_b32_e32 v53, v2
	v_mov_b32_e32 v62, v2
	v_mov_b32_e32 v63, v2
	v_mov_b32_e32 v64, v2
	v_mov_b32_e32 v65, v2
	v_mov_b32_e32 v74, v2
	v_mov_b32_e32 v75, v2
	v_mov_b32_e32 v76, v2
	v_mov_b32_e32 v77, v2
	v_mov_b32_e32 v86, v2
	v_mov_b32_e32 v87, v2
	v_mov_b32_e32 v88, v2
	v_mov_b32_e32 v89, v2
	v_mov_b32_e32 v98, v2
	v_mov_b32_e32 v99, v2
	v_mov_b32_e32 v100, v2
	v_mov_b32_e32 v101, v2
	v_mov_b32_e32 v90, v2
	v_mov_b32_e32 v91, v2
	v_mov_b32_e32 v92, v2
	v_mov_b32_e32 v93, v2
	v_mov_b32_e32 v102, v2
	v_mov_b32_e32 v103, v2
	v_mov_b32_e32 v104, v2
	v_mov_b32_e32 v105, v2
	v_mov_b32_e32 v106, v2
	v_mov_b32_e32 v107, v2
	v_mov_b32_e32 v108, v2
	v_mov_b32_e32 v109, v2
	v_mov_b32_e32 v110, v2
	v_mov_b32_e32 v111, v2
	v_mov_b32_e32 v112, v2
	v_mov_b32_e32 v113, v2
	v_mov_b32_e32 v114, v2
	v_mov_b32_e32 v115, v2
	v_mov_b32_e32 v116, v2
	v_mov_b32_e32 v117, v2
	v_mov_b32_e32 v118, v2
	v_mov_b32_e32 v119, v2
	v_mov_b32_e32 v120, v2
	v_mov_b32_e32 v121, v2
	v_mov_b32_e32 v122, v2
	v_mov_b32_e32 v123, v2
	v_mov_b32_e32 v124, v2
	v_mov_b32_e32 v125, v2
	v_mov_b32_e32 v126, v2
	v_mov_b32_e32 v127, v2
	v_mov_b32_e32 v128, v2
	v_mov_b32_e32 v129, v2
	s_waitcnt vmcnt(6)

; #define WAIT_V(n) asm volatile("s_waitcnt vmcnt(" #n ")" ::: "memory")
; #define WAIT_L(n) asm volatile("s_waitcnt lgkmcnt(" #n ")" ::: "memory")
; #define BAR __builtin_amdgcn_s_barrier()
; #define SCHED __builtin_amdgcn_sched_barrier(0)
; template <int MODE>
; __device__ __forceinline__ void gemm_tile(const int ph, const int which, const int pm, const int pn) {
;     ...
;   for (int t = 0; t < nt - 2; t += 2) {
;     LDB(B0, 0, 0); SCHED; LDA(At, 0, 0); STAGE(SA(1, 1), RA, brow + HALF, t + 1);
;     WAIT_L(8); BAR; WAIT_L(0); MMA(0, 0, At, B0); BAR; SCHED;
;     LDB(B1, 0, 1); STAGE(SB(0, 0), RB, bcol, t + 2);
;     BAR; WAIT_L(0); MMA(0, 1, At, B1); BAR;
;     LDA(At, 0, 1); STAGE(SA(0, 0), RA, brow, t + 2);
;     BAR; WAIT_L(0); MMA(1, 0, At, B0); BAR; SCHED;
;     STAGE(SB(0, 1), RB, bcolB, t + 2);
;     WAIT_V(6); BAR; MMA(1, 1, At, B1); BAR;
.LBB0_370:
	ds_read_b128 v[156:159], v154
	ds_read_b128 v[168:171], v154 offset:1024
	ds_read_b128 v[172:175], v154 offset:2048
	ds_read_b128 v[176:179], v154 offset:3072
	s_add_i32 s12, s10, s21
	v_readfirstlane_b32 s23, v151
	s_add_i32 s13, s12, 0x80
	s_mov_b32 m0, s23
	ds_read_b128 v[180:183], v141
	ds_read_b128 v[184:187], v141 offset:1024
	ds_read_b128 v[188:191], v140
	ds_read_b128 v[192:195], v140 offset:1024
	ds_read_b128 v[196:199], v139
	ds_read_b128 v[200:203], v139 offset:1024
	ds_read_b128 v[204:207], v138
	ds_read_b128 v[236:239], v138 offset:1024
	buffer_load_dwordx4 v130, s[4:7], s13 offen lds
	s_add_i32 s13, s3, s21
	v_readfirstlane_b32 s27, v149
	s_add_i32 s23, s13, 0x80
	s_mov_b32 m0, s27
	s_nop 0
	buffer_load_dwordx4 v130, s[4:7], s23 offen lds
	s_waitcnt lgkmcnt(8)
	s_barrier
	s_waitcnt lgkmcnt(0)
	s_setprio 1
	s_waitcnt lgkmcnt(7)
	v_mfma_f32_16x16x32_bf16 v[2:5], v[156:159], v[180:183], v[2:5]
	v_mfma_f32_16x16x32_bf16 v[6:9], v[172:175], v[180:183], v[6:9]
	s_waitcnt lgkmcnt(5)
	v_mfma_f32_16x16x32_bf16 v[18:21], v[156:159], v[188:191], v[18:21]
	v_mfma_f32_16x16x32_bf16 v[30:33], v[172:175], v[188:191], v[30:33]
	s_waitcnt lgkmcnt(3)
	v_mfma_f32_16x16x32_bf16 v[42:45], v[156:159], v[196:199], v[42:45]
	v_mfma_f32_16x16x32_bf16 v[54:57], v[172:175], v[196:199], v[54:57]
	s_waitcnt lgkmcnt(1)
	v_mfma_f32_16x16x32_bf16 v[66:69], v[156:159], v[204:207], v[66:69]
	v_mfma_f32_16x16x32_bf16 v[78:81], v[172:175], v[204:207], v[78:81]
	v_mfma_f32_16x16x32_bf16 v[2:5], v[168:171], v[184:187], v[2:5]
	v_mfma_f32_16x16x32_bf16 v[6:9], v[176:179], v[184:187], v[6:9]
	v_mfma_f32_16x16x32_bf16 v[18:21], v[168:171], v[192:195], v[18:21]
	v_mfma_f32_16x16x32_bf16 v[30:33], v[176:179], v[192:195], v[30:33]
	v_mfma_f32_16x16x32_bf16 v[42:45], v[168:171], v[200:203], v[42:45]
	v_mfma_f32_16x16x32_bf16 v[54:57], v[176:179], v[200:203], v[54:57]
	s_waitcnt lgkmcnt(0)
	v_mfma_f32_16x16x32_bf16 v[66:69], v[168:171], v[236:239], v[66:69]
	v_mfma_f32_16x16x32_bf16 v[78:81], v[176:179], v[236:239], v[78:81]
	s_setprio 0
	s_barrier
	s_add_i32 s23, s20, s21
	v_readfirstlane_b32 s28, v132
	s_add_i32 s27, s23, 0x100
	s_mov_b32 m0, s28
	ds_read_b128 v[240:243], v153
	ds_read_b128 v[244:247], v153 offset:1024
	ds_read_b128 v[248:251], v153 offset:2048
	ds_read_b128 v[210:213], v153 offset:3072
	buffer_load_dwordx4 v130, s[68:71], s27 offen lds
	s_add_i32 s27, s19, s21
	v_readfirstlane_b32 s29, v133
	s_add_i32 s28, s27, 0x100
	s_mov_b32 m0, s29
	s_add_i32 s22, s22, 2
	buffer_load_dwordx4 v130, s[68:71], s28 offen lds
	s_barrier
	s_waitcnt lgkmcnt(0)
	s_setprio 1
	s_waitcnt lgkmcnt(3)
	v_mfma_f32_16x16x32_bf16 v[10:13], v[240:243], v[180:183], v[10:13]
	s_waitcnt lgkmcnt(1)
	v_mfma_f32_16x16x32_bf16 v[22:25], v[248:251], v[180:183], v[22:25]
	v_mfma_f32_16x16x32_bf16 v[34:37], v[240:243], v[188:191], v[34:37]
	v_mfma_f32_16x16x32_bf16 v[46:49], v[248:251], v[188:191], v[46:49]
	v_mfma_f32_16x16x32_bf16 v[58:61], v[240:243], v[196:199], v[58:61]
	v_mfma_f32_16x16x32_bf16 v[70:73], v[248:251], v[196:199], v[70:73]
	v_mfma_f32_16x16x32_bf16 v[82:85], v[240:243], v[204:207], v[82:85]
	v_mfma_f32_16x16x32_bf16 v[94:97], v[248:251], v[204:207], v[94:97]
	v_mfma_f32_16x16x32_bf16 v[10:13], v[244:247], v[184:187], v[10:13]
	s_waitcnt lgkmcnt(0)
	v_mfma_f32_16x16x32_bf16 v[22:25], v[210:213], v[184:187], v[22:25]
	v_mfma_f32_16x16x32_bf16 v[34:37], v[244:247], v[192:195], v[34:37]
	v_mfma_f32_16x16x32_bf16 v[46:49], v[210:213], v[192:195], v[46:49]
	v_mfma_f32_16x16x32_bf16 v[58:61], v[244:247], v[200:203], v[58:61]
	v_mfma_f32_16x16x32_bf16 v[70:73], v[210:213], v[200:203], v[70:73]
	v_mfma_f32_16x16x32_bf16 v[82:85], v[244:247], v[236:239], v[82:85]
	v_mfma_f32_16x16x32_bf16 v[94:97], v[210:213], v[236:239], v[94:97]
	s_setprio 0
	s_add_i32 s28, s18, s21
	v_readfirstlane_b32 s38, v131
	s_add_i32 s29, s28, 0x100
	s_mov_b32 m0, s38
	s_barrier
	ds_read_b128 v[180:183], v141 offset:16384
	ds_read_b128 v[184:187], v141 offset:17408
	ds_read_b128 v[188:191], v140 offset:16384
	ds_read_b128 v[192:195], v140 offset:17408
	ds_read_b128 v[196:199], v139 offset:16384
	ds_read_b128 v[200:203], v139 offset:17408
	ds_read_b128 v[204:207], v138 offset:16384
	ds_read_b128 v[236:239], v138 offset:17408
	buffer_load_dwordx4 v130, s[4:7], s29 offen lds
	s_add_i32 s29, s17, s21
	v_readfirstlane_b32 s43, v134
	s_add_i32 s38, s29, 0x100
	s_mov_b32 m0, s43
	s_nop 0
	buffer_load_dwordx4 v130, s[4:7], s38 offen lds
	s_barrier
	s_waitcnt lgkmcnt(0)
	s_setprio 1
	s_waitcnt lgkmcnt(7)
	v_mfma_f32_16x16x32_bf16 v[14:17], v[156:159], v[180:183], v[14:17]
	v_mfma_f32_16x16x32_bf16 v[26:29], v[172:175], v[180:183], v[26:29]
	s_waitcnt lgkmcnt(5)
	v_mfma_f32_16x16x32_bf16 v[38:41], v[156:159], v[188:191], v[38:41]
	v_mfma_f32_16x16x32_bf16 v[50:53], v[172:175], v[188:191], v[50:53]
	s_waitcnt lgkmcnt(3)
	v_mfma_f32_16x16x32_bf16 v[62:65], v[156:159], v[196:199], v[62:65]
	v_mfma_f32_16x16x32_bf16 v[74:77], v[172:175], v[196:199], v[74:77]
	s_waitcnt lgkmcnt(1)
	v_mfma_f32_16x16x32_bf16 v[86:89], v[156:159], v[204:207], v[86:89]
	v_mfma_f32_16x16x32_bf16 v[98:101], v[172:175], v[204:207], v[98:101]
	v_mfma_f32_16x16x32_bf16 v[14:17], v[168:171], v[184:187], v[14:17]
	v_mfma_f32_16x16x32_bf16 v[26:29], v[176:179], v[184:187], v[26:29]
	v_mfma_f32_16x16x32_bf16 v[38:41], v[168:171], v[192:195], v[38:41]
	v_mfma_f32_16x16x32_bf16 v[50:53], v[176:179], v[192:195], v[50:53]
	v_mfma_f32_16x16x32_bf16 v[62:65], v[168:171], v[200:203], v[62:65]
	v_mfma_f32_16x16x32_bf16 v[74:77], v[176:179], v[200:203], v[74:77]
	s_waitcnt lgkmcnt(0)
	v_mfma_f32_16x16x32_bf16 v[86:89], v[168:171], v[236:239], v[86:89]
	v_mfma_f32_16x16x32_bf16 v[98:101], v[176:179], v[236:239], v[98:101]
	s_setprio 0
	s_barrier
; #define WAIT_V(n) asm volatile("s_waitcnt vmcnt(" #n ")" ::: "memory")
; #define WAIT_L(n) asm volatile("s_waitcnt lgkmcnt(" #n ")" ::: "memory")
; #define BAR __builtin_amdgcn_s_barrier()
; #define SCHED __builtin_amdgcn_sched_barrier(0)
; template <int MODE>
; __device__ __forceinline__ void gemm_tile(const int ph, const int which, const int pm, const int pn) {
;     ...
;     STAGE(SB(0, 1), RB, bcolB, t + 2);
;     WAIT_V(6); BAR; MMA(1, 1, At, B1); BAR;
;     LDB(B0, 1, 0); SCHED; LDA(At, 1, 0); STAGE(SA(0, 1), RA, brow + HALF, t + 2);
;     WAIT_L(8); BAR; WAIT_L(0); MMA(0, 0, At, B0); BAR; SCHED;
;     LDB(B1, 1, 1); STAGE(SB(1, 0), RB, bcol, t + 3);
;     BAR; WAIT_L(0); MMA(0, 1, At, B1); BAR;
;     LDA(At, 1, 1); STAGE(SA(1, 0), RA, brow, t + 3);
;     BAR; WAIT_L(0); MMA(1, 0, At, B0); BAR; SCHED;
	s_add_i32 s38, s16, s21
	v_readfirstlane_b32 s50, v135
	s_add_i32 s43, s38, 0x100
	s_mov_b32 m0, s50
	v_readfirstlane_b32 s51, v136
	buffer_load_dwordx4 v130, s[68:71], s43 offen lds
	s_add_i32 s43, s11, s21
	s_add_i32 s50, s43, 0x100
	s_mov_b32 m0, s51
	s_nop 0
	buffer_load_dwordx4 v130, s[68:71], s50 offen lds
	s_waitcnt vmcnt(6)
	s_barrier
	s_setprio 1
	v_mfma_f32_16x16x32_bf16 v[90:93], v[240:243], v[180:183], v[90:93]
	v_mfma_f32_16x16x32_bf16 v[102:105], v[248:251], v[180:183], v[102:105]
	v_mfma_f32_16x16x32_bf16 v[106:109], v[240:243], v[188:191], v[106:109]
	v_mfma_f32_16x16x32_bf16 v[110:113], v[248:251], v[188:191], v[110:113]
	v_mfma_f32_16x16x32_bf16 v[114:117], v[240:243], v[196:199], v[114:117]
	v_mfma_f32_16x16x32_bf16 v[118:121], v[248:251], v[196:199], v[118:121]
	v_mfma_f32_16x16x32_bf16 v[122:125], v[240:243], v[204:207], v[122:125]
	v_mfma_f32_16x16x32_bf16 v[126:129], v[248:251], v[204:207], v[126:129]
	v_mfma_f32_16x16x32_bf16 v[90:93], v[244:247], v[184:187], v[90:93]
	v_mfma_f32_16x16x32_bf16 v[102:105], v[210:213], v[184:187], v[102:105]
	v_mfma_f32_16x16x32_bf16 v[106:109], v[244:247], v[192:195], v[106:109]
	v_mfma_f32_16x16x32_bf16 v[110:113], v[210:213], v[192:195], v[110:113]
	v_mfma_f32_16x16x32_bf16 v[114:117], v[244:247], v[200:203], v[114:117]
	v_mfma_f32_16x16x32_bf16 v[118:121], v[210:213], v[200:203], v[118:121]
	v_mfma_f32_16x16x32_bf16 v[122:125], v[244:247], v[236:239], v[122:125]
	v_mfma_f32_16x16x32_bf16 v[126:129], v[210:213], v[236:239], v[126:129]
	s_setprio 0
	s_barrier
	ds_read_b128 v[156:159], v137
	ds_read_b128 v[168:171], v137 offset:1024
	ds_read_b128 v[172:175], v137 offset:2048
	ds_read_b128 v[176:179], v137 offset:3072
	v_readfirstlane_b32 s50, v143
	s_addk_i32 s12, 0x100
	s_mov_b32 m0, s50
	ds_read_b128 v[180:183], v141 offset:32768
	ds_read_b128 v[184:187], v141 offset:33792
	ds_read_b128 v[188:191], v140 offset:32768
	ds_read_b128 v[192:195], v140 offset:33792
	ds_read_b128 v[196:199], v139 offset:32768
	ds_read_b128 v[200:203], v139 offset:33792
	ds_read_b128 v[204:207], v138 offset:32768
	ds_read_b128 v[210:213], v138 offset:33792
	buffer_load_dwordx4 v130, s[4:7], s12 offen lds
	v_readfirstlane_b32 s12, v144
	s_addk_i32 s13, 0x100
	s_mov_b32 m0, s12
	s_nop 0
	buffer_load_dwordx4 v130, s[4:7], s13 offen lds
	s_waitcnt lgkmcnt(8)
	s_barrier
	s_waitcnt lgkmcnt(0)
	s_setprio 1
	s_waitcnt lgkmcnt(7)
	v_mfma_f32_16x16x32_bf16 v[2:5], v[156:159], v[180:183], v[2:5]
	v_mfma_f32_16x16x32_bf16 v[6:9], v[172:175], v[180:183], v[6:9]
	s_waitcnt lgkmcnt(5)
	v_mfma_f32_16x16x32_bf16 v[18:21], v[156:159], v[188:191], v[18:21]
	v_mfma_f32_16x16x32_bf16 v[30:33], v[172:175], v[188:191], v[30:33]
	s_waitcnt lgkmcnt(3)
	v_mfma_f32_16x16x32_bf16 v[42:45], v[156:159], v[196:199], v[42:45]
	v_mfma_f32_16x16x32_bf16 v[54:57], v[172:175], v[196:199], v[54:57]
	s_waitcnt lgkmcnt(1)
	v_mfma_f32_16x16x32_bf16 v[66:69], v[156:159], v[204:207], v[66:69]
	v_mfma_f32_16x16x32_bf16 v[78:81], v[172:175], v[204:207], v[78:81]
	v_mfma_f32_16x16x32_bf16 v[2:5], v[168:171], v[184:187], v[2:5]
	v_mfma_f32_16x16x32_bf16 v[6:9], v[176:179], v[184:187], v[6:9]
	v_mfma_f32_16x16x32_bf16 v[18:21], v[168:171], v[192:195], v[18:21]
	v_mfma_f32_16x16x32_bf16 v[30:33], v[176:179], v[192:195], v[30:33]
	v_mfma_f32_16x16x32_bf16 v[42:45], v[168:171], v[200:203], v[42:45]
	v_mfma_f32_16x16x32_bf16 v[54:57], v[176:179], v[200:203], v[54:57]
	s_waitcnt lgkmcnt(0)
	v_mfma_f32_16x16x32_bf16 v[66:69], v[168:171], v[210:213], v[66:69]
	v_mfma_f32_16x16x32_bf16 v[78:81], v[176:179], v[210:213], v[78:81]
	s_setprio 0
	s_barrier
	v_readfirstlane_b32 s12, v145
	s_addk_i32 s23, 0x180
	s_mov_b32 m0, s12
	v_readfirstlane_b32 s12, v146
	ds_read_b128 v[236:239], v142
	ds_read_b128 v[240:243], v142 offset:1024
	ds_read_b128 v[244:247], v142 offset:2048
	ds_read_b128 v[248:251], v142 offset:3072
	buffer_load_dwordx4 v130, s[68:71], s23 offen lds
	s_addk_i32 s27, 0x180
	s_mov_b32 m0, s12
	s_nop 0
	buffer_load_dwordx4 v130, s[68:71], s27 offen lds
	s_barrier
	s_waitcnt lgkmcnt(0)
	s_setprio 1
	s_waitcnt lgkmcnt(3)
	v_mfma_f32_16x16x32_bf16 v[10:13], v[236:239], v[180:183], v[10:13]
	s_waitcnt lgkmcnt(1)
	v_mfma_f32_16x16x32_bf16 v[22:25], v[244:247], v[180:183], v[22:25]
	v_mfma_f32_16x16x32_bf16 v[34:37], v[236:239], v[188:191], v[34:37]
	v_mfma_f32_16x16x32_bf16 v[46:49], v[244:247], v[188:191], v[46:49]
	v_mfma_f32_16x16x32_bf16 v[58:61], v[236:239], v[196:199], v[58:61]
	v_mfma_f32_16x16x32_bf16 v[70:73], v[244:247], v[196:199], v[70:73]
	v_mfma_f32_16x16x32_bf16 v[82:85], v[236:239], v[204:207], v[82:85]
	v_mfma_f32_16x16x32_bf16 v[94:97], v[244:247], v[204:207], v[94:97]
	v_mfma_f32_16x16x32_bf16 v[10:13], v[240:243], v[184:187], v[10:13]
	s_waitcnt lgkmcnt(0)
	v_mfma_f32_16x16x32_bf16 v[22:25], v[248:251], v[184:187], v[22:25]
	v_mfma_f32_16x16x32_bf16 v[34:37], v[240:243], v[192:195], v[34:37]
	v_mfma_f32_16x16x32_bf16 v[46:49], v[248:251], v[192:195], v[46:49]
	v_mfma_f32_16x16x32_bf16 v[58:61], v[240:243], v[200:203], v[58:61]
	v_mfma_f32_16x16x32_bf16 v[70:73], v[248:251], v[200:203], v[70:73]
	v_mfma_f32_16x16x32_bf16 v[82:85], v[240:243], v[210:213], v[82:85]
	v_mfma_f32_16x16x32_bf16 v[94:97], v[248:251], v[210:213], v[94:97]
	s_setprio 0
	v_readfirstlane_b32 s12, v147
	s_addk_i32 s28, 0x180
	s_mov_b32 m0, s12
	v_readfirstlane_b32 s12, v148
	s_barrier
	ds_read_b128 v[180:183], v141 offset:49152
	ds_read_b128 v[184:187], v141 offset:50176
	ds_read_b128 v[188:191], v140 offset:49152
	ds_read_b128 v[192:195], v140 offset:50176
	ds_read_b128 v[196:199], v139 offset:49152
	ds_read_b128 v[200:203], v139 offset:50176
	ds_read_b128 v[204:207], v138 offset:49152
	ds_read_b128 v[210:213], v138 offset:50176
	buffer_load_dwordx4 v130, s[4:7], s28 offen lds
	s_addk_i32 s29, 0x180
	s_mov_b32 m0, s12
	s_nop 0
	buffer_load_dwordx4 v130, s[4:7], s29 offen lds
	s_barrier
; #define WAIT_V(n) asm volatile("s_waitcnt vmcnt(" #n ")" ::: "memory")
; #define WAIT_L(n) asm volatile("s_waitcnt lgkmcnt(" #n ")" ::: "memory")
; #define BAR __builtin_amdgcn_s_barrier()
; #define SCHED __builtin_amdgcn_sched_barrier(0)
; template <int MODE>
; __device__ __forceinline__ void gemm_tile(const int ph, const int which, const int pm, const int pn) {
;     ...
;     BAR; WAIT_L(0); MMA(1, 0, At, B0); BAR; SCHED;
;     STAGE(SB(1, 1), RB, bcolB, t + 3);
;     WAIT_V(6); BAR; MMA(1, 1, At, B1); BAR;
;   }
;   {
;     LDB(B0, 0, 0); LDA(At, 0, 0); STAGE(SA(1, 1), RA, brow + HALF, nt - 1);
;     BAR; WAIT_L(0); MMA(0, 0, At, B0); BAR;
;     LDB(B1, 0, 1); BAR; WAIT_L(0); MMA(0, 1, At, B1); BAR;
	s_waitcnt lgkmcnt(0)
	s_setprio 1
	s_waitcnt lgkmcnt(7)
	v_mfma_f32_16x16x32_bf16 v[14:17], v[156:159], v[180:183], v[14:17]
	v_mfma_f32_16x16x32_bf16 v[26:29], v[172:175], v[180:183], v[26:29]
	s_waitcnt lgkmcnt(5)
	v_mfma_f32_16x16x32_bf16 v[38:41], v[156:159], v[188:191], v[38:41]
	v_mfma_f32_16x16x32_bf16 v[50:53], v[172:175], v[188:191], v[50:53]
	s_waitcnt lgkmcnt(3)
	v_mfma_f32_16x16x32_bf16 v[62:65], v[156:159], v[196:199], v[62:65]
	v_mfma_f32_16x16x32_bf16 v[74:77], v[172:175], v[196:199], v[74:77]
	s_waitcnt lgkmcnt(1)
	v_mfma_f32_16x16x32_bf16 v[86:89], v[156:159], v[204:207], v[86:89]
	v_mfma_f32_16x16x32_bf16 v[98:101], v[172:175], v[204:207], v[98:101]
	v_mfma_f32_16x16x32_bf16 v[14:17], v[168:171], v[184:187], v[14:17]
	v_mfma_f32_16x16x32_bf16 v[26:29], v[176:179], v[184:187], v[26:29]
	v_mfma_f32_16x16x32_bf16 v[38:41], v[168:171], v[192:195], v[38:41]
	v_mfma_f32_16x16x32_bf16 v[50:53], v[176:179], v[192:195], v[50:53]
	v_mfma_f32_16x16x32_bf16 v[62:65], v[168:171], v[200:203], v[62:65]
	v_mfma_f32_16x16x32_bf16 v[74:77], v[176:179], v[200:203], v[74:77]
	s_waitcnt lgkmcnt(0)
	v_mfma_f32_16x16x32_bf16 v[86:89], v[168:171], v[210:213], v[86:89]
	v_mfma_f32_16x16x32_bf16 v[98:101], v[176:179], v[210:213], v[98:101]
	s_setprio 0
	s_barrier
	v_readfirstlane_b32 s12, v150
	s_addk_i32 s38, 0x180
	s_mov_b32 m0, s12
	v_readfirstlane_b32 s12, v152
	buffer_load_dwordx4 v130, s[68:71], s38 offen lds
	s_addk_i32 s43, 0x180
	s_mov_b32 m0, s12
	s_nop 0
	buffer_load_dwordx4 v130, s[68:71], s43 offen lds
	s_waitcnt vmcnt(6)
	s_barrier
	s_setprio 1
	v_mfma_f32_16x16x32_bf16 v[90:93], v[236:239], v[180:183], v[90:93]
	v_mfma_f32_16x16x32_bf16 v[102:105], v[244:247], v[180:183], v[102:105]
	v_mfma_f32_16x16x32_bf16 v[106:109], v[236:239], v[188:191], v[106:109]
	v_mfma_f32_16x16x32_bf16 v[110:113], v[244:247], v[188:191], v[110:113]
	v_mfma_f32_16x16x32_bf16 v[114:117], v[236:239], v[196:199], v[114:117]
	v_mfma_f32_16x16x32_bf16 v[118:121], v[244:247], v[196:199], v[118:121]
	v_mfma_f32_16x16x32_bf16 v[122:125], v[236:239], v[204:207], v[122:125]
	v_mfma_f32_16x16x32_bf16 v[126:129], v[244:247], v[204:207], v[126:129]
	v_mfma_f32_16x16x32_bf16 v[90:93], v[240:243], v[184:187], v[90:93]
	v_mfma_f32_16x16x32_bf16 v[102:105], v[248:251], v[184:187], v[102:105]
	v_mfma_f32_16x16x32_bf16 v[106:109], v[240:243], v[192:195], v[106:109]
	v_mfma_f32_16x16x32_bf16 v[110:113], v[248:251], v[192:195], v[110:113]
	v_mfma_f32_16x16x32_bf16 v[114:117], v[240:243], v[200:203], v[114:117]
	v_mfma_f32_16x16x32_bf16 v[118:121], v[248:251], v[200:203], v[118:121]
	v_mfma_f32_16x16x32_bf16 v[122:125], v[240:243], v[210:213], v[122:125]
	v_mfma_f32_16x16x32_bf16 v[126:129], v[248:251], v[210:213], v[126:129]
	s_setprio 0
	s_addk_i32 s21, 0x100
	s_cmp_lt_u32 s22, s2
	s_cbranch_scc1 .Lgemm_head_370
	s_barrier
	s_add_i32 s2, s26, s9
	s_lshl_b32 s2, s2, 1
	v_readfirstlane_b32 s3, v151
	s_addk_i32 s2, 0xff80
	s_mov_b32 s6, s70
	s_mov_b32 s7, s71
	s_mov_b32 m0, s3
	v_readfirstlane_b32 s3, v149
	ds_read_b128 v[132:135], v154
	ds_read_b128 v[144:147], v154 offset:1024
	ds_read_b128 v[156:159], v154 offset:2048
	ds_read_b128 v[168:171], v154 offset:3072
	ds_read_b128 v[172:175], v141
	ds_read_b128 v[176:179], v141 offset:1024
	ds_read_b128 v[180:183], v140
	ds_read_b128 v[184:187], v140 offset:1024
	ds_read_b128 v[188:191], v139
	ds_read_b128 v[192:195], v139 offset:1024
	ds_read_b128 v[196:199], v138
	ds_read_b128 v[200:203], v138 offset:1024
	buffer_load_dwordx4 v130, s[4:7], s2 offen lds
	s_add_i32 s2, s2, s8
	s_mov_b32 m0, s3
	s_nop 0
	buffer_load_dwordx4 v130, s[4:7], s2 offen lds
	s_barrier
	s_waitcnt lgkmcnt(0)
	s_setprio 1
	s_waitcnt lgkmcnt(7)
	v_mfma_f32_16x16x32_bf16 v[2:5], v[132:135], v[172:175], v[2:5]
	v_mfma_f32_16x16x32_bf16 v[6:9], v[156:159], v[172:175], v[6:9]
	s_waitcnt lgkmcnt(5)
	v_mfma_f32_16x16x32_bf16 v[18:21], v[132:135], v[180:183], v[18:21]
	s_waitcnt lgkmcnt(1)
	v_mfma_f32_16x16x32_bf16 v[66:69], v[132:135], v[196:199], v[66:69]
	v_mfma_f32_16x16x32_bf16 v[78:81], v[156:159], v[196:199], v[78:81]
	v_mfma_f32_16x16x32_bf16 v[2:5], v[144:147], v[176:179], v[2:5]
	v_mfma_f32_16x16x32_bf16 v[6:9], v[168:171], v[176:179], v[6:9]
	v_mfma_f32_16x16x32_bf16 v[18:21], v[144:147], v[184:187], v[18:21]
	v_mfma_f32_16x16x32_bf16 v[30:33], v[156:159], v[180:183], v[30:33]
	v_mfma_f32_16x16x32_bf16 v[42:45], v[132:135], v[188:191], v[42:45]
	v_mfma_f32_16x16x32_bf16 v[54:57], v[156:159], v[188:191], v[54:57]
	s_waitcnt lgkmcnt(0)
	v_mfma_f32_16x16x32_bf16 v[66:69], v[144:147], v[200:203], v[66:69]
	v_mfma_f32_16x16x32_bf16 v[78:81], v[168:171], v[200:203], v[78:81]
	v_mfma_f32_16x16x32_bf16 v[30:33], v[168:171], v[184:187], v[30:33]
	v_mfma_f32_16x16x32_bf16 v[42:45], v[144:147], v[192:195], v[42:45]
	v_mfma_f32_16x16x32_bf16 v[54:57], v[168:171], v[192:195], v[54:57]
	s_setprio 0
	s_barrier
	ds_read_b128 v[148:151], v153
	ds_read_b128 v[204:207], v153 offset:1024
	ds_read_b128 v[210:213], v153 offset:2048
	ds_read_b128 v[152:155], v153 offset:3072
	s_barrier
; #define WAIT_V(n) asm volatile("s_waitcnt vmcnt(" #n ")" ::: "memory")
; #define WAIT_L(n) asm volatile("s_waitcnt lgkmcnt(" #n ")" ::: "memory")
; #define BAR __builtin_amdgcn_s_barrier()
; template <int MODE>
; __device__ __forceinline__ void gemm_tile(const int ph, const int which, const int pm, const int pn) {
;     ...
;     LDB(B1, 0, 1); BAR; WAIT_L(0); MMA(0, 1, At, B1); BAR;
;     LDA(At, 0, 1); WAIT_V(4); BAR; WAIT_L(0); MMA(1, 0, At, B0); MMA(1, 1, At, B1); BAR;
;   }
;   {
;     LDB(B0, 1, 0); LDA(At, 1, 0); WAIT_V(2); BAR; WAIT_L(0); MMA(0, 0, At, B0); BAR;
	s_waitcnt lgkmcnt(0)
	s_setprio 1
	s_waitcnt lgkmcnt(3)
	v_mfma_f32_16x16x32_bf16 v[10:13], v[148:151], v[172:175], v[10:13]
	s_waitcnt lgkmcnt(1)
	v_mfma_f32_16x16x32_bf16 v[22:25], v[210:213], v[172:175], v[22:25]
	v_mfma_f32_16x16x32_bf16 v[58:61], v[148:151], v[188:191], v[58:61]
	v_mfma_f32_16x16x32_bf16 v[70:73], v[210:213], v[188:191], v[70:73]
	v_mfma_f32_16x16x32_bf16 v[82:85], v[148:151], v[196:199], v[82:85]
	v_mfma_f32_16x16x32_bf16 v[10:13], v[204:207], v[176:179], v[10:13]
	s_waitcnt lgkmcnt(0)
	v_mfma_f32_16x16x32_bf16 v[22:25], v[152:155], v[176:179], v[22:25]
	v_mfma_f32_16x16x32_bf16 v[34:37], v[148:151], v[180:183], v[34:37]
	v_mfma_f32_16x16x32_bf16 v[46:49], v[210:213], v[180:183], v[46:49]
	v_mfma_f32_16x16x32_bf16 v[58:61], v[204:207], v[192:195], v[58:61]
	v_mfma_f32_16x16x32_bf16 v[70:73], v[152:155], v[192:195], v[70:73]
	v_mfma_f32_16x16x32_bf16 v[172:175], v[204:207], v[200:203], v[82:85]
	v_mfma_f32_16x16x32_bf16 v[82:85], v[210:213], v[196:199], v[94:97]
	v_mfma_f32_16x16x32_bf16 v[34:37], v[204:207], v[184:187], v[34:37]
	v_mfma_f32_16x16x32_bf16 v[46:49], v[152:155], v[184:187], v[46:49]
	v_mfma_f32_16x16x32_bf16 v[176:179], v[152:155], v[200:203], v[82:85]
	s_setprio 0
	s_barrier
	s_nop 2
	ds_read_b128 v[82:85], v141 offset:16384
	ds_read_b128 v[94:97], v141 offset:17408
	ds_read_b128 v[180:183], v140 offset:16384
	ds_read_b128 v[184:187], v140 offset:17408
	ds_read_b128 v[188:191], v139 offset:16384
	ds_read_b128 v[192:195], v139 offset:17408
	ds_read_b128 v[196:199], v138 offset:16384
	ds_read_b128 v[200:203], v138 offset:17408
	s_waitcnt vmcnt(4)
	s_barrier
	s_waitcnt lgkmcnt(0)
	s_setprio 1
	s_waitcnt lgkmcnt(3)
	v_mfma_f32_16x16x32_bf16 v[74:77], v[156:159], v[188:191], v[74:77]
	s_waitcnt lgkmcnt(2)
	v_mfma_f32_16x16x32_bf16 v[236:239], v[168:171], v[192:195], v[74:77]
	s_waitcnt lgkmcnt(1)
	v_mfma_f32_16x16x32_bf16 v[74:77], v[132:135], v[196:199], v[86:89]
	v_mfma_f32_16x16x32_bf16 v[14:17], v[132:135], v[82:85], v[14:17]
	v_mfma_f32_16x16x32_bf16 v[62:65], v[132:135], v[188:191], v[62:65]
	s_waitcnt lgkmcnt(0)
	v_mfma_f32_16x16x32_bf16 v[240:243], v[144:147], v[200:203], v[74:77]
	v_mfma_f32_16x16x32_bf16 v[74:77], v[156:159], v[196:199], v[98:101]
	v_mfma_f32_16x16x32_bf16 v[14:17], v[144:147], v[94:97], v[14:17]
	v_mfma_f32_16x16x32_bf16 v[26:29], v[156:159], v[82:85], v[26:29]
	v_mfma_f32_16x16x32_bf16 v[38:41], v[132:135], v[180:183], v[38:41]
	v_mfma_f32_16x16x32_bf16 v[50:53], v[156:159], v[180:183], v[50:53]
	v_mfma_f32_16x16x32_bf16 v[62:65], v[144:147], v[192:195], v[62:65]
	v_mfma_f32_16x16x32_bf16 v[98:101], v[168:171], v[200:203], v[74:77]
	v_mfma_f32_16x16x32_bf16 v[26:29], v[168:171], v[94:97], v[26:29]
	v_mfma_f32_16x16x32_bf16 v[38:41], v[144:147], v[184:187], v[38:41]
	v_mfma_f32_16x16x32_bf16 v[50:53], v[168:171], v[184:187], v[50:53]
	s_setprio 0
	s_setprio 1
	v_mfma_f32_16x16x32_bf16 v[74:77], v[148:151], v[82:85], v[90:93]
	v_mfma_f32_16x16x32_bf16 v[168:171], v[204:207], v[94:97], v[74:77]
	v_mfma_f32_16x16x32_bf16 v[74:77], v[210:213], v[82:85], v[102:105]
	v_mfma_f32_16x16x32_bf16 v[244:247], v[152:155], v[94:97], v[74:77]
	v_mfma_f32_16x16x32_bf16 v[74:77], v[148:151], v[180:183], v[106:109]
	v_mfma_f32_16x16x32_bf16 v[248:251], v[204:207], v[184:187], v[74:77]
	v_mfma_f32_16x16x32_bf16 v[74:77], v[210:213], v[180:183], v[110:113]
	v_mfma_f32_16x16x32_bf16 v[180:183], v[152:155], v[184:187], v[74:77]
	v_mfma_f32_16x16x32_bf16 v[74:77], v[148:151], v[188:191], v[114:117]
	v_mfma_f32_16x16x32_bf16 v[184:187], v[204:207], v[192:195], v[74:77]
	v_mfma_f32_16x16x32_bf16 v[74:77], v[210:213], v[188:191], v[118:121]
	v_mfma_f32_16x16x32_bf16 v[188:191], v[152:155], v[192:195], v[74:77]
	v_mfma_f32_16x16x32_bf16 v[74:77], v[148:151], v[196:199], v[122:125]
	v_mfma_f32_16x16x32_bf16 v[192:195], v[204:207], v[200:203], v[74:77]
	v_mfma_f32_16x16x32_bf16 v[74:77], v[210:213], v[196:199], v[126:129]
	v_mfma_f32_16x16x32_bf16 v[196:199], v[152:155], v[200:203], v[74:77]
	s_setprio 0
	s_barrier
	ds_read_b128 v[102:105], v137
	ds_read_b128 v[200:203], v137 offset:1024
	ds_read_b128 v[204:207], v137 offset:2048
	ds_read_b128 v[210:213], v137 offset:3072
	s_nop 0
	ds_read_b128 v[74:77], v141 offset:32768
	ds_read_b128 v[82:85], v141 offset:33792
	ds_read_b128 v[144:147], v140 offset:32768
	ds_read_b128 v[148:151], v140 offset:33792
	ds_read_b128 v[152:155], v139 offset:32768
	ds_read_b128 v[156:159], v139 offset:33792
	ds_read_b128 v[218:221], v138 offset:32768
	ds_read_b128 v[230:233], v138 offset:33792
	s_waitcnt vmcnt(2)
	s_barrier
; #define WAIT_V(n) asm volatile("s_waitcnt vmcnt(" #n ")" ::: "memory")
; #define WAIT_L(n) asm volatile("s_waitcnt lgkmcnt(" #n ")" ::: "memory")
; #define BAR __builtin_amdgcn_s_barrier()
; template <int MODE>
; __device__ __forceinline__ void gemm_tile(const int ph, const int which, const int pm, const int pn) {
;     ...
;     LDB(B0, 1, 0); LDA(At, 1, 0); WAIT_V(2); BAR; WAIT_L(0); MMA(0, 0, At, B0); BAR;
;     LDB(B1, 1, 1); WAIT_V(0); BAR; WAIT_L(0); MMA(0, 1, At, B1); BAR;
;     LDA(At, 1, 1); BAR; WAIT_L(0); MMA(1, 0, At, B0); MMA(1, 1, At, B1); BAR;
;   }
;   if (wr == 0) BAR;
	s_waitcnt lgkmcnt(0)
	s_setprio 1
	s_waitcnt lgkmcnt(7)
	v_mfma_f32_16x16x32_bf16 v[2:5], v[102:105], v[74:77], v[2:5]
	s_waitcnt lgkmcnt(6)
	v_mfma_f32_16x16x32_bf16 v[106:109], v[200:203], v[82:85], v[2:5]
	v_mfma_f32_16x16x32_bf16 v[2:5], v[204:207], v[74:77], v[6:9]
	v_mfma_f32_16x16x32_bf16 v[110:113], v[210:213], v[82:85], v[2:5]
	s_waitcnt lgkmcnt(5)
	v_mfma_f32_16x16x32_bf16 v[2:5], v[102:105], v[144:147], v[18:21]
	s_waitcnt lgkmcnt(4)
	v_mfma_f32_16x16x32_bf16 v[114:117], v[200:203], v[148:151], v[2:5]
	v_mfma_f32_16x16x32_bf16 v[2:5], v[204:207], v[144:147], v[30:33]
	v_mfma_f32_16x16x32_bf16 v[118:121], v[210:213], v[148:151], v[2:5]
	s_waitcnt lgkmcnt(3)
	v_mfma_f32_16x16x32_bf16 v[2:5], v[102:105], v[152:155], v[42:45]
	s_waitcnt lgkmcnt(2)
	v_mfma_f32_16x16x32_bf16 v[122:125], v[200:203], v[156:159], v[2:5]
	v_mfma_f32_16x16x32_bf16 v[2:5], v[204:207], v[152:155], v[54:57]
	v_mfma_f32_16x16x32_bf16 v[126:129], v[210:213], v[156:159], v[2:5]
	s_waitcnt lgkmcnt(1)
	v_mfma_f32_16x16x32_bf16 v[2:5], v[102:105], v[218:221], v[66:69]
	s_waitcnt lgkmcnt(0)
	v_mfma_f32_16x16x32_bf16 v[130:133], v[200:203], v[230:233], v[2:5]
	v_mfma_f32_16x16x32_bf16 v[2:5], v[204:207], v[218:221], v[78:81]
	v_mfma_f32_16x16x32_bf16 v[134:137], v[210:213], v[230:233], v[2:5]
	s_setprio 0
	s_barrier
	s_nop 4
	ds_read_b128 v[2:5], v142
	ds_read_b128 v[6:9], v142 offset:1024
	ds_read_b128 v[30:33], v142 offset:2048
	ds_read_b128 v[42:45], v142 offset:3072
	s_waitcnt vmcnt(0)
	s_barrier
	s_waitcnt lgkmcnt(0)
	s_setprio 1
	s_waitcnt lgkmcnt(3)
	v_mfma_f32_16x16x32_bf16 v[10:13], v[2:5], v[74:77], v[10:13]
	s_waitcnt lgkmcnt(2)
	v_mfma_f32_16x16x32_bf16 v[94:97], v[6:9], v[82:85], v[10:13]
	s_waitcnt lgkmcnt(1)
	v_mfma_f32_16x16x32_bf16 v[10:13], v[30:33], v[74:77], v[22:25]
	s_waitcnt lgkmcnt(0)
	v_mfma_f32_16x16x32_bf16 v[90:93], v[42:45], v[82:85], v[10:13]
	v_mfma_f32_16x16x32_bf16 v[10:13], v[2:5], v[144:147], v[34:37]
	v_mfma_f32_16x16x32_bf16 v[86:89], v[6:9], v[148:151], v[10:13]
	v_mfma_f32_16x16x32_bf16 v[10:13], v[30:33], v[144:147], v[46:49]
	v_mfma_f32_16x16x32_bf16 v[82:85], v[42:45], v[148:151], v[10:13]
	v_mfma_f32_16x16x32_bf16 v[10:13], v[2:5], v[152:155], v[58:61]
	v_mfma_f32_16x16x32_bf16 v[78:81], v[6:9], v[156:159], v[10:13]
	v_mfma_f32_16x16x32_bf16 v[10:13], v[30:33], v[152:155], v[70:73]
	v_mfma_f32_16x16x32_bf16 v[74:77], v[42:45], v[156:159], v[10:13]
	v_mfma_f32_16x16x32_bf16 v[10:13], v[2:5], v[218:221], v[172:175]
	v_mfma_f32_16x16x32_bf16 v[70:73], v[6:9], v[230:233], v[10:13]
	v_mfma_f32_16x16x32_bf16 v[10:13], v[30:33], v[218:221], v[176:179]
	v_mfma_f32_16x16x32_bf16 v[66:69], v[42:45], v[230:233], v[10:13]
	s_setprio 0
	s_barrier
	s_nop 4
	ds_read_b128 v[10:13], v141 offset:49152
	ds_read_b128 v[18:21], v141 offset:50176
	ds_read_b128 v[34:37], v140 offset:49152
	ds_read_b128 v[46:49], v140 offset:50176
	ds_read_b128 v[54:57], v139 offset:49152
	ds_read_b128 v[172:175], v139 offset:50176
	ds_read_b128 v[176:179], v138 offset:49152
	ds_read_b128 v[218:221], v138 offset:50176
	s_barrier
	s_waitcnt lgkmcnt(0)
	s_setprio 1
	s_waitcnt lgkmcnt(7)
	v_mfma_f32_16x16x32_bf16 v[14:17], v[102:105], v[10:13], v[14:17]
	s_waitcnt lgkmcnt(6)
	v_mfma_f32_16x16x32_bf16 v[158:161], v[200:203], v[18:21], v[14:17]
	v_mfma_f32_16x16x32_bf16 v[14:17], v[204:207], v[10:13], v[26:29]
	v_mfma_f32_16x16x32_bf16 v[154:157], v[210:213], v[18:21], v[14:17]
	s_waitcnt lgkmcnt(5)
	v_mfma_f32_16x16x32_bf16 v[14:17], v[102:105], v[34:37], v[38:41]
	s_waitcnt lgkmcnt(4)
	v_mfma_f32_16x16x32_bf16 v[150:153], v[200:203], v[46:49], v[14:17]
	v_mfma_f32_16x16x32_bf16 v[14:17], v[204:207], v[34:37], v[50:53]
	v_mfma_f32_16x16x32_bf16 v[146:149], v[210:213], v[46:49], v[14:17]
	s_waitcnt lgkmcnt(3)
	v_mfma_f32_16x16x32_bf16 v[14:17], v[102:105], v[54:57], v[62:65]
	s_waitcnt lgkmcnt(2)
	v_mfma_f32_16x16x32_bf16 v[142:145], v[200:203], v[172:175], v[14:17]
	v_mfma_f32_16x16x32_bf16 v[14:17], v[204:207], v[54:57], v[236:239]
	v_mfma_f32_16x16x32_bf16 v[138:141], v[210:213], v[172:175], v[14:17]
	s_waitcnt lgkmcnt(1)
	v_mfma_f32_16x16x32_bf16 v[14:17], v[102:105], v[176:179], v[240:243]
	s_waitcnt lgkmcnt(0)
	v_mfma_f32_16x16x32_bf16 v[102:105], v[200:203], v[218:221], v[14:17]
	v_mfma_f32_16x16x32_bf16 v[14:17], v[204:207], v[176:179], v[98:101]
	v_mfma_f32_16x16x32_bf16 v[98:101], v[210:213], v[218:221], v[14:17]
	s_setprio 0
	s_setprio 1
	v_mfma_f32_16x16x32_bf16 v[14:17], v[2:5], v[10:13], v[168:171]
	v_mfma_f32_16x16x32_bf16 v[10:13], v[30:33], v[10:13], v[244:247]
	v_mfma_f32_16x16x32_bf16 v[58:61], v[42:45], v[18:21], v[10:13]
	v_mfma_f32_16x16x32_bf16 v[10:13], v[2:5], v[34:37], v[248:251]
	v_mfma_f32_16x16x32_bf16 v[22:25], v[6:9], v[46:49], v[10:13]
	v_mfma_f32_16x16x32_bf16 v[10:13], v[30:33], v[34:37], v[180:183]
	v_mfma_f32_16x16x32_bf16 v[62:65], v[6:9], v[18:21], v[14:17]
	v_mfma_f32_16x16x32_bf16 v[18:21], v[42:45], v[46:49], v[10:13]
	v_mfma_f32_16x16x32_bf16 v[10:13], v[2:5], v[54:57], v[184:187]
	v_mfma_f32_16x16x32_bf16 v[2:5], v[2:5], v[176:179], v[192:195]
	v_mfma_f32_16x16x32_bf16 v[14:17], v[6:9], v[172:175], v[10:13]
	v_mfma_f32_16x16x32_bf16 v[10:13], v[30:33], v[54:57], v[188:191]
	v_mfma_f32_16x16x32_bf16 v[6:9], v[6:9], v[218:221], v[2:5]
	v_mfma_f32_16x16x32_bf16 v[2:5], v[30:33], v[176:179], v[196:199]
	v_mfma_f32_16x16x32_bf16 v[10:13], v[42:45], v[172:175], v[10:13]
	v_mfma_f32_16x16x32_bf16 v[2:5], v[42:45], v[218:221], v[2:5]
	s_setprio 0
	s_movk_i32 s2, 0x100
	v_cmp_gt_u32_e32 vcc, s2, v164
	s_barrier
	s_and_saveexec_b64 s[2:3], vcc
	s_cbranch_execz .LBB0_373
	s_barrier

; #define WAIT_V(n) asm volatile("s_waitcnt vmcnt(" #n ")" ::: "memory")
; #define BAR __builtin_amdgcn_s_barrier()
; template <int MODE>
; __device__ __forceinline__ void gemm_tile(const int ph, const int which, const int pm, const int pn) {
;     ...
;   f32x4 acc[2][2][4][2] = {};
;   bf16x8 At[4][2], B0[2][2], B1[2][2];
;   const int nt = K / BK;
;   const int brow = browA;
;   STAGE(SB(0, 0), RB, bcol, 0);
;   STAGE(SA(0, 0), RA, brow, 0);
;   STAGE(SB(0, 1), RB, bcolB, 0);
;   STAGE(SA(0, 1), RA, brow + HALF, 0);
;   if (wr == 1) BAR;
;   WAIT_V(4);
;   BAR;
;   STAGE(SB(1, 0), RB, bcol, 1);
;   STAGE(SA(1, 0), RA, brow, 1);
;   STAGE(SB(1, 1), RB, bcolB, 1);
;   WAIT_V(6);
;   BAR;
.LBB0_539:
	s_or_b64 exec, exec, s[2:3]
	v_add_u32_e32 v147, 0x18000, v137
	v_add_u32_e32 v148, 0x1a000, v137
	v_readfirstlane_b32 s6, v147
	s_or_b32 s3, s19, 0x80
	s_mov_b32 m0, s6
	v_readfirstlane_b32 s6, v148
	s_waitcnt vmcnt(4)
	s_barrier
	buffer_load_dwordx4 v136, s[68:71], s3 offen lds
	s_add_i32 s3, s3, s8
	s_mov_b32 m0, s6
	v_add_u32_e32 v149, 0x8000, v137
	buffer_load_dwordx4 v136, s[68:71], s3 offen lds
	s_or_b32 s3, s11, 0x80
	v_readfirstlane_b32 s11, v149
	v_add_u32_e32 v150, 0xa000, v137
	s_mov_b32 s6, s70
	s_mov_b32 s7, s71
	s_mov_b32 m0, s11
	v_readfirstlane_b32 s11, v150
	buffer_load_dwordx4 v136, s[4:7], s3 offen lds
	s_add_i32 s3, s3, s8
	s_mov_b32 m0, s11
	v_add_u32_e32 v152, 0x1c000, v137
	buffer_load_dwordx4 v136, s[4:7], s3 offen lds
	s_or_b32 s3, s10, 0x80
	v_readfirstlane_b32 s10, v152
	v_add_u32_e32 v154, 0x1e000, v137
	s_mov_b32 m0, s10
	v_readfirstlane_b32 s10, v154
	buffer_load_dwordx4 v136, s[68:71], s3 offen lds
	s_add_i32 s3, s3, s8
	s_mov_b32 m0, s10
	v_and_b32_e32 v3, 15, v0
	buffer_load_dwordx4 v136, s[68:71], s3 offen lds
	v_and_b32_e32 v5, 48, v0
	v_lshlrev_b32_e32 v6, 6, v3
	v_lshlrev_b32_e32 v8, 2, v0
	v_or_b32_e32 v7, v6, v5
	v_and_b32_e32 v8, 32, v8
	s_mov_b32 s3, 0x10000
	v_bitop3_b32 v9, v7, s3, v8 bitop3:0xde
	s_mov_b32 s3, 0x14000
	v_bitop3_b32 v10, v7, s3, v8 bitop3:0xde
	s_mov_b32 s3, 0x18000
	v_lshl_or_b32 v131, v2, 6, v3
	v_lshlrev_b32_e32 v3, 13, v2
	v_lshlrev_b32_e32 v2, 6, v0
	v_bfe_u32 v130, v0, 6, 2
	v_bitop3_b32 v11, v7, s3, v8 bitop3:0xde
	s_mov_b32 s3, 0x1c000
	v_and_b32_e32 v2, 0x3c0, v2
	s_lshl_b32 s19, s20, 1
	s_lshl_b32 s11, s17, 1
	s_lshl_b32 s21, s22, 1
	s_lshr_b32 s2, s24, 6
	v_lshlrev_b32_e32 v4, 12, v130
	v_bitop3_b32 v6, v6, v8, v5 bitop3:0x36
	v_bitop3_b32 v7, v7, s3, v8 bitop3:0xde
	v_bitop3_b32 v5, v2, v8, v5 bitop3:0x36
	v_or_b32_e32 v8, 0x800, v3
	v_or_b32_e32 v12, 0x1000, v3
	v_or_b32_e32 v13, 0x1800, v3
	s_add_i32 s3, s19, 0x180
	s_lshl_b32 s23, s24, 1
	s_add_i32 s10, s20, 0x80
	s_addk_i32 s11, 0x80
	s_addk_i32 s19, 0x80
	s_addk_i32 s21, 0x80
	v_mov_b32_e32 v2, 0
	s_add_i32 s2, s2, -2
	v_add_u32_e32 v153, 0xc000, v137
	v_add_u32_e32 v151, 0xe000, v137
	s_mul_i32 s3, s24, s3
	s_mul_i32 s10, s23, s10
	s_mul_i32 s11, s24, s11
	s_mul_i32 s17, s23, s17
	s_mul_i32 s19, s24, s19
	s_mul_i32 s20, s23, s20
	s_mul_i32 s21, s24, s21
	s_mul_i32 s22, s23, s22
	s_mov_b32 s23, 0
	v_add_u32_e32 v156, v9, v4
	v_add_u32_e32 v135, v6, v3
	v_add_u32_e32 v134, v5, v8
	v_add_u32_e32 v133, v5, v12
	v_add_u32_e32 v132, v5, v13
	v_add_u32_e32 v155, v10, v4
	v_add_u32_e32 v144, v11, v4
	v_add_u32_e32 v138, v7, v4
	s_mov_b32 s25, 0
	v_mov_b32_e32 v3, v2
	v_mov_b32_e32 v4, v2
	v_mov_b32_e32 v5, v2
	v_mov_b32_e32 v6, v2
	v_mov_b32_e32 v7, v2
	v_mov_b32_e32 v8, v2
	v_mov_b32_e32 v9, v2
	v_mov_b32_e32 v10, v2
	v_mov_b32_e32 v11, v2
	v_mov_b32_e32 v12, v2
	v_mov_b32_e32 v13, v2
	v_mov_b32_e32 v14, v2
	v_mov_b32_e32 v15, v2
	v_mov_b32_e32 v16, v2
	v_mov_b32_e32 v17, v2
	v_mov_b32_e32 v18, v2
	v_mov_b32_e32 v19, v2
	v_mov_b32_e32 v20, v2
	v_mov_b32_e32 v21, v2
	v_mov_b32_e32 v22, v2
	v_mov_b32_e32 v23, v2
	v_mov_b32_e32 v24, v2
	v_mov_b32_e32 v25, v2
	s_waitcnt vmcnt(18)
	v_mov_b32_e32 v26, v2
	v_mov_b32_e32 v27, v2
	v_mov_b32_e32 v28, v2
	v_mov_b32_e32 v29, v2
	s_waitcnt vmcnt(16)
	v_mov_b32_e32 v30, v2
	v_mov_b32_e32 v31, v2
	v_mov_b32_e32 v32, v2
	v_mov_b32_e32 v33, v2
	s_waitcnt vmcnt(14)
	v_mov_b32_e32 v34, v2
	v_mov_b32_e32 v35, v2
	v_mov_b32_e32 v36, v2
	v_mov_b32_e32 v37, v2
	v_mov_b32_e32 v38, v2
	v_mov_b32_e32 v39, v2
	v_mov_b32_e32 v40, v2
	v_mov_b32_e32 v41, v2
	v_mov_b32_e32 v42, v2
	v_mov_b32_e32 v43, v2
	v_mov_b32_e32 v44, v2
	v_mov_b32_e32 v45, v2
	v_mov_b32_e32 v46, v2
	v_mov_b32_e32 v47, v2
	v_mov_b32_e32 v48, v2
	v_mov_b32_e32 v49, v2
	v_mov_b32_e32 v50, v2
	v_mov_b32_e32 v51, v2
	v_mov_b32_e32 v52, v2
	v_mov_b32_e32 v53, v2
	v_mov_b32_e32 v54, v2
	v_mov_b32_e32 v55, v2
	v_mov_b32_e32 v56, v2
	v_mov_b32_e32 v57, v2
	v_mov_b32_e32 v58, v2
	v_mov_b32_e32 v59, v2
	v_mov_b32_e32 v60, v2
	v_mov_b32_e32 v61, v2
	v_mov_b32_e32 v62, v2
	v_mov_b32_e32 v63, v2
	v_mov_b32_e32 v64, v2
	v_mov_b32_e32 v65, v2
	v_mov_b32_e32 v66, v2
	v_mov_b32_e32 v67, v2
	v_mov_b32_e32 v68, v2
	v_mov_b32_e32 v69, v2
	v_mov_b32_e32 v70, v2
	v_mov_b32_e32 v71, v2
	v_mov_b32_e32 v72, v2
	v_mov_b32_e32 v73, v2
	v_mov_b32_e32 v74, v2
	v_mov_b32_e32 v75, v2
	v_mov_b32_e32 v76, v2
	v_mov_b32_e32 v77, v2
	v_mov_b32_e32 v78, v2
	v_mov_b32_e32 v79, v2
	v_mov_b32_e32 v80, v2
	v_mov_b32_e32 v81, v2
	v_mov_b32_e32 v82, v2
	v_mov_b32_e32 v83, v2
	v_mov_b32_e32 v84, v2
	v_mov_b32_e32 v85, v2
	v_mov_b32_e32 v86, v2
	v_mov_b32_e32 v87, v2
	v_mov_b32_e32 v88, v2
	v_mov_b32_e32 v89, v2
	v_mov_b32_e32 v90, v2
	v_mov_b32_e32 v91, v2
	v_mov_b32_e32 v92, v2
	v_mov_b32_e32 v93, v2
	v_mov_b32_e32 v94, v2
	v_mov_b32_e32 v95, v2
	v_mov_b32_e32 v96, v2
	v_mov_b32_e32 v97, v2
	v_mov_b32_e32 v98, v2
	v_mov_b32_e32 v99, v2
	v_mov_b32_e32 v100, v2
	v_mov_b32_e32 v101, v2
	v_mov_b32_e32 v102, v2
	v_mov_b32_e32 v103, v2
	v_mov_b32_e32 v104, v2
	v_mov_b32_e32 v105, v2
	v_mov_b32_e32 v106, v2
	v_mov_b32_e32 v107, v2
	v_mov_b32_e32 v108, v2
	v_mov_b32_e32 v109, v2
	v_mov_b32_e32 v110, v2
	v_mov_b32_e32 v111, v2
	v_mov_b32_e32 v112, v2
	v_mov_b32_e32 v113, v2
	v_mov_b32_e32 v114, v2
	v_mov_b32_e32 v115, v2
	v_mov_b32_e32 v116, v2
	v_mov_b32_e32 v117, v2
	v_mov_b32_e32 v118, v2
	v_mov_b32_e32 v119, v2
	v_mov_b32_e32 v120, v2
	v_mov_b32_e32 v121, v2
	v_mov_b32_e32 v122, v2
	v_mov_b32_e32 v123, v2
	v_mov_b32_e32 v124, v2
	v_mov_b32_e32 v125, v2
	v_mov_b32_e32 v126, v2
	v_mov_b32_e32 v127, v2
	v_mov_b32_e32 v128, v2
	v_mov_b32_e32 v129, v2
	s_waitcnt vmcnt(6)

; #define WAIT_V(n) asm volatile("s_waitcnt vmcnt(" #n ")" ::: "memory")
; #define WAIT_L(n) asm volatile("s_waitcnt lgkmcnt(" #n ")" ::: "memory")
; #define BAR __builtin_amdgcn_s_barrier()
; #define SCHED __builtin_amdgcn_sched_barrier(0)
; template <int MODE>
; __device__ __forceinline__ void gemm_tile(const int ph, const int which, const int pm, const int pn) {
;     ...
;   for (int t = 0; t < nt - 2; t += 2) {
;     LDB(B0, 0, 0); SCHED; LDA(At, 0, 0); STAGE(SA(1, 1), RA, brow + HALF, t + 1);
;     WAIT_L(8); BAR; WAIT_L(0); MMA(0, 0, At, B0); BAR; SCHED;
;     LDB(B1, 0, 1); STAGE(SB(0, 0), RB, bcol, t + 2);
;     BAR; WAIT_L(0); MMA(0, 1, At, B1); BAR;
;     LDA(At, 0, 1); STAGE(SA(0, 0), RA, brow, t + 2);
;     BAR; WAIT_L(0); MMA(1, 0, At, B0); BAR; SCHED;
;     STAGE(SB(0, 1), RB, bcolB, t + 2);
;     WAIT_V(6); BAR; MMA(1, 1, At, B1); BAR;
.LBB0_540:
	ds_read_b128 v[158:161], v156
	ds_read_b128 v[162:165], v156 offset:1024
	ds_read_b128 v[166:169], v156 offset:2048
	ds_read_b128 v[170:173], v156 offset:3072
	s_add_i32 s26, s10, s23
	v_readfirstlane_b32 s28, v153
	s_add_i32 s27, s26, 0x80
	s_mov_b32 m0, s28
	ds_read_b128 v[174:177], v135
	ds_read_b128 v[178:181], v135 offset:1024
	ds_read_b128 v[182:185], v134
	ds_read_b128 v[186:189], v134 offset:1024
	ds_read_b128 v[190:193], v133
	ds_read_b128 v[194:197], v133 offset:1024
	ds_read_b128 v[198:201], v132
	ds_read_b128 v[202:205], v132 offset:1024
	buffer_load_dwordx4 v136, s[4:7], s27 offen lds
	s_add_i32 s27, s3, s23
	v_readfirstlane_b32 s51, v151
	s_add_i32 s28, s27, 0x80
	s_mov_b32 m0, s51
	s_nop 0
	buffer_load_dwordx4 v136, s[4:7], s28 offen lds
	s_waitcnt lgkmcnt(8)
	s_barrier
	s_waitcnt lgkmcnt(0)
	s_setprio 1
	s_waitcnt lgkmcnt(7)
	v_mfma_f32_16x16x32_bf16 v[126:129], v[158:161], v[174:177], v[126:129]
	v_mfma_f32_16x16x32_bf16 v[122:125], v[166:169], v[174:177], v[122:125]
	s_waitcnt lgkmcnt(5)
	v_mfma_f32_16x16x32_bf16 v[118:121], v[158:161], v[182:185], v[118:121]
	v_mfma_f32_16x16x32_bf16 v[114:117], v[166:169], v[182:185], v[114:117]
	s_waitcnt lgkmcnt(3)
	v_mfma_f32_16x16x32_bf16 v[110:113], v[158:161], v[190:193], v[110:113]
	v_mfma_f32_16x16x32_bf16 v[106:109], v[166:169], v[190:193], v[106:109]
	s_waitcnt lgkmcnt(1)
	v_mfma_f32_16x16x32_bf16 v[102:105], v[158:161], v[198:201], v[102:105]
	v_mfma_f32_16x16x32_bf16 v[98:101], v[166:169], v[198:201], v[98:101]
	v_mfma_f32_16x16x32_bf16 v[126:129], v[162:165], v[178:181], v[126:129]
	v_mfma_f32_16x16x32_bf16 v[122:125], v[170:173], v[178:181], v[122:125]
	v_mfma_f32_16x16x32_bf16 v[118:121], v[162:165], v[186:189], v[118:121]
	v_mfma_f32_16x16x32_bf16 v[114:117], v[170:173], v[186:189], v[114:117]
	v_mfma_f32_16x16x32_bf16 v[110:113], v[162:165], v[194:197], v[110:113]
	v_mfma_f32_16x16x32_bf16 v[106:109], v[170:173], v[194:197], v[106:109]
	s_waitcnt lgkmcnt(0)
	v_mfma_f32_16x16x32_bf16 v[102:105], v[162:165], v[202:205], v[102:105]
	v_mfma_f32_16x16x32_bf16 v[98:101], v[170:173], v[202:205], v[98:101]
	s_setprio 0
	s_barrier
	s_add_i32 s28, s22, s23
	v_readfirstlane_b32 s84, v139
	s_add_i32 s51, s28, 0x100
	s_mov_b32 m0, s84
	ds_read_b128 v[236:239], v155
	ds_read_b128 v[240:243], v155 offset:1024
	ds_read_b128 v[244:247], v155 offset:2048
	ds_read_b128 v[248:251], v155 offset:3072
	buffer_load_dwordx4 v136, s[68:71], s51 offen lds
	s_add_i32 s51, s21, s23
	v_readfirstlane_b32 s50, v140
	s_add_i32 s84, s51, 0x100
	s_mov_b32 m0, s50
	s_add_i32 s25, s25, 2
	buffer_load_dwordx4 v136, s[68:71], s84 offen lds
	s_barrier
	s_waitcnt lgkmcnt(0)
	s_setprio 1
	s_waitcnt lgkmcnt(3)
	v_mfma_f32_16x16x32_bf16 v[94:97], v[236:239], v[174:177], v[94:97]
	s_waitcnt lgkmcnt(1)
	v_mfma_f32_16x16x32_bf16 v[90:93], v[244:247], v[174:177], v[90:93]
	v_mfma_f32_16x16x32_bf16 v[86:89], v[236:239], v[182:185], v[86:89]
	v_mfma_f32_16x16x32_bf16 v[82:85], v[244:247], v[182:185], v[82:85]
	v_mfma_f32_16x16x32_bf16 v[78:81], v[236:239], v[190:193], v[78:81]
	v_mfma_f32_16x16x32_bf16 v[74:77], v[244:247], v[190:193], v[74:77]
	v_mfma_f32_16x16x32_bf16 v[70:73], v[236:239], v[198:201], v[70:73]
	v_mfma_f32_16x16x32_bf16 v[66:69], v[244:247], v[198:201], v[66:69]
	v_mfma_f32_16x16x32_bf16 v[94:97], v[240:243], v[178:181], v[94:97]
	s_waitcnt lgkmcnt(0)
	v_mfma_f32_16x16x32_bf16 v[90:93], v[248:251], v[178:181], v[90:93]
	v_mfma_f32_16x16x32_bf16 v[86:89], v[240:243], v[186:189], v[86:89]
	v_mfma_f32_16x16x32_bf16 v[82:85], v[248:251], v[186:189], v[82:85]
	v_mfma_f32_16x16x32_bf16 v[78:81], v[240:243], v[194:197], v[78:81]
	v_mfma_f32_16x16x32_bf16 v[74:77], v[248:251], v[194:197], v[74:77]
	v_mfma_f32_16x16x32_bf16 v[70:73], v[240:243], v[202:205], v[70:73]
	v_mfma_f32_16x16x32_bf16 v[66:69], v[248:251], v[202:205], v[66:69]
	s_setprio 0
	s_add_i32 s50, s20, s23
	v_readfirstlane_b32 s29, v137
	s_add_i32 s84, s50, 0x100
	s_mov_b32 m0, s29
	s_add_i32 s29, s19, s23
	v_readfirstlane_b32 s43, v141
	s_barrier
	ds_read_b128 v[174:177], v135 offset:16384
	ds_read_b128 v[178:181], v135 offset:17408
	ds_read_b128 v[182:185], v134 offset:16384
	ds_read_b128 v[186:189], v134 offset:17408
	ds_read_b128 v[190:193], v133 offset:16384
	ds_read_b128 v[194:197], v133 offset:17408
	ds_read_b128 v[198:201], v132 offset:16384
	ds_read_b128 v[202:205], v132 offset:17408
	buffer_load_dwordx4 v136, s[4:7], s84 offen lds
	s_add_i32 s84, s29, 0x100
	s_mov_b32 m0, s43
	s_nop 0
	buffer_load_dwordx4 v136, s[4:7], s84 offen lds
	s_barrier
	s_waitcnt lgkmcnt(0)
	s_setprio 1
	s_waitcnt lgkmcnt(7)
	v_mfma_f32_16x16x32_bf16 v[62:65], v[158:161], v[174:177], v[62:65]
	v_mfma_f32_16x16x32_bf16 v[58:61], v[166:169], v[174:177], v[58:61]
	s_waitcnt lgkmcnt(5)
	v_mfma_f32_16x16x32_bf16 v[54:57], v[158:161], v[182:185], v[54:57]
	v_mfma_f32_16x16x32_bf16 v[50:53], v[166:169], v[182:185], v[50:53]
	s_waitcnt lgkmcnt(3)
	v_mfma_f32_16x16x32_bf16 v[46:49], v[158:161], v[190:193], v[46:49]
	v_mfma_f32_16x16x32_bf16 v[42:45], v[166:169], v[190:193], v[42:45]
	s_waitcnt lgkmcnt(1)
	v_mfma_f32_16x16x32_bf16 v[38:41], v[158:161], v[198:201], v[38:41]
	v_mfma_f32_16x16x32_bf16 v[34:37], v[166:169], v[198:201], v[34:37]
	v_mfma_f32_16x16x32_bf16 v[62:65], v[162:165], v[178:181], v[62:65]
	v_mfma_f32_16x16x32_bf16 v[58:61], v[170:173], v[178:181], v[58:61]
	v_mfma_f32_16x16x32_bf16 v[54:57], v[162:165], v[186:189], v[54:57]
	v_mfma_f32_16x16x32_bf16 v[50:53], v[170:173], v[186:189], v[50:53]
	v_mfma_f32_16x16x32_bf16 v[46:49], v[162:165], v[194:197], v[46:49]
	v_mfma_f32_16x16x32_bf16 v[42:45], v[170:173], v[194:197], v[42:45]
	s_waitcnt lgkmcnt(0)
	v_mfma_f32_16x16x32_bf16 v[38:41], v[162:165], v[202:205], v[38:41]
	v_mfma_f32_16x16x32_bf16 v[34:37], v[170:173], v[202:205], v[34:37]
	s_setprio 0
	s_barrier
; #define WAIT_V(n) asm volatile("s_waitcnt vmcnt(" #n ")" ::: "memory")
; #define WAIT_L(n) asm volatile("s_waitcnt lgkmcnt(" #n ")" ::: "memory")
; #define BAR __builtin_amdgcn_s_barrier()
; #define SCHED __builtin_amdgcn_sched_barrier(0)
; template <int MODE>
; __device__ __forceinline__ void gemm_tile(const int ph, const int which, const int pm, const int pn) {
;     ...
;     STAGE(SB(0, 1), RB, bcolB, t + 2);
;     WAIT_V(6); BAR; MMA(1, 1, At, B1); BAR;
;     LDB(B0, 1, 0); SCHED; LDA(At, 1, 0); STAGE(SA(0, 1), RA, brow + HALF, t + 2);
;     WAIT_L(8); BAR; WAIT_L(0); MMA(0, 0, At, B0); BAR; SCHED;
;     LDB(B1, 1, 1); STAGE(SB(1, 0), RB, bcol, t + 3);
;     BAR; WAIT_L(0); MMA(0, 1, At, B1); BAR;
;     LDA(At, 1, 1); STAGE(SA(1, 0), RA, brow, t + 3);
;     BAR; WAIT_L(0); MMA(1, 0, At, B0); BAR; SCHED;
	s_add_i32 s43, s17, s23
	v_readfirstlane_b32 s38, v142
	s_add_i32 s84, s43, 0x100
	s_mov_b32 m0, s38
	s_add_i32 s38, s11, s23
	v_readfirstlane_b32 s12, v143
	buffer_load_dwordx4 v136, s[68:71], s84 offen lds
	s_add_i32 s84, s38, 0x100
	s_mov_b32 m0, s12
	s_nop 0
	buffer_load_dwordx4 v136, s[68:71], s84 offen lds
	s_waitcnt vmcnt(6)
	s_barrier
	s_setprio 1
	v_mfma_f32_16x16x32_bf16 v[30:33], v[236:239], v[174:177], v[30:33]
	v_mfma_f32_16x16x32_bf16 v[26:29], v[244:247], v[174:177], v[26:29]
	v_mfma_f32_16x16x32_bf16 v[22:25], v[236:239], v[182:185], v[22:25]
	v_mfma_f32_16x16x32_bf16 v[18:21], v[244:247], v[182:185], v[18:21]
	v_mfma_f32_16x16x32_bf16 v[14:17], v[236:239], v[190:193], v[14:17]
	v_mfma_f32_16x16x32_bf16 v[10:13], v[244:247], v[190:193], v[10:13]
	v_mfma_f32_16x16x32_bf16 v[6:9], v[236:239], v[198:201], v[6:9]
	v_mfma_f32_16x16x32_bf16 v[2:5], v[244:247], v[198:201], v[2:5]
	v_mfma_f32_16x16x32_bf16 v[30:33], v[240:243], v[178:181], v[30:33]
	v_mfma_f32_16x16x32_bf16 v[26:29], v[248:251], v[178:181], v[26:29]
	v_mfma_f32_16x16x32_bf16 v[22:25], v[240:243], v[186:189], v[22:25]
	v_mfma_f32_16x16x32_bf16 v[18:21], v[248:251], v[186:189], v[18:21]
	v_mfma_f32_16x16x32_bf16 v[14:17], v[240:243], v[194:197], v[14:17]
	v_mfma_f32_16x16x32_bf16 v[10:13], v[248:251], v[194:197], v[10:13]
	v_mfma_f32_16x16x32_bf16 v[6:9], v[240:243], v[202:205], v[6:9]
	v_mfma_f32_16x16x32_bf16 v[2:5], v[248:251], v[202:205], v[2:5]
	s_setprio 0
	s_barrier
	ds_read_b128 v[158:161], v144
	ds_read_b128 v[162:165], v144 offset:1024
	ds_read_b128 v[166:169], v144 offset:2048
	ds_read_b128 v[170:173], v144 offset:3072
	v_readfirstlane_b32 s12, v145
	s_addk_i32 s26, 0x100
	s_mov_b32 m0, s12
	v_readfirstlane_b32 s12, v146
	ds_read_b128 v[174:177], v135 offset:32768
	ds_read_b128 v[178:181], v135 offset:33792
	ds_read_b128 v[182:185], v134 offset:32768
	ds_read_b128 v[186:189], v134 offset:33792
	ds_read_b128 v[190:193], v133 offset:32768
	ds_read_b128 v[194:197], v133 offset:33792
	ds_read_b128 v[198:201], v132 offset:32768
	ds_read_b128 v[202:205], v132 offset:33792
	buffer_load_dwordx4 v136, s[4:7], s26 offen lds
	s_addk_i32 s27, 0x100
	s_mov_b32 m0, s12
	s_nop 0
	buffer_load_dwordx4 v136, s[4:7], s27 offen lds
	s_waitcnt lgkmcnt(8)
	s_barrier
	s_waitcnt lgkmcnt(0)
	s_setprio 1
	s_waitcnt lgkmcnt(7)
	v_mfma_f32_16x16x32_bf16 v[126:129], v[158:161], v[174:177], v[126:129]
	v_mfma_f32_16x16x32_bf16 v[122:125], v[166:169], v[174:177], v[122:125]
	s_waitcnt lgkmcnt(5)
	v_mfma_f32_16x16x32_bf16 v[118:121], v[158:161], v[182:185], v[118:121]
	v_mfma_f32_16x16x32_bf16 v[114:117], v[166:169], v[182:185], v[114:117]
	s_waitcnt lgkmcnt(3)
	v_mfma_f32_16x16x32_bf16 v[110:113], v[158:161], v[190:193], v[110:113]
	v_mfma_f32_16x16x32_bf16 v[106:109], v[166:169], v[190:193], v[106:109]
	s_waitcnt lgkmcnt(1)
	v_mfma_f32_16x16x32_bf16 v[102:105], v[158:161], v[198:201], v[102:105]
	v_mfma_f32_16x16x32_bf16 v[98:101], v[166:169], v[198:201], v[98:101]
	v_mfma_f32_16x16x32_bf16 v[126:129], v[162:165], v[178:181], v[126:129]
	v_mfma_f32_16x16x32_bf16 v[122:125], v[170:173], v[178:181], v[122:125]
	v_mfma_f32_16x16x32_bf16 v[118:121], v[162:165], v[186:189], v[118:121]
	v_mfma_f32_16x16x32_bf16 v[114:117], v[170:173], v[186:189], v[114:117]
	v_mfma_f32_16x16x32_bf16 v[110:113], v[162:165], v[194:197], v[110:113]
	v_mfma_f32_16x16x32_bf16 v[106:109], v[170:173], v[194:197], v[106:109]
	s_waitcnt lgkmcnt(0)
	v_mfma_f32_16x16x32_bf16 v[102:105], v[162:165], v[202:205], v[102:105]
	v_mfma_f32_16x16x32_bf16 v[98:101], v[170:173], v[202:205], v[98:101]
	s_setprio 0
	s_barrier
	v_readfirstlane_b32 s12, v147
	s_addk_i32 s28, 0x180
	s_mov_b32 m0, s12
	v_readfirstlane_b32 s12, v148
	ds_read_b128 v[236:239], v138
	ds_read_b128 v[240:243], v138 offset:1024
	ds_read_b128 v[244:247], v138 offset:2048
	ds_read_b128 v[248:251], v138 offset:3072
	buffer_load_dwordx4 v136, s[68:71], s28 offen lds
	s_addk_i32 s51, 0x180
	s_mov_b32 m0, s12
	s_nop 0
	buffer_load_dwordx4 v136, s[68:71], s51 offen lds
	s_barrier
	s_waitcnt lgkmcnt(0)
	s_setprio 1
	s_waitcnt lgkmcnt(3)
	v_mfma_f32_16x16x32_bf16 v[94:97], v[236:239], v[174:177], v[94:97]
	s_waitcnt lgkmcnt(1)
	v_mfma_f32_16x16x32_bf16 v[90:93], v[244:247], v[174:177], v[90:93]
	v_mfma_f32_16x16x32_bf16 v[86:89], v[236:239], v[182:185], v[86:89]
	v_mfma_f32_16x16x32_bf16 v[82:85], v[244:247], v[182:185], v[82:85]
	v_mfma_f32_16x16x32_bf16 v[78:81], v[236:239], v[190:193], v[78:81]
	v_mfma_f32_16x16x32_bf16 v[74:77], v[244:247], v[190:193], v[74:77]
	v_mfma_f32_16x16x32_bf16 v[70:73], v[236:239], v[198:201], v[70:73]
	v_mfma_f32_16x16x32_bf16 v[66:69], v[244:247], v[198:201], v[66:69]
	v_mfma_f32_16x16x32_bf16 v[94:97], v[240:243], v[178:181], v[94:97]
	s_waitcnt lgkmcnt(0)
	v_mfma_f32_16x16x32_bf16 v[90:93], v[248:251], v[178:181], v[90:93]
	v_mfma_f32_16x16x32_bf16 v[86:89], v[240:243], v[186:189], v[86:89]
	v_mfma_f32_16x16x32_bf16 v[82:85], v[248:251], v[186:189], v[82:85]
	v_mfma_f32_16x16x32_bf16 v[78:81], v[240:243], v[194:197], v[78:81]
	v_mfma_f32_16x16x32_bf16 v[74:77], v[248:251], v[194:197], v[74:77]
	v_mfma_f32_16x16x32_bf16 v[70:73], v[240:243], v[202:205], v[70:73]
	v_mfma_f32_16x16x32_bf16 v[66:69], v[248:251], v[202:205], v[66:69]
	s_setprio 0
	v_readfirstlane_b32 s12, v149
	s_addk_i32 s50, 0x180
	s_mov_b32 m0, s12
	v_readfirstlane_b32 s12, v150
	s_barrier
	ds_read_b128 v[174:177], v135 offset:49152
	ds_read_b128 v[178:181], v135 offset:50176
	ds_read_b128 v[182:185], v134 offset:49152
	ds_read_b128 v[186:189], v134 offset:50176
	ds_read_b128 v[190:193], v133 offset:49152
	ds_read_b128 v[194:197], v133 offset:50176
	ds_read_b128 v[198:201], v132 offset:49152
	ds_read_b128 v[202:205], v132 offset:50176
	buffer_load_dwordx4 v136, s[4:7], s50 offen lds
	s_addk_i32 s29, 0x180
	s_mov_b32 m0, s12
	s_nop 0
	buffer_load_dwordx4 v136, s[4:7], s29 offen lds
	s_barrier
; #define WAIT_V(n) asm volatile("s_waitcnt vmcnt(" #n ")" ::: "memory")
; #define WAIT_L(n) asm volatile("s_waitcnt lgkmcnt(" #n ")" ::: "memory")
; #define BAR __builtin_amdgcn_s_barrier()
; #define SCHED __builtin_amdgcn_sched_barrier(0)
; template <int MODE>
; __device__ __forceinline__ void gemm_tile(const int ph, const int which, const int pm, const int pn) {
;     ...
;     BAR; WAIT_L(0); MMA(1, 0, At, B0); BAR; SCHED;
;     STAGE(SB(1, 1), RB, bcolB, t + 3);
;     WAIT_V(6); BAR; MMA(1, 1, At, B1); BAR;
;   }
;   {
;     LDB(B0, 0, 0); LDA(At, 0, 0); STAGE(SA(1, 1), RA, brow + HALF, nt - 1);
;     BAR; WAIT_L(0); MMA(0, 0, At, B0); BAR;
;     LDB(B1, 0, 1); BAR; WAIT_L(0); MMA(0, 1, At, B1); BAR;
	s_waitcnt lgkmcnt(0)
	s_setprio 1
	s_waitcnt lgkmcnt(7)
	v_mfma_f32_16x16x32_bf16 v[62:65], v[158:161], v[174:177], v[62:65]
	v_mfma_f32_16x16x32_bf16 v[58:61], v[166:169], v[174:177], v[58:61]
	s_waitcnt lgkmcnt(5)
	v_mfma_f32_16x16x32_bf16 v[54:57], v[158:161], v[182:185], v[54:57]
	v_mfma_f32_16x16x32_bf16 v[50:53], v[166:169], v[182:185], v[50:53]
	s_waitcnt lgkmcnt(3)
	v_mfma_f32_16x16x32_bf16 v[46:49], v[158:161], v[190:193], v[46:49]
	v_mfma_f32_16x16x32_bf16 v[42:45], v[166:169], v[190:193], v[42:45]
	s_waitcnt lgkmcnt(1)
	v_mfma_f32_16x16x32_bf16 v[38:41], v[158:161], v[198:201], v[38:41]
	v_mfma_f32_16x16x32_bf16 v[34:37], v[166:169], v[198:201], v[34:37]
	v_mfma_f32_16x16x32_bf16 v[62:65], v[162:165], v[178:181], v[62:65]
	v_mfma_f32_16x16x32_bf16 v[58:61], v[170:173], v[178:181], v[58:61]
	v_mfma_f32_16x16x32_bf16 v[54:57], v[162:165], v[186:189], v[54:57]
	v_mfma_f32_16x16x32_bf16 v[50:53], v[170:173], v[186:189], v[50:53]
	v_mfma_f32_16x16x32_bf16 v[46:49], v[162:165], v[194:197], v[46:49]
	v_mfma_f32_16x16x32_bf16 v[42:45], v[170:173], v[194:197], v[42:45]
	s_waitcnt lgkmcnt(0)
	v_mfma_f32_16x16x32_bf16 v[38:41], v[162:165], v[202:205], v[38:41]
	v_mfma_f32_16x16x32_bf16 v[34:37], v[170:173], v[202:205], v[34:37]
	s_setprio 0
	s_barrier
	v_readfirstlane_b32 s12, v152
	s_addk_i32 s43, 0x180
	s_mov_b32 m0, s12
	v_readfirstlane_b32 s12, v154
	buffer_load_dwordx4 v136, s[68:71], s43 offen lds
	s_addk_i32 s38, 0x180
	s_mov_b32 m0, s12
	s_nop 0
	buffer_load_dwordx4 v136, s[68:71], s38 offen lds
	s_waitcnt vmcnt(6)
	s_barrier
	s_setprio 1
	v_mfma_f32_16x16x32_bf16 v[30:33], v[236:239], v[174:177], v[30:33]
	v_mfma_f32_16x16x32_bf16 v[26:29], v[244:247], v[174:177], v[26:29]
	v_mfma_f32_16x16x32_bf16 v[22:25], v[236:239], v[182:185], v[22:25]
	v_mfma_f32_16x16x32_bf16 v[18:21], v[244:247], v[182:185], v[18:21]
	v_mfma_f32_16x16x32_bf16 v[14:17], v[236:239], v[190:193], v[14:17]
	v_mfma_f32_16x16x32_bf16 v[10:13], v[244:247], v[190:193], v[10:13]
	v_mfma_f32_16x16x32_bf16 v[6:9], v[236:239], v[198:201], v[6:9]
	v_mfma_f32_16x16x32_bf16 v[2:5], v[244:247], v[198:201], v[2:5]
	v_mfma_f32_16x16x32_bf16 v[30:33], v[240:243], v[178:181], v[30:33]
	v_mfma_f32_16x16x32_bf16 v[26:29], v[248:251], v[178:181], v[26:29]
	v_mfma_f32_16x16x32_bf16 v[22:25], v[240:243], v[186:189], v[22:25]
	v_mfma_f32_16x16x32_bf16 v[18:21], v[248:251], v[186:189], v[18:21]
	v_mfma_f32_16x16x32_bf16 v[14:17], v[240:243], v[194:197], v[14:17]
	v_mfma_f32_16x16x32_bf16 v[10:13], v[248:251], v[194:197], v[10:13]
	v_mfma_f32_16x16x32_bf16 v[6:9], v[240:243], v[202:205], v[6:9]
	v_mfma_f32_16x16x32_bf16 v[2:5], v[248:251], v[202:205], v[2:5]
	s_setprio 0
	s_addk_i32 s23, 0x100
	s_cmp_lt_u32 s25, s2
	s_cbranch_scc1 .Lgemm_head_540
	s_barrier
	s_add_i32 s2, s24, s9
	s_lshl_b32 s2, s2, 1
	v_readfirstlane_b32 s3, v153
	s_addk_i32 s2, 0xff80
	s_mov_b32 s6, s70
	s_mov_b32 s7, s71
	s_mov_b32 m0, s3
	v_readfirstlane_b32 s3, v151
	ds_read_b128 v[140:143], v156
	ds_read_b128 v[146:149], v156 offset:1024
	ds_read_b128 v[158:161], v156 offset:2048
	ds_read_b128 v[162:165], v156 offset:3072
	ds_read_b128 v[166:169], v135
	ds_read_b128 v[170:173], v135 offset:1024
	ds_read_b128 v[174:177], v134
	ds_read_b128 v[178:181], v134 offset:1024
	ds_read_b128 v[182:185], v133
	ds_read_b128 v[186:189], v133 offset:1024
	ds_read_b128 v[190:193], v132
	ds_read_b128 v[194:197], v132 offset:1024
	buffer_load_dwordx4 v136, s[4:7], s2 offen lds
	s_add_i32 s2, s2, s8
	s_mov_b32 m0, s3
	s_nop 0
	buffer_load_dwordx4 v136, s[4:7], s2 offen lds
	s_barrier
	s_waitcnt lgkmcnt(0)
	s_setprio 1
	s_waitcnt lgkmcnt(7)
	v_mfma_f32_16x16x32_bf16 v[126:129], v[140:143], v[166:169], v[126:129]
	v_mfma_f32_16x16x32_bf16 v[122:125], v[158:161], v[166:169], v[122:125]
	s_waitcnt lgkmcnt(3)
	v_mfma_f32_16x16x32_bf16 v[110:113], v[140:143], v[182:185], v[110:113]
	v_mfma_f32_16x16x32_bf16 v[106:109], v[158:161], v[182:185], v[106:109]
	v_mfma_f32_16x16x32_bf16 v[126:129], v[146:149], v[170:173], v[126:129]
	v_mfma_f32_16x16x32_bf16 v[122:125], v[162:165], v[170:173], v[122:125]
	v_mfma_f32_16x16x32_bf16 v[118:121], v[140:143], v[174:177], v[118:121]
	v_mfma_f32_16x16x32_bf16 v[114:117], v[158:161], v[174:177], v[114:117]
	s_waitcnt lgkmcnt(2)
	v_mfma_f32_16x16x32_bf16 v[110:113], v[146:149], v[186:189], v[110:113]
	v_mfma_f32_16x16x32_bf16 v[106:109], v[162:165], v[186:189], v[106:109]
	s_waitcnt lgkmcnt(1)
	v_mfma_f32_16x16x32_bf16 v[102:105], v[140:143], v[190:193], v[102:105]
	v_mfma_f32_16x16x32_bf16 v[98:101], v[158:161], v[190:193], v[98:101]
	v_mfma_f32_16x16x32_bf16 v[150:153], v[146:149], v[178:181], v[118:121]
	v_mfma_f32_16x16x32_bf16 v[198:201], v[162:165], v[178:181], v[114:117]
	s_waitcnt lgkmcnt(0)
	v_mfma_f32_16x16x32_bf16 v[202:205], v[146:149], v[194:197], v[102:105]
	v_mfma_f32_16x16x32_bf16 v[236:239], v[162:165], v[194:197], v[98:101]
	s_setprio 0
	s_barrier
	s_nop 0
	ds_read_b128 v[98:101], v155
	ds_read_b128 v[102:105], v155 offset:1024
	ds_read_b128 v[114:117], v155 offset:2048
	ds_read_b128 v[118:121], v155 offset:3072
	s_barrier
; #define WAIT_V(n) asm volatile("s_waitcnt vmcnt(" #n ")" ::: "memory")
; #define WAIT_L(n) asm volatile("s_waitcnt lgkmcnt(" #n ")" ::: "memory")
; #define BAR __builtin_amdgcn_s_barrier()
; template <int MODE>
; __device__ __forceinline__ void gemm_tile(const int ph, const int which, const int pm, const int pn) {
;     ...
;     LDB(B1, 0, 1); BAR; WAIT_L(0); MMA(0, 1, At, B1); BAR;
;     LDA(At, 0, 1); WAIT_V(4); BAR; WAIT_L(0); MMA(1, 0, At, B0); MMA(1, 1, At, B1); BAR;
;   }
;   {
;     LDB(B0, 1, 0); LDA(At, 1, 0); WAIT_V(2); BAR; WAIT_L(0); MMA(0, 0, At, B0); BAR;
	s_waitcnt lgkmcnt(0)
	s_setprio 1
	s_waitcnt lgkmcnt(3)
	v_mfma_f32_16x16x32_bf16 v[94:97], v[98:101], v[166:169], v[94:97]
	s_waitcnt lgkmcnt(1)
	v_mfma_f32_16x16x32_bf16 v[90:93], v[114:117], v[166:169], v[90:93]
	v_mfma_f32_16x16x32_bf16 v[78:81], v[98:101], v[182:185], v[78:81]
	v_mfma_f32_16x16x32_bf16 v[74:77], v[114:117], v[182:185], v[74:77]
	v_mfma_f32_16x16x32_bf16 v[70:73], v[98:101], v[190:193], v[70:73]
	v_mfma_f32_16x16x32_bf16 v[66:69], v[114:117], v[190:193], v[66:69]
	v_mfma_f32_16x16x32_bf16 v[94:97], v[102:105], v[170:173], v[94:97]
	s_waitcnt lgkmcnt(0)
	v_mfma_f32_16x16x32_bf16 v[90:93], v[118:121], v[170:173], v[90:93]
	v_mfma_f32_16x16x32_bf16 v[86:89], v[98:101], v[174:177], v[86:89]
	v_mfma_f32_16x16x32_bf16 v[82:85], v[114:117], v[174:177], v[82:85]
	v_mfma_f32_16x16x32_bf16 v[78:81], v[102:105], v[186:189], v[78:81]
	v_mfma_f32_16x16x32_bf16 v[74:77], v[118:121], v[186:189], v[74:77]
	v_mfma_f32_16x16x32_bf16 v[70:73], v[102:105], v[194:197], v[70:73]
	v_mfma_f32_16x16x32_bf16 v[66:69], v[118:121], v[194:197], v[66:69]
	v_mfma_f32_16x16x32_bf16 v[154:157], v[102:105], v[178:181], v[86:89]
	v_mfma_f32_16x16x32_bf16 v[166:169], v[118:121], v[178:181], v[82:85]
	s_setprio 0
	s_barrier
	s_nop 0
	ds_read_b128 v[82:85], v135 offset:16384
	ds_read_b128 v[86:89], v135 offset:17408
	ds_read_b128 v[170:173], v134 offset:16384
	ds_read_b128 v[174:177], v134 offset:17408
	ds_read_b128 v[178:181], v133 offset:16384
	ds_read_b128 v[182:185], v133 offset:17408
	ds_read_b128 v[186:189], v132 offset:16384
	ds_read_b128 v[190:193], v132 offset:17408
	s_waitcnt vmcnt(4)
	s_barrier
	s_waitcnt lgkmcnt(0)
	s_setprio 1
	s_waitcnt lgkmcnt(7)
	v_mfma_f32_16x16x32_bf16 v[62:65], v[140:143], v[82:85], v[62:65]
	s_waitcnt lgkmcnt(3)
	v_mfma_f32_16x16x32_bf16 v[46:49], v[140:143], v[178:181], v[46:49]
	v_mfma_f32_16x16x32_bf16 v[42:45], v[158:161], v[178:181], v[42:45]
	v_mfma_f32_16x16x32_bf16 v[62:65], v[146:149], v[86:89], v[62:65]
	v_mfma_f32_16x16x32_bf16 v[58:61], v[158:161], v[82:85], v[58:61]
	v_mfma_f32_16x16x32_bf16 v[54:57], v[140:143], v[170:173], v[54:57]
	v_mfma_f32_16x16x32_bf16 v[50:53], v[158:161], v[170:173], v[50:53]
	s_waitcnt lgkmcnt(2)
	v_mfma_f32_16x16x32_bf16 v[46:49], v[146:149], v[182:185], v[46:49]
	v_mfma_f32_16x16x32_bf16 v[42:45], v[162:165], v[182:185], v[42:45]
	s_waitcnt lgkmcnt(1)
	v_mfma_f32_16x16x32_bf16 v[38:41], v[140:143], v[186:189], v[38:41]
	v_mfma_f32_16x16x32_bf16 v[34:37], v[158:161], v[186:189], v[34:37]
	v_mfma_f32_16x16x32_bf16 v[194:197], v[162:165], v[86:89], v[58:61]
	v_mfma_f32_16x16x32_bf16 v[240:243], v[146:149], v[174:177], v[54:57]
	v_mfma_f32_16x16x32_bf16 v[244:247], v[162:165], v[174:177], v[50:53]
	s_waitcnt lgkmcnt(0)
	v_mfma_f32_16x16x32_bf16 v[140:143], v[146:149], v[190:193], v[38:41]
	v_mfma_f32_16x16x32_bf16 v[146:149], v[162:165], v[190:193], v[34:37]
	s_setprio 0
	s_setprio 1
	v_mfma_f32_16x16x32_bf16 v[30:33], v[98:101], v[82:85], v[30:33]
	v_mfma_f32_16x16x32_bf16 v[26:29], v[114:117], v[82:85], v[26:29]
	v_mfma_f32_16x16x32_bf16 v[14:17], v[98:101], v[178:181], v[14:17]
	v_mfma_f32_16x16x32_bf16 v[10:13], v[114:117], v[178:181], v[10:13]
	v_mfma_f32_16x16x32_bf16 v[30:33], v[102:105], v[86:89], v[30:33]
	v_mfma_f32_16x16x32_bf16 v[26:29], v[118:121], v[86:89], v[26:29]
	v_mfma_f32_16x16x32_bf16 v[22:25], v[98:101], v[170:173], v[22:25]
	v_mfma_f32_16x16x32_bf16 v[18:21], v[114:117], v[170:173], v[18:21]
	v_mfma_f32_16x16x32_bf16 v[14:17], v[102:105], v[182:185], v[14:17]
	v_mfma_f32_16x16x32_bf16 v[10:13], v[118:121], v[182:185], v[10:13]
	v_mfma_f32_16x16x32_bf16 v[6:9], v[98:101], v[186:189], v[6:9]
	v_mfma_f32_16x16x32_bf16 v[2:5], v[114:117], v[186:189], v[2:5]
	v_mfma_f32_16x16x32_bf16 v[158:161], v[102:105], v[174:177], v[22:25]
	v_mfma_f32_16x16x32_bf16 v[162:165], v[118:121], v[174:177], v[18:21]
	v_mfma_f32_16x16x32_bf16 v[170:173], v[102:105], v[190:193], v[6:9]
	v_mfma_f32_16x16x32_bf16 v[174:177], v[118:121], v[190:193], v[2:5]
	s_setprio 0
	s_barrier
	s_nop 1
	ds_read_b128 v[2:5], v144
	ds_read_b128 v[6:9], v144 offset:1024
	ds_read_b128 v[178:181], v144 offset:2048
	ds_read_b128 v[182:185], v144 offset:3072
	ds_read_b128 v[18:21], v135 offset:32768
	ds_read_b128 v[22:25], v135 offset:33792
	ds_read_b128 v[34:37], v134 offset:32768
	ds_read_b128 v[38:41], v134 offset:33792
	ds_read_b128 v[58:61], v133 offset:32768
	ds_read_b128 v[186:189], v133 offset:33792
	ds_read_b128 v[190:193], v132 offset:32768
	ds_read_b128 v[248:251], v132 offset:33792
	s_waitcnt vmcnt(2)
	s_barrier
; #define WAIT_V(n) asm volatile("s_waitcnt vmcnt(" #n ")" ::: "memory")
; #define WAIT_L(n) asm volatile("s_waitcnt lgkmcnt(" #n ")" ::: "memory")
; #define BAR __builtin_amdgcn_s_barrier()
; template <int MODE>
; __device__ __forceinline__ void gemm_tile(const int ph, const int which, const int pm, const int pn) {
;     ...
;     LDB(B0, 1, 0); LDA(At, 1, 0); WAIT_V(2); BAR; WAIT_L(0); MMA(0, 0, At, B0); BAR;
;     LDB(B1, 1, 1); WAIT_V(0); BAR; WAIT_L(0); MMA(0, 1, At, B1); BAR;
;     LDA(At, 1, 1); BAR; WAIT_L(0); MMA(1, 0, At, B0); MMA(1, 1, At, B1); BAR;
;   }
;   if (wr == 0) BAR;
	s_waitcnt lgkmcnt(0)
	s_setprio 1
	s_waitcnt lgkmcnt(7)
	v_mfma_f32_16x16x32_bf16 v[50:53], v[2:5], v[18:21], v[126:129]
	s_waitcnt lgkmcnt(6)
	v_mfma_f32_16x16x32_bf16 v[114:117], v[6:9], v[22:25], v[50:53]
	v_mfma_f32_16x16x32_bf16 v[50:53], v[178:181], v[18:21], v[122:125]
	v_mfma_f32_16x16x32_bf16 v[118:121], v[182:185], v[22:25], v[50:53]
	s_waitcnt lgkmcnt(5)
	v_mfma_f32_16x16x32_bf16 v[50:53], v[2:5], v[34:37], v[150:153]
	s_waitcnt lgkmcnt(4)
	v_mfma_f32_16x16x32_bf16 v[98:101], v[6:9], v[38:41], v[50:53]
	v_mfma_f32_16x16x32_bf16 v[50:53], v[178:181], v[34:37], v[198:201]
	v_mfma_f32_16x16x32_bf16 v[102:105], v[182:185], v[38:41], v[50:53]
	s_waitcnt lgkmcnt(3)
	v_mfma_f32_16x16x32_bf16 v[50:53], v[2:5], v[58:61], v[110:113]
	s_waitcnt lgkmcnt(2)
	v_mfma_f32_16x16x32_bf16 v[82:85], v[6:9], v[186:189], v[50:53]
	v_mfma_f32_16x16x32_bf16 v[50:53], v[178:181], v[58:61], v[106:109]
	v_mfma_f32_16x16x32_bf16 v[86:89], v[182:185], v[186:189], v[50:53]
	s_waitcnt lgkmcnt(1)
	v_mfma_f32_16x16x32_bf16 v[50:53], v[2:5], v[190:193], v[202:205]
	v_mfma_f32_16x16x32_bf16 v[54:57], v[178:181], v[190:193], v[236:239]
	s_waitcnt lgkmcnt(0)
	v_mfma_f32_16x16x32_bf16 v[50:53], v[6:9], v[248:251], v[50:53]
	v_mfma_f32_16x16x32_bf16 v[54:57], v[182:185], v[248:251], v[54:57]
	s_setprio 0
	s_barrier
	ds_read_b128 v[150:153], v138
	ds_read_b128 v[198:201], v138 offset:1024
	ds_read_b128 v[202:205], v138 offset:2048
	ds_read_b128 v[136:139], v138 offset:3072
	s_waitcnt vmcnt(0)
	s_barrier
	s_waitcnt lgkmcnt(0)
	s_setprio 1
	s_waitcnt lgkmcnt(3)
	v_mfma_f32_16x16x32_bf16 v[94:97], v[150:153], v[18:21], v[94:97]
	s_waitcnt lgkmcnt(1)
	v_mfma_f32_16x16x32_bf16 v[18:21], v[202:205], v[18:21], v[90:93]
	s_waitcnt lgkmcnt(0)
	v_mfma_f32_16x16x32_bf16 v[126:129], v[136:139], v[22:25], v[18:21]
	v_mfma_f32_16x16x32_bf16 v[18:21], v[150:153], v[34:37], v[154:157]
	v_mfma_f32_16x16x32_bf16 v[106:109], v[198:201], v[38:41], v[18:21]
	v_mfma_f32_16x16x32_bf16 v[18:21], v[202:205], v[34:37], v[166:169]
	v_mfma_f32_16x16x32_bf16 v[110:113], v[136:139], v[38:41], v[18:21]
	v_mfma_f32_16x16x32_bf16 v[18:21], v[150:153], v[58:61], v[78:81]
	v_mfma_f32_16x16x32_bf16 v[90:93], v[198:201], v[186:189], v[18:21]
	v_mfma_f32_16x16x32_bf16 v[18:21], v[202:205], v[58:61], v[74:77]
	v_mfma_f32_16x16x32_bf16 v[122:125], v[198:201], v[22:25], v[94:97]
	v_mfma_f32_16x16x32_bf16 v[94:97], v[136:139], v[186:189], v[18:21]
	v_mfma_f32_16x16x32_bf16 v[18:21], v[150:153], v[190:193], v[70:73]
	v_mfma_f32_16x16x32_bf16 v[74:77], v[198:201], v[248:251], v[18:21]
	v_mfma_f32_16x16x32_bf16 v[18:21], v[202:205], v[190:193], v[66:69]
	v_mfma_f32_16x16x32_bf16 v[78:81], v[136:139], v[248:251], v[18:21]
	s_setprio 0
	s_barrier
	ds_read_b128 v[70:73], v135 offset:49152
	ds_read_b128 v[154:157], v135 offset:50176
	ds_read_b128 v[166:169], v134 offset:49152
	ds_read_b128 v[186:189], v134 offset:50176
	ds_read_b128 v[190:193], v133 offset:49152
	ds_read_b128 v[236:239], v133 offset:50176
	ds_read_b128 v[248:251], v132 offset:49152
	ds_read_b128 v[132:135], v132 offset:50176
	s_barrier
	s_waitcnt lgkmcnt(0)
	s_setprio 1
	s_waitcnt lgkmcnt(7)
	v_mfma_f32_16x16x32_bf16 v[18:21], v[2:5], v[70:73], v[62:65]
	s_waitcnt lgkmcnt(6)
	v_mfma_f32_16x16x32_bf16 v[58:61], v[6:9], v[154:157], v[18:21]
	v_mfma_f32_16x16x32_bf16 v[18:21], v[178:181], v[70:73], v[194:197]
	v_mfma_f32_16x16x32_bf16 v[62:65], v[182:185], v[154:157], v[18:21]
	s_waitcnt lgkmcnt(5)
	v_mfma_f32_16x16x32_bf16 v[18:21], v[2:5], v[166:169], v[240:243]
	s_waitcnt lgkmcnt(4)
	v_mfma_f32_16x16x32_bf16 v[34:37], v[6:9], v[186:189], v[18:21]
	v_mfma_f32_16x16x32_bf16 v[18:21], v[178:181], v[166:169], v[244:247]
	v_mfma_f32_16x16x32_bf16 v[38:41], v[182:185], v[186:189], v[18:21]
	s_waitcnt lgkmcnt(3)
	v_mfma_f32_16x16x32_bf16 v[18:21], v[2:5], v[190:193], v[46:49]
	s_waitcnt lgkmcnt(1)
	v_mfma_f32_16x16x32_bf16 v[2:5], v[2:5], v[248:251], v[140:143]
	v_mfma_f32_16x16x32_bf16 v[18:21], v[6:9], v[236:239], v[18:21]
	v_mfma_f32_16x16x32_bf16 v[22:25], v[178:181], v[190:193], v[42:45]
	s_waitcnt lgkmcnt(0)
	v_mfma_f32_16x16x32_bf16 v[2:5], v[6:9], v[132:135], v[2:5]
	v_mfma_f32_16x16x32_bf16 v[6:9], v[178:181], v[248:251], v[146:149]
	v_mfma_f32_16x16x32_bf16 v[22:25], v[182:185], v[236:239], v[22:25]
	v_mfma_f32_16x16x32_bf16 v[6:9], v[182:185], v[132:135], v[6:9]
	s_setprio 0
	s_setprio 1
	v_mfma_f32_16x16x32_bf16 v[26:29], v[202:205], v[70:73], v[26:29]
	v_mfma_f32_16x16x32_bf16 v[30:33], v[150:153], v[70:73], v[30:33]
	v_mfma_f32_16x16x32_bf16 v[70:73], v[136:139], v[154:157], v[26:29]
	v_mfma_f32_16x16x32_bf16 v[26:29], v[150:153], v[166:169], v[158:161]
	v_mfma_f32_16x16x32_bf16 v[42:45], v[198:201], v[186:189], v[26:29]
	v_mfma_f32_16x16x32_bf16 v[26:29], v[202:205], v[166:169], v[162:165]
	v_mfma_f32_16x16x32_bf16 v[14:17], v[150:153], v[190:193], v[14:17]
	v_mfma_f32_16x16x32_bf16 v[10:13], v[202:205], v[190:193], v[10:13]
	v_mfma_f32_16x16x32_bf16 v[66:69], v[198:201], v[154:157], v[30:33]
	v_mfma_f32_16x16x32_bf16 v[46:49], v[136:139], v[186:189], v[26:29]
	v_mfma_f32_16x16x32_bf16 v[26:29], v[198:201], v[236:239], v[14:17]
	v_mfma_f32_16x16x32_bf16 v[30:33], v[136:139], v[236:239], v[10:13]
	v_mfma_f32_16x16x32_bf16 v[10:13], v[150:153], v[248:251], v[170:173]
	v_mfma_f32_16x16x32_bf16 v[14:17], v[202:205], v[248:251], v[174:177]
	v_mfma_f32_16x16x32_bf16 v[10:13], v[198:201], v[132:135], v[10:13]
	v_mfma_f32_16x16x32_bf16 v[14:17], v[136:139], v[132:135], v[14:17]
	s_setprio 0
	s_movk_i32 s2, 0x100
	v_cmp_gt_u32_e32 vcc, s2, v0
	s_barrier
	s_and_saveexec_b64 s[2:3], vcc
	s_cbranch_execz .LBB0_543
	s_barrier

; __device__ __forceinline__ unsigned short f2bf(float f) { return (unsigned short)(pack2(f, 0.f) & 0xffffu); }
; __device__ void filt_item(const Params& p, int item) {
;     ...
;   for (int mt = wid; mt < L / 16; mt += 8) {
;     const float* hrow = H2 + (size_t)(mt * 16 + n) * 64 + quad * 8;
;     f32x4 acc = {0.f, 0.f, 0.f, 0.f};
; #pragma unroll
;     for (int ks = 0; ks < 2; ++ks) {
;       float4 a0 = *(const float4*)(hrow + ks * 32), a1 = *(const float4*)(hrow + ks * 32 + 4);
;       float hv[8] = {a0.x, a0.y, a0.z, a0.w, a1.x, a1.y, a1.z, a1.w};
;       bf16x8 ah, al;
;       split_bf16x8(hv, ah, al);
;       acc = __builtin_amdgcn_mfma_f32_16x16x32_bf16(ah, bh[ks], acc, 0, 0, 0);
;       acc = __builtin_amdgcn_mfma_f32_16x16x32_bf16(al, bh[ks], acc, 0, 0, 0);
;       acc = __builtin_amdgcn_mfma_f32_16x16x32_bf16(ah, bl[ks], acc, 0, 0, 0);
;     }
; #pragma unroll
;     for (int rr = 0; rr < 4; ++rr) {
;       const int tap = mt * 16 + quad * 4 + rr;
;       float v = acc[rr] * expf(-(float)tap * inv * adelta);
;       if (dir == 0) {
;         if (tap == 0) v += fbias;
;         G[L - tap] = f2bf(v);
;       } else if (tap >= 1) {
;         G[L + tap] = f2bf(v);
;       }
.LBB0_1313:
	global_load_dwordx4 v[18:21], v[30:31], off offset:-112
	global_load_dwordx4 v[22:25], v[30:31], off offset:-128
	global_load_dwordx4 v[184:187], v[30:31], off offset:16
	global_load_dwordx4 v[188:191], v[30:31], off
	v_cvt_f32_i32_e32 v0, v39
	s_mov_b64 s[8:9], 0
	v_mul_f32_e64 v0, v38, -v0
	s_waitcnt vmcnt(2)
	v_cvt_pk_bf16_f32 v40, v22, v23
	v_lshlrev_b32_e32 v42, 16, v40
	v_and_b32_e32 v43, 0xffff0000, v40
	v_cvt_pk_bf16_f32 v41, v24, v25
	v_pk_add_f32 v[22:23], v[22:23], v[42:43] neg_lo:[0,1] neg_hi:[0,1]
	v_lshlrev_b32_e32 v42, 16, v41
	v_and_b32_e32 v43, 0xffff0000, v41
	v_pk_add_f32 v[24:25], v[24:25], v[42:43] neg_lo:[0,1] neg_hi:[0,1]
	v_cvt_pk_bf16_f32 v42, v18, v19
	v_cvt_pk_bf16_f32 v22, v22, v23
	v_cvt_pk_bf16_f32 v23, v24, v25
	v_lshlrev_b32_e32 v24, 16, v42
	v_and_b32_e32 v25, 0xffff0000, v42
	v_cvt_pk_bf16_f32 v43, v20, v21
	v_pk_add_f32 v[18:19], v[18:19], v[24:25] neg_lo:[0,1] neg_hi:[0,1]
	s_nop 0
	v_cvt_pk_bf16_f32 v24, v18, v19
	v_lshlrev_b32_e32 v18, 16, v43
	v_and_b32_e32 v19, 0xffff0000, v43
	v_pk_add_f32 v[18:19], v[20:21], v[18:19] neg_lo:[0,1] neg_hi:[0,1]
	s_nop 0
	v_cvt_pk_bf16_f32 v25, v18, v19
	v_mfma_f32_16x16x32_bf16 v[18:21], v[40:43], v[10:13], 0
	s_nop 0
	v_mfma_f32_16x16x32_bf16 v[18:21], v[22:25], v[10:13], v[18:21]
	v_mfma_f32_16x16x32_bf16 v[18:21], v[40:43], v[14:17], v[18:21]
	s_waitcnt vmcnt(0)
	v_mov_b32_e32 v22, v184
	v_mov_b32_e32 v23, v185
	v_mov_b32_e32 v24, v186
	v_mov_b32_e32 v25, v187
	v_mov_b32_e32 v40, v188
	v_mov_b32_e32 v41, v189
	v_mov_b32_e32 v42, v190
	v_mov_b32_e32 v43, v191
	v_cvt_pk_bf16_f32 v44, v40, v41
	v_lshlrev_b32_e32 v46, 16, v44
	v_and_b32_e32 v47, 0xffff0000, v44
	v_cvt_pk_bf16_f32 v45, v42, v43
	v_pk_add_f32 v[40:41], v[40:41], v[46:47] neg_lo:[0,1] neg_hi:[0,1]
	v_lshlrev_b32_e32 v46, 16, v45
	v_and_b32_e32 v47, 0xffff0000, v45
	v_pk_add_f32 v[42:43], v[42:43], v[46:47] neg_lo:[0,1] neg_hi:[0,1]
	v_cvt_pk_bf16_f32 v46, v22, v23
	v_cvt_pk_bf16_f32 v40, v40, v41
	v_cvt_pk_bf16_f32 v41, v42, v43
	v_lshlrev_b32_e32 v42, 16, v46
	v_and_b32_e32 v43, 0xffff0000, v46
	v_cvt_pk_bf16_f32 v47, v24, v25
	v_pk_add_f32 v[22:23], v[22:23], v[42:43] neg_lo:[0,1] neg_hi:[0,1]
	s_nop 0
	v_cvt_pk_bf16_f32 v42, v22, v23
	v_lshlrev_b32_e32 v22, 16, v47
	v_and_b32_e32 v23, 0xffff0000, v47
	v_pk_add_f32 v[22:23], v[24:25], v[22:23] neg_lo:[0,1] neg_hi:[0,1]
	v_mfma_f32_16x16x32_bf16 v[18:21], v[44:47], v[2:5], v[18:21]
	v_cvt_pk_bf16_f32 v43, v22, v23
	v_mul_f32_e64 v24, |v36|, v0
	v_cmp_ngt_f32_e64 s[4:5], s94, v24
	v_mfma_f32_16x16x32_bf16 v[18:21], v[40:43], v[2:5], v[18:21]
	v_cmp_nlt_f32_e64 s[6:7], s95, v24
	v_mfma_f32_16x16x32_bf16 v[18:21], v[44:47], v[6:9], v[18:21]
	s_and_saveexec_b64 s[46:47], vcc
	s_xor_b64 s[46:47], exec, s[46:47]
	s_cbranch_execz .LBB0_1317
	v_cmp_lt_i32_e64 s[8:9], 0, v39
	s_mov_b64 s[50:51], 0
	s_and_saveexec_b64 s[90:91], s[8:9]
	s_xor_b64 s[8:9], exec, s[90:91]
	v_add_u32_e32 v0, s84, v39
	s_mov_b64 s[50:51], exec
	v_mov_b64_e32 v[22:23], v[0:1]
	s_or_b64 exec, exec, s[8:9]
	s_and_b64 s[8:9], s[50:51], exec

; __device__ __forceinline__ int opaque_tid() { int t = threadIdx.x; asm volatile("" : "+v"(t)); return t; }
; __device__ void attn_item(const Params& p, int layer, int item, int dry) {
;   unsigned char* ws = p.ws;
;   const int tid = opaque_tid(), wid = tid >> 6, lane = tid & 63, r = lane & 15, quad = lane >> 4;
;   bf16_t* cat = (bf16_t*)(ws + O_S + S_CAT);
;   const bf16_t* kv = (const bf16_t*)(ws + O_KV) + layer * 512;
;   const int tile = item >> 2, h = item & 3;
;   const int tok0 = tile * 128;
;   const int seq = tok0 < 32768 ? (tok0 >> 11) : 16 + ((tok0 - 32768) >> 12);
;   bf16_t* Ks = (bf16_t*)smem;
;   bf16_t* Vt = (bf16_t*)(smem + 256 * 72 * 2);
;   const bf16_t* kvs = kv + (size_t)seq * 256 * 1024;
;   for (int i = 0; i < 4; ++i) {
;     int idx = tid + 512 * i;
;     int m = idx >> 3, d0 = (idx & 7) * 8;
;     uint4 uk = *(const uint4*)(kvs + (size_t)m * 1024 + h * 64 + d0);
;     *(uint4*)(Ks + m * 72 + d0) = uk;
;     uint4 uv = *(const uint4*)(kvs + (size_t)m * 1024 + 256 + h * 64 + d0);
;     unsigned uu[4] = {uv.x, uv.y, uv.z, uv.w};
;     for (int j = 0; j < 8; ++j) Vt[(d0 + j) * 264 + m] = (bf16_t)((j & 1) ? (uu[j >> 1] >> 16) : (uu[j >> 1] & 0xffff));
;   }
;   __syncthreads();
;   const int t = tok0 + wid * 16 + r;
;   bf16_t* qp = cat + (size_t)t * 1024 + 768 + h * 64;
;   bf16x8 qf[2];
;   qf[0] = *(const bf16x8*)(qp + quad * 8);
;   qf[1] = *(const bf16x8*)(qp + 32 + quad * 8);
.LBB0_1348:
	s_and_b64 vcc, exec, s[4:5]
	s_cbranch_vccz .LBB0_1365
	s_lshl_b32 s4, s27, 5
	s_and_b32 s6, s4, 0xffffff80
	s_addk_i32 s4, 0x8000
	s_lshr_b32 s4, s4, 12
	s_ashr_i32 s5, s27, 6
	s_add_i32 s4, s4, 16
	s_cmp_lt_i32 s6, 0x8000
	v_mov_b32_e32 v44, v208
	s_cselect_b32 s4, s5, s4
	s_ashr_i32 s5, s4, 31
	v_add_u32_e32 v10, 0x200, v44
	v_add_u32_e32 v18, 0x400, v44
	v_add_u32_e32 v26, 0x600, v44
	s_lshl_b64 s[4:5], s[4:5], 19
	v_ashrrev_i32_e32 v34, 3, v44
	v_ashrrev_i32_e32 v36, 3, v10
	v_ashrrev_i32_e32 v38, 3, v18
	v_ashrrev_i32_e32 v40, 3, v26
	s_add_u32 s4, s77, s4
	v_ashrrev_i32_e32 v35, 31, v34
	v_ashrrev_i32_e32 v37, 31, v36
	v_ashrrev_i32_e32 v39, 31, v38
	v_ashrrev_i32_e32 v41, 31, v40
	s_addc_u32 s5, s78, s5
	v_lshlrev_b32_e32 v0, 3, v44
	v_lshlrev_b64 v[2:3], 11, v[34:35]
	s_lshl_b32 s7, s27, 7
	v_lshlrev_b64 v[10:11], 11, v[36:37]
	v_lshlrev_b64 v[18:19], 11, v[38:39]
	v_lshlrev_b64 v[26:27], 11, v[40:41]
	v_and_b32_e32 v42, 56, v0
	v_lshl_add_u64 v[2:3], s[4:5], 0, v[2:3]
	s_and_b32 s66, s7, 0x180
	v_lshl_add_u64 v[10:11], s[4:5], 0, v[10:11]
	v_lshl_add_u64 v[18:19], s[4:5], 0, v[18:19]
	v_lshl_add_u64 v[26:27], s[4:5], 0, v[26:27]
	v_lshlrev_b32_e32 v0, 1, v42
	v_lshl_add_u64 v[2:3], v[2:3], 0, s[66:67]
	v_lshl_add_u64 v[10:11], v[10:11], 0, s[66:67]
	v_lshl_add_u64 v[18:19], v[18:19], 0, s[66:67]
	v_lshl_add_u64 v[26:27], v[26:27], 0, s[66:67]
	v_lshl_add_u64 v[6:7], v[2:3], 0, v[0:1]
	v_lshl_add_u64 v[14:15], v[10:11], 0, v[0:1]
	v_lshl_add_u64 v[22:23], v[18:19], 0, v[0:1]
	v_lshl_add_u64 v[30:31], v[26:27], 0, v[0:1]
	global_load_dwordx4 v[2:5], v[6:7], off
	s_nop 0
	global_load_dwordx4 v[6:9], v[6:7], off offset:512
	s_nop 0
	global_load_dwordx4 v[10:13], v[14:15], off
	s_nop 0
	global_load_dwordx4 v[14:17], v[14:15], off offset:512
	s_nop 0
	global_load_dwordx4 v[18:21], v[22:23], off
	s_nop 0
	global_load_dwordx4 v[22:25], v[22:23], off offset:512
	s_nop 0
	global_load_dwordx4 v[26:29], v[30:31], off
	s_nop 0
	global_load_dwordx4 v[30:33], v[30:31], off offset:512
	s_movk_i32 s7, 0x90
	v_mul_u32_u24_e32 v41, 0x251, v42
	v_mad_u64_u32 v[42:43], s[4:5], v34, s7, v[0:1]
	v_lshl_add_u32 v43, v34, 1, v41
	v_mad_u64_u32 v[34:35], s[4:5], v36, s7, v[0:1]
	v_lshl_add_u32 v35, v36, 1, v41
	v_mad_u64_u32 v[36:37], s[4:5], v38, s7, v[0:1]
	v_lshl_add_u32 v37, v38, 1, v41
	v_mad_u64_u32 v[38:39], s[4:5], v40, s7, v[0:1]
	v_lshl_add_u32 v0, v40, 1, v41
	v_and_b32_e32 v60, 15, v44
	v_bfe_u32 v61, v44, 4, 2
	s_mov_b64 s[4:5], 0xe1a6600
	s_waitcnt vmcnt(7)
	ds_write_b128 v42, v[2:5]
	s_waitcnt vmcnt(6)
	ds_write_b16 v43, v6 offset:36864
	ds_write_b16_d16_hi v43, v6 offset:37456
	ds_write_b16 v43, v7 offset:38048
	ds_write_b16_d16_hi v43, v7 offset:38640
	ds_write_b16 v43, v8 offset:39232
	ds_write_b16_d16_hi v43, v8 offset:39824
	ds_write_b16 v43, v9 offset:40416
	ds_write_b16_d16_hi v43, v9 offset:41008
	s_waitcnt vmcnt(5)
	ds_write_b128 v34, v[10:13]
	s_waitcnt vmcnt(4)
	ds_write_b16 v35, v14 offset:36864
	ds_write_b16_d16_hi v35, v14 offset:37456
	ds_write_b16 v35, v15 offset:38048
	ds_write_b16_d16_hi v35, v15 offset:38640
	ds_write_b16 v35, v16 offset:39232
	ds_write_b16_d16_hi v35, v16 offset:39824
	ds_write_b16 v35, v17 offset:40416
	ds_write_b16_d16_hi v35, v17 offset:41008
	s_waitcnt vmcnt(3)
	ds_write_b128 v36, v[18:21]
	s_waitcnt vmcnt(2)
	ds_write_b16 v37, v22 offset:36864
	ds_write_b16_d16_hi v37, v22 offset:37456
	ds_write_b16 v37, v23 offset:38048
	ds_write_b16_d16_hi v37, v23 offset:38640
	ds_write_b16 v37, v24 offset:39232
	ds_write_b16_d16_hi v37, v24 offset:39824
	ds_write_b16 v37, v25 offset:40416
	ds_write_b16_d16_hi v37, v25 offset:41008
	s_waitcnt vmcnt(1)
	ds_write_b128 v38, v[26:29]
	s_waitcnt vmcnt(0)
	ds_write_b16 v0, v30 offset:36864
	ds_write_b16_d16_hi v0, v30 offset:37456
	ds_write_b16 v0, v31 offset:38048
	ds_write_b16_d16_hi v0, v31 offset:38640
	ds_write_b16 v0, v32 offset:39232
	ds_write_b16_d16_hi v0, v32 offset:39824
	ds_write_b16 v0, v33 offset:40416
	ds_write_b16_d16_hi v0, v33 offset:41008
	v_ashrrev_i32_e32 v0, 2, v44
	v_and_b32_e32 v0, -16, v0
	v_add_u32_e32 v0, s6, v0
	v_or_b32_e32 v2, v0, v60
	v_ashrrev_i32_e32 v3, 31, v2
	v_lshlrev_b64 v[2:3], 11, v[2:3]
	v_lshl_add_u64 v[2:3], s[14:15], 0, v[2:3]
	v_lshl_add_u64 v[2:3], v[2:3], 0, s[66:67]
	v_lshl_add_u64 v[54:55], v[2:3], 0, s[4:5]
	v_lshlrev_b32_e32 v0, 4, v61
	v_lshl_add_u64 v[34:35], v[54:55], 0, v[0:1]
	global_load_dwordx4 v[2:5], v[34:35], off
	global_load_dwordx4 v[56:59], v[34:35], off offset:64
	s_waitcnt lgkmcnt(0)
	s_barrier
; __device__ void attn_item(const Params& p, int layer, int item, int dry) {
;     ...
;   f32x4 s[16];
;   for (int mt = 0; mt < 16; ++mt) {
;     s[mt] = f32x4{0.f, 0.f, 0.f, 0.f};
;     for (int ks = 0; ks < 2; ++ks) {
;       bf16x8 a = *(const bf16x8*)(Ks + (mt * 16 + r) * 72 + ks * 32 + quad * 8);
;       s[mt] = __builtin_amdgcn_mfma_f32_16x16x32_bf16(a, qf[ks], s[mt], 0, 0, 0);
;     }
;   }
;   float mx = -1e30f;
;   for (int mt = 0; mt < 16; ++mt)
;     for (int j = 0; j < 4; ++j) mx = fmaxf(mx, s[mt][j]);
;   mx = fmaxf(mx, __shfl_xor(mx, 16));
;   mx = fmaxf(mx, __shfl_xor(mx, 32));
	v_mad_u32_u24 v98, v60, s7, v0
	ds_read_b128 v[38:41], v98 offset:18432
	ds_read_b128 v[6:9], v98
	ds_read_b128 v[10:13], v98 offset:2304
	ds_read_b128 v[14:17], v98 offset:4608
	ds_read_b128 v[18:21], v98 offset:6912
	ds_read_b128 v[22:25], v98 offset:9216
	ds_read_b128 v[26:29], v98 offset:11520
	ds_read_b128 v[30:33], v98 offset:13824
	ds_read_b128 v[34:37], v98 offset:16128
	s_mov_b32 s4, 0xf149f2ca
	s_waitcnt vmcnt(1) lgkmcnt(8)
	v_mfma_f32_16x16x32_bf16 v[62:65], v[38:41], v[2:5], 0
	ds_read_b128 v[38:41], v98 offset:20736
	s_waitcnt lgkmcnt(0)
	v_mfma_f32_16x16x32_bf16 v[66:69], v[38:41], v[2:5], 0
	ds_read_b128 v[38:41], v98 offset:23040
	s_waitcnt lgkmcnt(0)
	v_mfma_f32_16x16x32_bf16 v[70:73], v[38:41], v[2:5], 0
	ds_read_b128 v[38:41], v98 offset:25344
	s_waitcnt lgkmcnt(0)
	v_mfma_f32_16x16x32_bf16 v[74:77], v[38:41], v[2:5], 0
	ds_read_b128 v[38:41], v98 offset:27648
	s_waitcnt lgkmcnt(0)
	v_mfma_f32_16x16x32_bf16 v[78:81], v[38:41], v[2:5], 0
	ds_read_b128 v[38:41], v98 offset:29952
	s_waitcnt lgkmcnt(0)
	v_mfma_f32_16x16x32_bf16 v[82:85], v[38:41], v[2:5], 0
	ds_read_b128 v[38:41], v98 offset:64
	v_mfma_f32_16x16x32_bf16 v[6:9], v[6:9], v[2:5], 0
	s_waitcnt vmcnt(0) lgkmcnt(0)
	v_mfma_f32_16x16x32_bf16 v[86:89], v[38:41], v[56:59], v[6:9]
	s_nop 5
	ds_read_b128 v[6:9], v98 offset:2368
	v_mfma_f32_16x16x32_bf16 v[10:13], v[10:13], v[2:5], 0
	s_waitcnt lgkmcnt(0)
	v_mfma_f32_16x16x32_bf16 v[90:93], v[6:9], v[56:59], v[10:13]
	ds_read_b128 v[6:9], v98 offset:4672
	v_mfma_f32_16x16x32_bf16 v[14:17], v[14:17], v[2:5], 0
	s_waitcnt lgkmcnt(0)
	v_mfma_f32_16x16x32_bf16 v[94:97], v[6:9], v[56:59], v[14:17]
	ds_read_b128 v[6:9], v98 offset:6976
	v_mfma_f32_16x16x32_bf16 v[18:21], v[18:21], v[2:5], 0
	s_waitcnt lgkmcnt(0)
	v_mfma_f32_16x16x32_bf16 v[50:53], v[6:9], v[56:59], v[18:21]
	ds_read_b128 v[6:9], v98 offset:9280
	v_mfma_f32_16x16x32_bf16 v[22:25], v[22:25], v[2:5], 0
	s_waitcnt lgkmcnt(0)
	v_mfma_f32_16x16x32_bf16 v[46:49], v[6:9], v[56:59], v[22:25]
	ds_read_b128 v[6:9], v98 offset:11584
	v_mfma_f32_16x16x32_bf16 v[26:29], v[26:29], v[2:5], 0
	s_waitcnt lgkmcnt(0)
	v_mfma_f32_16x16x32_bf16 v[42:45], v[6:9], v[56:59], v[26:29]
	ds_read_b128 v[6:9], v98 offset:13888
	v_mfma_f32_16x16x32_bf16 v[30:33], v[30:33], v[2:5], 0
	s_waitcnt lgkmcnt(0)
	v_mfma_f32_16x16x32_bf16 v[38:41], v[6:9], v[56:59], v[30:33]
	ds_read_b128 v[6:9], v98 offset:16192
	v_mfma_f32_16x16x32_bf16 v[34:37], v[34:37], v[2:5], 0
	s_waitcnt lgkmcnt(0)
	v_mfma_f32_16x16x32_bf16 v[34:37], v[6:9], v[56:59], v[34:37]
	ds_read_b128 v[6:9], v98 offset:18496
	s_waitcnt lgkmcnt(0)
	v_mfma_f32_16x16x32_bf16 v[30:33], v[6:9], v[56:59], v[62:65]
	ds_read_b128 v[6:9], v98 offset:20800
	s_nop 1
	ds_read_b128 v[62:65], v98 offset:32320
	s_waitcnt lgkmcnt(1)
	v_mfma_f32_16x16x32_bf16 v[26:29], v[6:9], v[56:59], v[66:69]
	ds_read_b128 v[6:9], v98 offset:23104
	s_waitcnt lgkmcnt(0)
	v_mfma_f32_16x16x32_bf16 v[22:25], v[6:9], v[56:59], v[70:73]
	ds_read_b128 v[6:9], v98 offset:25408
	s_waitcnt lgkmcnt(0)
	v_mfma_f32_16x16x32_bf16 v[18:21], v[6:9], v[56:59], v[74:77]
	ds_read_b128 v[6:9], v98 offset:27712
	s_waitcnt lgkmcnt(0)
	v_mfma_f32_16x16x32_bf16 v[14:17], v[6:9], v[56:59], v[78:81]
	ds_read_b128 v[6:9], v98 offset:30016
	s_waitcnt lgkmcnt(0)
	v_mfma_f32_16x16x32_bf16 v[10:13], v[6:9], v[56:59], v[82:85]
	ds_read_b128 v[6:9], v98 offset:32256
	s_waitcnt lgkmcnt(0)
	v_mfma_f32_16x16x32_bf16 v[6:9], v[6:9], v[2:5], 0
	v_mfma_f32_16x16x32_bf16 v[6:9], v[62:65], v[56:59], v[6:9]
	ds_read_b128 v[62:65], v98 offset:34560
	s_waitcnt lgkmcnt(0)
	v_mfma_f32_16x16x32_bf16 v[2:5], v[62:65], v[2:5], 0
	ds_read_b128 v[62:65], v98 offset:34624
	s_waitcnt lgkmcnt(0)
	v_mfma_f32_16x16x32_bf16 v[2:5], v[62:65], v[56:59], v[2:5]
	v_max3_f32 v56, v86, s4, v87
	v_max3_f32 v56, v56, v88, v89
	v_max3_f32 v56, v56, v90, v91
	v_max3_f32 v56, v56, v92, v93
	v_max3_f32 v56, v56, v94, v95
	v_max3_f32 v56, v56, v96, v97
	v_max3_f32 v56, v56, v50, v51
	v_max3_f32 v56, v56, v52, v53
	v_max3_f32 v56, v56, v46, v47
	v_max3_f32 v56, v56, v48, v49
	v_max3_f32 v56, v56, v42, v43
	v_max3_f32 v56, v56, v44, v45
	v_max3_f32 v56, v56, v38, v39
	v_max3_f32 v56, v56, v40, v41
	v_max3_f32 v56, v56, v34, v35
	v_max3_f32 v56, v56, v36, v37
	v_max3_f32 v56, v56, v30, v31
	v_max3_f32 v56, v56, v32, v33
	v_max3_f32 v56, v56, v26, v27
	v_max3_f32 v56, v56, v28, v29
	v_max3_f32 v56, v56, v22, v23
	v_max3_f32 v56, v56, v24, v25
	v_max3_f32 v56, v56, v18, v19
	v_max3_f32 v56, v56, v20, v21
	v_max3_f32 v56, v56, v14, v15
	v_max3_f32 v56, v56, v16, v17
	v_max3_f32 v56, v56, v10, v11
	v_max3_f32 v56, v56, v12, v13
	v_and_b32_e32 v58, 64, v228
	v_max3_f32 v56, v56, v6, v7
	v_xor_b32_e32 v57, 16, v228
	v_add_u32_e32 v59, 64, v58
	v_max3_f32 v56, v56, v8, v9
	v_cmp_lt_i32_e32 vcc, v57, v59
	v_max3_f32 v56, v56, v2, v3
	v_max3_f32 v56, v56, v4, v5
	v_cndmask_b32_e32 v57, v228, v57, vcc
	v_lshlrev_b32_e32 v58, 2, v57
	ds_bpermute_b32 v57, v58, v56
	s_movk_i32 s4, 0x210
	s_waitcnt lgkmcnt(0)
	v_max_f32_e32 v57, v57, v57
	v_max_f32_e32 v62, v56, v57
	v_xor_b32_e32 v56, 32, v228
	v_cmp_lt_i32_e32 vcc, v56, v59
	s_nop 1
	v_cndmask_b32_e32 v56, v228, v56, vcc
	v_lshlrev_b32_e32 v57, 2, v56
	ds_bpermute_b32 v59, v57, v62
	v_lshlrev_b32_e32 v56, 3, v61
	v_sub_u32_e32 v0, v0, v56
	s_andn2_b64 vcc, exec, s[24:25]
	s_waitcnt lgkmcnt(0)
; __device__ void attn_item(const Params& p, int layer, int item, int dry) {
;     ...
;   float sum = 0.f;
;   for (int mt = 0; mt < 16; ++mt)
;     for (int j = 0; j < 4; ++j) {
;       float e = __expf((s[mt][j] - mx) * 0.125f);
;       s[mt][j] = e;
;       sum += e;
;     }
	v_max_f32_e32 v59, v59, v59
	v_max_f32_e32 v59, v62, v59
	v_sub_f32_e32 v61, v86, v59
	v_mul_f32_e32 v61, 0x3e000000, v61
	v_mul_f32_e32 v61, 0x3fb8aa3b, v61
	v_exp_f32_e32 v65, v61
	v_sub_f32_e32 v61, v87, v59
	v_mul_f32_e32 v61, 0x3e000000, v61
	v_sub_f32_e32 v62, v90, v59
	v_mul_f32_e32 v61, 0x3fb8aa3b, v61
	v_mul_f32_e32 v62, 0x3e000000, v62
	v_exp_f32_e32 v66, v61
	v_sub_f32_e32 v61, v88, v59
	v_mul_f32_e32 v62, 0x3fb8aa3b, v62
	v_mul_f32_e32 v61, 0x3e000000, v61
	v_exp_f32_e32 v68, v62
	v_sub_f32_e32 v62, v91, v59
	v_mul_f32_e32 v61, 0x3fb8aa3b, v61
	v_mul_f32_e32 v62, 0x3e000000, v62
	v_exp_f32_e32 v67, v61
	v_sub_f32_e32 v61, v89, v59
	v_mul_f32_e32 v62, 0x3fb8aa3b, v62
	v_mul_f32_e32 v61, 0x3e000000, v61
	v_exp_f32_e32 v75, v62
	v_sub_f32_e32 v62, v92, v59
	v_mul_f32_e32 v61, 0x3fb8aa3b, v61
	v_mul_f32_e32 v62, 0x3e000000, v62
	v_exp_f32_e32 v74, v61
	v_mul_f32_e32 v62, 0x3fb8aa3b, v62
	v_add_f32_e32 v61, 0, v65
	v_exp_f32_e32 v69, v62
	v_sub_f32_e32 v62, v93, v59
	v_add_f32_e32 v61, v66, v61
	v_mul_f32_e32 v62, 0x3e000000, v62
	v_add_f32_e32 v61, v67, v61
	v_mul_f32_e32 v62, 0x3fb8aa3b, v62
	v_add_f32_e32 v61, v74, v61
	v_exp_f32_e32 v70, v62
	v_add_f32_e32 v61, v68, v61
	v_add_f32_e32 v61, v75, v61
	v_sub_f32_e32 v50, v50, v59
	v_add_f32_e32 v61, v69, v61
	v_mul_f32_e32 v50, 0x3e000000, v50
	v_add_f32_e32 v71, v70, v61
	v_sub_f32_e32 v61, v94, v59
	v_mul_f32_e32 v50, 0x3fb8aa3b, v50
	v_mul_f32_e32 v61, 0x3e000000, v61
	v_sub_f32_e32 v62, v95, v59
	v_exp_f32_e32 v90, v50
	v_sub_f32_e32 v50, v51, v59
	v_mul_f32_e32 v61, 0x3fb8aa3b, v61
	v_mul_f32_e32 v62, 0x3e000000, v62
	v_sub_f32_e32 v63, v96, v59
	v_mul_f32_e32 v50, 0x3e000000, v50
	v_exp_f32_e32 v61, v61
	v_mul_f32_e32 v62, 0x3fb8aa3b, v62
	v_mul_f32_e32 v63, 0x3e000000, v63
	v_sub_f32_e32 v64, v97, v59
	v_mul_f32_e32 v50, 0x3fb8aa3b, v50
	v_exp_f32_e32 v62, v62
	v_mul_f32_e32 v63, 0x3fb8aa3b, v63
	v_mul_f32_e32 v64, 0x3e000000, v64
	v_exp_f32_e32 v91, v50
	v_sub_f32_e32 v50, v52, v59
	v_exp_f32_e32 v63, v63
	v_mul_f32_e32 v64, 0x3fb8aa3b, v64
	v_mul_f32_e32 v50, 0x3e000000, v50
	v_exp_f32_e32 v64, v64
	v_mul_f32_e32 v50, 0x3fb8aa3b, v50
	v_add_f32_e32 v71, v61, v71
	v_exp_f32_e32 v92, v50
	v_sub_f32_e32 v50, v53, v59
	v_add_f32_e32 v71, v62, v71
	v_mul_f32_e32 v50, 0x3e000000, v50
	v_sub_f32_e32 v46, v46, v59
	v_add_f32_e32 v71, v63, v71
	v_mul_f32_e32 v50, 0x3fb8aa3b, v50
	v_mul_f32_e32 v46, 0x3e000000, v46
	v_sub_f32_e32 v47, v47, v59
	v_add_f32_e32 v71, v64, v71
	v_exp_f32_e32 v53, v50
	v_mul_f32_e32 v46, 0x3fb8aa3b, v46
	v_mul_f32_e32 v47, 0x3e000000, v47
	v_sub_f32_e32 v48, v48, v59
	v_add_f32_e32 v50, v90, v71
	v_exp_f32_e32 v46, v46
	v_mul_f32_e32 v47, 0x3fb8aa3b, v47
	v_mul_f32_e32 v48, 0x3e000000, v48
	v_sub_f32_e32 v49, v49, v59
	v_add_f32_e32 v50, v91, v50
	v_exp_f32_e32 v47, v47
	v_mul_f32_e32 v48, 0x3fb8aa3b, v48
	v_mul_f32_e32 v49, 0x3e000000, v49
	v_add_f32_e32 v50, v92, v50
	v_exp_f32_e32 v48, v48
	v_mul_f32_e32 v49, 0x3fb8aa3b, v49
	v_add_f32_e32 v50, v53, v50
	v_exp_f32_e32 v49, v49
	v_add_f32_e32 v50, v46, v50
	v_sub_f32_e32 v42, v42, v59
	v_add_f32_e32 v50, v47, v50
	v_mul_f32_e32 v42, 0x3e000000, v42
	v_add_f32_e32 v50, v48, v50
	v_mul_f32_e32 v42, 0x3fb8aa3b, v42
	v_add_f32_e32 v71, v49, v50
	v_exp_f32_e32 v50, v42
	v_sub_f32_e32 v42, v43, v59
	v_mul_f32_e32 v42, 0x3e000000, v42
	v_mul_f32_e32 v42, 0x3fb8aa3b, v42
	v_exp_f32_e32 v51, v42
	v_sub_f32_e32 v42, v44, v59
	v_mul_f32_e32 v42, 0x3e000000, v42
	v_mul_f32_e32 v42, 0x3fb8aa3b, v42
	v_exp_f32_e32 v52, v42
	v_sub_f32_e32 v42, v45, v59
	v_mul_f32_e32 v42, 0x3e000000, v42
	v_sub_f32_e32 v38, v38, v59
	v_mul_f32_e32 v42, 0x3fb8aa3b, v42
	v_mul_f32_e32 v38, 0x3e000000, v38
	v_sub_f32_e32 v39, v39, v59
	v_exp_f32_e32 v45, v42
	v_mul_f32_e32 v38, 0x3fb8aa3b, v38
	v_mul_f32_e32 v39, 0x3e000000, v39
	v_sub_f32_e32 v40, v40, v59
	v_add_f32_e32 v42, v50, v71
	v_exp_f32_e32 v38, v38
	v_mul_f32_e32 v39, 0x3fb8aa3b, v39
	v_mul_f32_e32 v40, 0x3e000000, v40
	v_sub_f32_e32 v41, v41, v59
	v_add_f32_e32 v42, v51, v42
	v_exp_f32_e32 v39, v39
	v_mul_f32_e32 v40, 0x3fb8aa3b, v40
	v_mul_f32_e32 v41, 0x3e000000, v41
	v_add_f32_e32 v42, v52, v42
	v_exp_f32_e32 v40, v40
	v_mul_f32_e32 v41, 0x3fb8aa3b, v41
	v_add_f32_e32 v42, v45, v42
	v_exp_f32_e32 v41, v41
	v_add_f32_e32 v42, v38, v42
	v_sub_f32_e32 v34, v34, v59
	v_add_f32_e32 v42, v39, v42
	v_mul_f32_e32 v34, 0x3e000000, v34
	v_add_f32_e32 v42, v40, v42
	v_mul_f32_e32 v34, 0x3fb8aa3b, v34
	v_add_f32_e32 v71, v41, v42
	v_exp_f32_e32 v42, v34
	v_sub_f32_e32 v34, v35, v59
	v_mul_f32_e32 v34, 0x3e000000, v34
	v_mul_f32_e32 v34, 0x3fb8aa3b, v34
	v_exp_f32_e32 v43, v34
	v_sub_f32_e32 v34, v36, v59
	v_mul_f32_e32 v34, 0x3e000000, v34
	v_mul_f32_e32 v34, 0x3fb8aa3b, v34
	v_exp_f32_e32 v44, v34
	v_sub_f32_e32 v34, v37, v59
	v_mul_f32_e32 v34, 0x3e000000, v34
	v_sub_f32_e32 v30, v30, v59
	v_mul_f32_e32 v34, 0x3fb8aa3b, v34
	v_mul_f32_e32 v30, 0x3e000000, v30
	v_sub_f32_e32 v31, v31, v59
	v_exp_f32_e32 v37, v34
	v_mul_f32_e32 v30, 0x3fb8aa3b, v30
	v_mul_f32_e32 v31, 0x3e000000, v31
	v_sub_f32_e32 v32, v32, v59
	v_add_f32_e32 v34, v42, v71
	v_exp_f32_e32 v30, v30
	v_mul_f32_e32 v31, 0x3fb8aa3b, v31
	v_mul_f32_e32 v32, 0x3e000000, v32
	v_sub_f32_e32 v33, v33, v59
	v_add_f32_e32 v34, v43, v34
	v_exp_f32_e32 v31, v31
	v_mul_f32_e32 v32, 0x3fb8aa3b, v32
	v_mul_f32_e32 v33, 0x3e000000, v33
	v_add_f32_e32 v34, v44, v34
	v_exp_f32_e32 v32, v32
	v_mul_f32_e32 v33, 0x3fb8aa3b, v33
	v_add_f32_e32 v34, v37, v34
	v_exp_f32_e32 v33, v33
	v_add_f32_e32 v34, v30, v34
	v_sub_f32_e32 v26, v26, v59
	v_add_f32_e32 v34, v31, v34
	v_mul_f32_e32 v26, 0x3e000000, v26
	v_add_f32_e32 v34, v32, v34
; __device__ __forceinline__ unsigned short f2bf(float f) { return (unsigned short)(pack2(f, 0.f) & 0xffffu); }
; __device__ void attn_item(const Params& p, int layer, int item, int dry) {
;     ...
;   for (int mt = 0; mt < 16; ++mt)
;     for (int j = 0; j < 4; ++j) {
;       float e = __expf((s[mt][j] - mx) * 0.125f);
;       s[mt][j] = e;
;       sum += e;
;     }
;   sum += __shfl_xor(sum, 16);
;   sum += __shfl_xor(sum, 32);
;   const float inv = 1.f / sum;
;   f32x4 o[4] = {};
;   for (int ks = 0; ks < 8; ++ks) {
;     bf16x8 pb;
;     for (int j = 0; j < 4; ++j) {
;       pb[j] = (short)f2bf(s[2 * ks][j]);
;       pb[4 + j] = (short)f2bf(s[2 * ks + 1][j]);
;     }
;     for (int dt = 0; dt < 4; ++dt) {
;       const bf16_t* vp = Vt + (dt * 16 + r) * 264 + ks * 32 + quad * 4;
;       uint2 v0 = *(const uint2*)vp, v1 = *(const uint2*)(vp + 16);
;       bf16x8 av;
;       av[0] = (short)(v0.x & 0xffff); av[1] = (short)(v0.x >> 16); av[2] = (short)(v0.y & 0xffff); av[3] = (short)(v0.y >> 16);
;       av[4] = (short)(v1.x & 0xffff); av[5] = (short)(v1.x >> 16); av[6] = (short)(v1.y & 0xffff); av[7] = (short)(v1.y >> 16);
;       o[dt] = __builtin_amdgcn_mfma_f32_16x16x32_bf16(av, pb, o[dt], 0, 0, 0);
	v_mul_f32_e32 v26, 0x3fb8aa3b, v26
	v_add_f32_e32 v71, v33, v34
	v_exp_f32_e32 v34, v26
	v_sub_f32_e32 v26, v27, v59
	v_mul_f32_e32 v26, 0x3e000000, v26
	v_mul_f32_e32 v26, 0x3fb8aa3b, v26
	v_exp_f32_e32 v35, v26
	v_sub_f32_e32 v26, v28, v59
	v_mul_f32_e32 v26, 0x3e000000, v26
	v_mul_f32_e32 v26, 0x3fb8aa3b, v26
	v_exp_f32_e32 v28, v26
	v_sub_f32_e32 v26, v29, v59
	v_mul_f32_e32 v26, 0x3e000000, v26
	v_sub_f32_e32 v22, v22, v59
	v_mul_f32_e32 v26, 0x3fb8aa3b, v26
	v_mul_f32_e32 v22, 0x3e000000, v22
	v_sub_f32_e32 v23, v23, v59
	v_exp_f32_e32 v36, v26
	v_mul_f32_e32 v22, 0x3fb8aa3b, v22
	v_mul_f32_e32 v23, 0x3e000000, v23
	v_sub_f32_e32 v24, v24, v59
	v_add_f32_e32 v26, v34, v71
	v_exp_f32_e32 v22, v22
	v_mul_f32_e32 v23, 0x3fb8aa3b, v23
	v_mul_f32_e32 v24, 0x3e000000, v24
	v_sub_f32_e32 v25, v25, v59
	v_add_f32_e32 v26, v35, v26
	v_exp_f32_e32 v23, v23
	v_mul_f32_e32 v24, 0x3fb8aa3b, v24
	v_mul_f32_e32 v25, 0x3e000000, v25
	v_add_f32_e32 v26, v28, v26
	v_exp_f32_e32 v24, v24
	v_mul_f32_e32 v25, 0x3fb8aa3b, v25
	v_add_f32_e32 v26, v36, v26
	v_exp_f32_e32 v25, v25
	v_add_f32_e32 v26, v22, v26
	v_sub_f32_e32 v18, v18, v59
	v_sub_f32_e32 v20, v20, v59
	v_add_f32_e32 v26, v23, v26
	v_mul_f32_e32 v18, 0x3e000000, v18
	v_sub_f32_e32 v19, v19, v59
	v_mul_f32_e32 v20, 0x3e000000, v20
	v_add_f32_e32 v26, v24, v26
	v_mul_f32_e32 v18, 0x3fb8aa3b, v18
	v_mul_f32_e32 v19, 0x3e000000, v19
	v_mul_f32_e32 v20, 0x3fb8aa3b, v20
	v_add_f32_e32 v29, v25, v26
	v_exp_f32_e32 v18, v18
	v_mul_f32_e32 v19, 0x3fb8aa3b, v19
	v_exp_f32_e32 v26, v20
	v_sub_f32_e32 v20, v21, v59
	v_exp_f32_e32 v19, v19
	v_mul_f32_e32 v20, 0x3e000000, v20
	v_sub_f32_e32 v14, v14, v59
	v_mul_f32_e32 v20, 0x3fb8aa3b, v20
	v_mul_f32_e32 v14, 0x3e000000, v14
	v_sub_f32_e32 v15, v15, v59
	v_exp_f32_e32 v27, v20
	v_mul_f32_e32 v14, 0x3fb8aa3b, v14
	v_mul_f32_e32 v15, 0x3e000000, v15
	v_sub_f32_e32 v16, v16, v59
	v_add_f32_e32 v20, v18, v29
	v_exp_f32_e32 v14, v14
	v_mul_f32_e32 v15, 0x3fb8aa3b, v15
	v_mul_f32_e32 v16, 0x3e000000, v16
	v_sub_f32_e32 v17, v17, v59
	v_add_f32_e32 v20, v19, v20
	v_exp_f32_e32 v15, v15
	v_mul_f32_e32 v16, 0x3fb8aa3b, v16
	v_mul_f32_e32 v17, 0x3e000000, v17
	v_sub_f32_e32 v10, v10, v59
	v_add_f32_e32 v20, v26, v20
	v_exp_f32_e32 v16, v16
	v_mul_f32_e32 v17, 0x3fb8aa3b, v17
	v_mul_f32_e32 v10, 0x3e000000, v10
	v_sub_f32_e32 v11, v11, v59
	v_add_f32_e32 v20, v27, v20
	v_exp_f32_e32 v17, v17
	v_mul_f32_e32 v10, 0x3fb8aa3b, v10
	v_mul_f32_e32 v11, 0x3e000000, v11
	v_sub_f32_e32 v12, v12, v59
	v_add_f32_e32 v20, v14, v20
	v_exp_f32_e32 v10, v10
	v_mul_f32_e32 v11, 0x3fb8aa3b, v11
	v_mul_f32_e32 v12, 0x3e000000, v12
	v_sub_f32_e32 v13, v13, v59
	v_add_f32_e32 v20, v15, v20
	v_exp_f32_e32 v11, v11
	v_mul_f32_e32 v12, 0x3fb8aa3b, v12
	v_mul_f32_e32 v13, 0x3e000000, v13
	v_add_f32_e32 v20, v16, v20
	v_exp_f32_e32 v12, v12
	v_mul_f32_e32 v13, 0x3fb8aa3b, v13
	v_add_f32_e32 v20, v17, v20
	v_exp_f32_e32 v13, v13
	v_add_f32_e32 v20, v10, v20
	v_add_f32_e32 v20, v11, v20
	v_add_f32_e32 v20, v12, v20
	v_add_f32_e32 v86, v13, v20
	v_sub_f32_e32 v7, v7, v59
	v_mul_u32_u24_e32 v176, 0x250, v60
	v_lshrrev_b32_e32 v177, 3, v60
	v_add_u32_e32 v20, v176, v0
	v_lshl_add_u32 v20, v177, 3, v20
	v_mul_f32_e32 v29, 0x3e000000, v7
	v_add_u32_e32 v21, 0x9000, v20
	v_add_u32_e32 v7, 0xb410, v20
	v_add_u32_e32 v0, 0xd820, v20
	v_add_u32_e32 v20, 0xfc30, v20
	v_cvt_pk_bf16_f32 v69, v69, v70
	ds_read2_b64 v[70:73], v21 offset1:4
	v_cvt_pk_bf16_f32 v68, v68, v75
	v_cvt_pk_bf16_f32 v67, v67, v74
	ds_read2_b64 v[74:77], v7 offset0:32 offset1:36
	ds_read2_b64 v[78:81], v0 offset0:64 offset1:68
	ds_read2_b64 v[82:85], v20 offset0:96 offset1:100
	v_sub_f32_e32 v6, v6, v59
	v_mul_f32_e32 v6, 0x3e000000, v6
	v_mul_f32_e32 v6, 0x3fb8aa3b, v6
	v_exp_f32_e32 v6, v6
	s_waitcnt lgkmcnt(3)
	v_bfi_b32 v72, s65, v72, v72
	s_waitcnt lgkmcnt(2)
	v_bfi_b32 v76, s65, v76, v76
	s_waitcnt lgkmcnt(1)
	v_bfi_b32 v80, s65, v80, v80
	v_mul_f32_e32 v29, 0x3fb8aa3b, v29
	s_waitcnt lgkmcnt(0)
	v_bfi_b32 v84, s65, v84, v84
	v_exp_f32_e32 v29, v29
	v_cvt_pk_bf16_f32 v66, v65, v66
	v_add_f32_e32 v60, v6, v86
	ds_read2_b64 v[86:89], v21 offset0:8 offset1:12
	v_mfma_f32_16x16x32_bf16 v[70:73], v[70:73], v[66:69], 0
	v_add_f32_e32 v94, v29, v60
	v_sub_f32_e32 v8, v8, v59
	v_mul_f32_e32 v8, 0x3e000000, v8
	v_mfma_f32_16x16x32_bf16 v[74:77], v[74:77], v[66:69], 0
	s_waitcnt lgkmcnt(0)
	v_bfi_b32 v88, s65, v88, v88
	v_mul_f32_e32 v8, 0x3fb8aa3b, v8
	v_sub_f32_e32 v2, v2, v59
	v_mfma_f32_16x16x32_bf16 v[78:81], v[78:81], v[66:69], 0
	v_mul_f32_e32 v2, 0x3e000000, v2
	v_mul_f32_e32 v2, 0x3fb8aa3b, v2
	v_cvt_pk_bf16_f32 v27, v26, v27
	v_mfma_f32_16x16x32_bf16 v[66:69], v[82:85], v[66:69], 0
	v_cvt_pk_bf16_f32 v83, v63, v64
	v_cvt_pk_bf16_f32 v82, v61, v62
	ds_read2_b64 v[60:63], v0 offset0:72 offset1:76
	v_cvt_pk_bf16_f32 v85, v92, v53
	v_cvt_pk_bf16_f32 v84, v90, v91
	ds_read2_b64 v[90:93], v7 offset0:40 offset1:44
	v_cvt_pk_bf16_f32 v53, v52, v45
	s_waitcnt lgkmcnt(1)
	v_bfi_b32 v62, s65, v62, v62
	v_mfma_f32_16x16x32_bf16 v[70:73], v[86:89], v[82:85], v[70:73]
	ds_read2_b64 v[86:89], v20 offset0:104 offset1:108
	v_cvt_pk_bf16_f32 v52, v50, v51
	v_cvt_pk_bf16_f32 v51, v48, v49
	v_mfma_f32_16x16x32_bf16 v[60:63], v[60:63], v[82:85], v[78:81]
	v_cvt_pk_bf16_f32 v50, v46, v47
	ds_read2_b64 v[46:49], v0 offset0:80 offset1:84
	s_waitcnt lgkmcnt(2)
	v_bfi_b32 v92, s65, v92, v92
	ds_read2_b64 v[78:81], v21 offset0:16 offset1:20
	s_waitcnt lgkmcnt(2)
	v_bfi_b32 v88, s65, v88, v88
	v_mfma_f32_16x16x32_bf16 v[74:77], v[90:93], v[82:85], v[74:77]
	s_waitcnt lgkmcnt(0)
; __device__ __forceinline__ unsigned short f2bf(float f) { return (unsigned short)(pack2(f, 0.f) & 0xffffu); }
; __device__ void attn_item(const Params& p, int layer, int item, int dry) {
;     ...
;   for (int ks = 0; ks < 8; ++ks) {
;     bf16x8 pb;
;     for (int j = 0; j < 4; ++j) {
;       pb[j] = (short)f2bf(s[2 * ks][j]);
;       pb[4 + j] = (short)f2bf(s[2 * ks + 1][j]);
;     }
;     for (int dt = 0; dt < 4; ++dt) {
;       const bf16_t* vp = Vt + (dt * 16 + r) * 264 + ks * 32 + quad * 4;
;       uint2 v0 = *(const uint2*)vp, v1 = *(const uint2*)(vp + 16);
;       bf16x8 av;
;       av[0] = (short)(v0.x & 0xffff); av[1] = (short)(v0.x >> 16); av[2] = (short)(v0.y & 0xffff); av[3] = (short)(v0.y >> 16);
;       av[4] = (short)(v1.x & 0xffff); av[5] = (short)(v1.x >> 16); av[6] = (short)(v1.y & 0xffff); av[7] = (short)(v1.y >> 16);
;       o[dt] = __builtin_amdgcn_mfma_f32_16x16x32_bf16(av, pb, o[dt], 0, 0, 0);
;     }
;   }
;   for (int dt = 0; dt < 4; ++dt) {
;     uint2 ov;
;     ov.x = pack2(o[dt][0] * inv, o[dt][1] * inv);
;     ov.y = pack2(o[dt][2] * inv, o[dt][3] * inv);
;     if (!dry) *(uint2*)(qp + dt * 16 + quad * 4) = ov;
;   }
	v_bfi_b32 v80, s65, v80, v80
	v_bfi_b32 v48, s65, v48, v48
	v_cvt_pk_bf16_f32 v45, v44, v37
	v_mfma_f32_16x16x32_bf16 v[64:67], v[86:89], v[82:85], v[66:69]
	ds_read2_b64 v[82:85], v7 offset0:48 offset1:52
	v_cvt_pk_bf16_f32 v44, v42, v43
	v_cvt_pk_bf16_f32 v43, v40, v41
	v_mfma_f32_16x16x32_bf16 v[68:71], v[78:81], v[50:53], v[70:73]
	ds_read2_b64 v[78:81], v20 offset0:112 offset1:116
	v_cvt_pk_bf16_f32 v42, v38, v39
	ds_read2_b64 v[38:41], v0 offset0:88 offset1:92
	v_mfma_f32_16x16x32_bf16 v[46:49], v[46:49], v[50:53], v[60:63]
	s_waitcnt lgkmcnt(2)
	v_bfi_b32 v84, s65, v84, v84
	s_waitcnt lgkmcnt(1)
	v_bfi_b32 v80, s65, v80, v80
	v_cvt_pk_bf16_f32 v37, v28, v36
	ds_read2_b64 v[60:63], v21 offset0:24 offset1:28
	s_waitcnt lgkmcnt(1)
	v_bfi_b32 v40, s65, v40, v40
	v_mfma_f32_16x16x32_bf16 v[72:75], v[82:85], v[50:53], v[74:77]
	v_cvt_pk_bf16_f32 v36, v34, v35
	v_cvt_pk_bf16_f32 v35, v32, v33
	s_waitcnt lgkmcnt(0)
	v_bfi_b32 v62, s65, v62, v62
	v_mfma_f32_16x16x32_bf16 v[50:53], v[78:81], v[50:53], v[64:67]
	v_cvt_pk_bf16_f32 v34, v30, v31
	ds_read2_b64 v[30:33], v0 offset0:96 offset1:100
	v_exp_f32_e32 v90, v8
	ds_read2_b64 v[64:67], v7 offset0:56 offset1:60
	v_mfma_f32_16x16x32_bf16 v[60:63], v[60:63], v[42:45], v[68:71]
	v_sub_f32_e32 v8, v9, v59
	s_waitcnt lgkmcnt(1)
	v_bfi_b32 v32, s65, v32, v32
	v_mul_f32_e32 v8, 0x3e000000, v8
	ds_read2_b64 v[68:71], v20 offset0:120 offset1:124
	v_mfma_f32_16x16x32_bf16 v[38:41], v[38:41], v[42:45], v[46:49]
	s_waitcnt lgkmcnt(1)
	v_bfi_b32 v66, s65, v66, v66
	v_mul_f32_e32 v8, 0x3fb8aa3b, v8
	v_exp_f32_e32 v9, v2
	ds_read2_b64 v[46:49], v21 offset0:32 offset1:36
	s_waitcnt lgkmcnt(1)
	v_bfi_b32 v70, s65, v70, v70
	v_mfma_f32_16x16x32_bf16 v[64:67], v[64:67], v[42:45], v[72:75]
	v_sub_f32_e32 v2, v3, v59
	v_exp_f32_e32 v76, v8
	s_waitcnt lgkmcnt(0)
	v_bfi_b32 v48, s65, v48, v48
	v_mfma_f32_16x16x32_bf16 v[42:45], v[68:71], v[42:45], v[50:53]
	v_mul_f32_e32 v2, 0x3e000000, v2
	v_mul_f32_e32 v2, 0x3fb8aa3b, v2
	v_exp_f32_e32 v28, v2
	ds_read2_b64 v[50:53], v7 offset0:64 offset1:68
	v_mfma_f32_16x16x32_bf16 v[46:49], v[46:49], v[34:37], v[60:63]
	v_add_f32_e32 v8, v90, v94
	v_add_f32_e32 v8, v76, v8
	v_add_f32_e32 v2, v9, v8
	ds_read2_b64 v[60:63], v20 offset0:128 offset1:132
	v_mfma_f32_16x16x32_bf16 v[30:33], v[30:33], v[34:37], v[38:41]
	s_waitcnt lgkmcnt(1)
	v_bfi_b32 v52, s65, v52, v52
	v_add_f32_e32 v8, v28, v2
	v_sub_f32_e32 v2, v4, v59
	ds_read2_b64 v[38:41], v21 offset0:40 offset1:44
	s_waitcnt lgkmcnt(1)
	v_bfi_b32 v62, s65, v62, v62
	v_mfma_f32_16x16x32_bf16 v[50:53], v[50:53], v[34:37], v[64:67]
	v_mul_f32_e32 v2, 0x3e000000, v2
	v_mul_f32_e32 v2, 0x3fb8aa3b, v2
	s_waitcnt lgkmcnt(0)
	v_bfi_b32 v40, s65, v40, v40
	v_mfma_f32_16x16x32_bf16 v[34:37], v[60:63], v[34:37], v[42:45]
	ds_read2_b64 v[60:63], v0 offset0:104 offset1:108
	v_cvt_pk_bf16_f32 v26, v18, v19
	v_cvt_pk_bf16_f32 v25, v24, v25
	v_cvt_pk_bf16_f32 v24, v22, v23
	v_exp_f32_e32 v18, v2
	v_sub_f32_e32 v19, v5, v59
	ds_read2_b64 v[2:5], v21 offset0:48 offset1:52
	ds_read2_b64 v[42:45], v7 offset0:72 offset1:76
	v_mfma_f32_16x16x32_bf16 v[38:41], v[38:41], v[24:27], v[46:49]
	v_cvt_pk_bf16_f32 v13, v12, v13
	v_cvt_pk_bf16_f32 v12, v10, v11
	v_cvt_pk_bf16_f32 v11, v16, v17
	ds_read2_b64 v[46:49], v20 offset0:136 offset1:140
	v_cvt_pk_bf16_f32 v10, v14, v15
	ds_read2_b64 v[14:17], v0 offset0:112 offset1:116
	s_waitcnt lgkmcnt(4)
	v_bfi_b32 v62, s65, v62, v62
	s_waitcnt lgkmcnt(3)
	v_bfi_b32 v4, s65, v4, v4
	s_waitcnt lgkmcnt(2)
	v_bfi_b32 v44, s65, v44, v44
	s_waitcnt lgkmcnt(1)
	v_bfi_b32 v48, s65, v48, v48
	s_waitcnt lgkmcnt(0)
	v_bfi_b32 v16, s65, v16, v16
	v_mfma_f32_16x16x32_bf16 v[30:33], v[60:63], v[24:27], v[30:33]
	v_mul_f32_e32 v19, 0x3e000000, v19
	v_mul_f32_e32 v19, 0x3fb8aa3b, v19
	v_exp_f32_e32 v19, v19
	v_mfma_f32_16x16x32_bf16 v[2:5], v[2:5], v[10:13], v[38:41]
	v_add_f32_e32 v8, v18, v8
	s_nop 1
	ds_read2_b64 v[38:41], v20 offset0:144 offset1:148
	v_mfma_f32_16x16x32_bf16 v[42:45], v[42:45], v[24:27], v[50:53]
	s_waitcnt lgkmcnt(0)
	v_bfi_b32 v40, s65, v40, v40
	v_mfma_f32_16x16x32_bf16 v[22:25], v[46:49], v[24:27], v[34:37]
	s_nop 2
	ds_read2_b64 v[34:37], v7 offset0:80 offset1:84
	v_mfma_f32_16x16x32_bf16 v[14:17], v[14:17], v[10:13], v[30:33]
	s_waitcnt lgkmcnt(0)
	v_bfi_b32 v36, s65, v36, v36
	s_nop 0
	ds_read2_b64 v[30:33], v21 offset0:56 offset1:60
	v_mfma_f32_16x16x32_bf16 v[22:25], v[38:41], v[10:13], v[22:25]
	v_cvt_pk_bf16_f32 v41, v18, v19
	v_cvt_pk_bf16_f32 v40, v9, v28
	v_cvt_pk_bf16_f32 v39, v90, v76
	s_waitcnt lgkmcnt(0)
	v_bfi_b32 v32, s65, v32, v32
	v_cvt_pk_bf16_f32 v38, v6, v29
	v_mfma_f32_16x16x32_bf16 v[34:37], v[34:37], v[10:13], v[42:45]
	v_add_f32_e32 v21, v19, v8
	ds_read2_b64 v[8:11], v7 offset0:88 offset1:92
	ds_read2_b64 v[26:29], v0 offset0:120 offset1:124
	v_mfma_f32_16x16x32_bf16 v[2:5], v[30:33], v[38:41], v[2:5]
	ds_read2_b64 v[30:33], v20 offset0:152 offset1:156
	ds_bpermute_b32 v0, v58, v21
	s_waitcnt lgkmcnt(3)
	v_bfi_b32 v10, s65, v10, v10
	s_waitcnt lgkmcnt(2)
	v_bfi_b32 v28, s65, v28, v28
	s_waitcnt lgkmcnt(1)
	v_bfi_b32 v32, s65, v32, v32
	s_waitcnt lgkmcnt(0)
	v_add_f32_e32 v0, v21, v0
	ds_bpermute_b32 v18, v57, v0
	v_mfma_f32_16x16x32_bf16 v[6:9], v[8:11], v[38:41], v[34:37]
	v_mfma_f32_16x16x32_bf16 v[10:13], v[26:29], v[38:41], v[14:17]
	v_mfma_f32_16x16x32_bf16 v[14:17], v[30:33], v[38:41], v[22:25]
	s_cbranch_vccnz .LBB0_1351
	s_waitcnt lgkmcnt(0)
	v_add_f32_e32 v0, v0, v18
	v_div_scale_f32 v18, s[4:5], v0, v0, 1.0
	v_rcp_f32_e32 v19, v18
	v_mov_b32_e32 v57, v1
	v_lshl_add_u64 v[20:21], v[54:55], 0, v[56:57]
	v_fma_f32 v22, -v18, v19, 1.0
	v_fmac_f32_e32 v19, v22, v19
	v_div_scale_f32 v22, vcc, 1.0, v0, 1.0
	v_mul_f32_e32 v23, v22, v19
	v_fma_f32 v24, -v18, v23, v22
	v_fmac_f32_e32 v23, v24, v19
	v_fma_f32 v18, -v18, v23, v22
	v_div_fmas_f32 v18, v18, v19, v23
	v_div_fixup_f32 v0, v18, v0, 1.0
	v_pk_mul_f32 v[4:5], v[0:1], v[4:5] op_sel_hi:[0,1]
	v_pk_mul_f32 v[2:3], v[0:1], v[2:3] op_sel_hi:[0,1]
	v_cvt_pk_bf16_f32 v5, v4, v5
	v_cvt_pk_bf16_f32 v4, v2, v3
	global_store_dwordx2 v[20:21], v[4:5], off
	v_pk_mul_f32 v[2:3], v[0:1], v[8:9] op_sel_hi:[0,1]
	v_pk_mul_f32 v[4:5], v[0:1], v[6:7] op_sel_hi:[0,1]
	v_cvt_pk_bf16_f32 v3, v2, v3
	v_cvt_pk_bf16_f32 v2, v4, v5
	global_store_dwordx2 v[20:21], v[2:3], off offset:32
	v_pk_mul_f32 v[2:3], v[0:1], v[12:13] op_sel_hi:[0,1]
	v_pk_mul_f32 v[4:5], v[0:1], v[10:11] op_sel_hi:[0,1]
	v_cvt_pk_bf16_f32 v3, v2, v3
	v_cvt_pk_bf16_f32 v2, v4, v5
	global_store_dwordx2 v[20:21], v[2:3], off offset:64
	v_pk_mul_f32 v[2:3], v[0:1], v[16:17] op_sel_hi:[0,1]
	v_pk_mul_f32 v[4:5], v[0:1], v[14:15] op_sel_hi:[0,1]
	v_cvt_pk_bf16_f32 v3, v2, v3
	v_cvt_pk_bf16_f32 v2, v4, v5
	global_store_dwordx2 v[20:21], v[2:3], off offset:96

; __device__ __forceinline__ int opaque_tid() { int t = threadIdx.x; asm volatile("" : "+v"(t)); return t; }
; __device__ void transpose_item(const Params& p, int item) {
;   unsigned char* ws = p.ws;
;   const int tid = opaque_tid();
;   const bf16_t* PT = (const bf16_t*)p.out;
;   bf16_t* cat = (bf16_t*)(ws + O_S + S_CAT);
;   bf16_t* tl = (bf16_t*)smem;
;   const int cb = item % 12, tb = item / 12;
;   const int ch0 = cb * 64, t0 = tb * 128;
;   for (int i = 0; i < 2; ++i) {
;     int idx = tid + 512 * i;
;     int row = idx >> 4, c8 = (idx & 15) * 8;
;     uint4 u = *(const uint4*)(PT + (size_t)(ch0 + row) * T_TOK + t0 + c8);
;     unsigned* d = (unsigned*)(tl + row * 130 + c8);
;     d[0] = u.x; d[1] = u.y; d[2] = u.z; d[3] = u.w;
;   }
;   __syncthreads();
;   for (int i = 0; i < 2; ++i) {
;     int idx = tid + 512 * i;
;     int tok = idx >> 3, c8 = (idx & 7) * 8;
;     unsigned short v[8];
;     for (int j = 0; j < 8; ++j) v[j] = tl[(c8 + j) * 130 + tok];
;     uint4 o;
;     o.x = v[0] | ((unsigned)v[1] << 16); o.y = v[2] | ((unsigned)v[3] << 16);
;     o.z = v[4] | ((unsigned)v[5] << 16); o.w = v[6] | ((unsigned)v[7] << 16);
;     *(uint4*)(cat + (size_t)(t0 + tok) * 1024 + ch0 + c8) = o;
;   }
.LBB0_1353:
	s_mov_b64 s[4:5], -1
	s_and_b64 vcc, exec, s[2:3]
	s_cbranch_vccz .LBB0_1355
	s_mul_hi_i32 s4, s88, 0x2aaaaaab
	v_mov_b32_e32 v10, v208
	s_lshr_b32 s5, s4, 31
	s_ashr_i32 s4, s4, 1
	s_add_i32 s4, s4, s5
	s_load_dwordx4 s[28:31], s[72:73], 0xe8
	s_mul_i32 s5, s4, 12
	s_sub_i32 s5, s88, s5
	s_lshl_b32 s4, s4, 7
	s_lshl_b32 s6, s5, 6
	s_ashr_i32 s5, s4, 31
	s_lshl_b64 s[8:9], s[4:5], 1
	v_ashrrev_i32_e32 v4, 4, v10
	s_waitcnt lgkmcnt(0)
	s_add_u32 s8, s30, s8
	v_lshlrev_b32_e32 v0, 4, v10
	v_add_u32_e32 v2, s6, v4
	s_addc_u32 s9, s31, s9
	v_and_b32_e32 v0, 0xf0, v0
	v_ashrrev_i32_e32 v3, 31, v2
	v_lshl_add_u64 v[6:7], s[8:9], 0, v[0:1]
	v_lshlrev_b64 v[2:3], 17, v[2:3]
	v_lshl_add_u64 v[2:3], v[6:7], 0, v[2:3]
	s_movk_i32 s5, 0x104
	v_mad_u64_u32 v[8:9], s[8:9], v4, s5, v[0:1]
	global_load_dwordx4 v[2:5], v[2:3], off
	v_add_u32_e32 v12, 0x200, v10
	v_ashrrev_i32_e32 v178, 4, v12
	v_add_u32_e32 v178, s6, v178
	v_ashrrev_i32_e32 v179, 31, v178
	v_lshlrev_b64 v[178:179], 17, v[178:179]
	v_lshl_add_u64 v[178:179], v[6:7], 0, v[178:179]
	global_load_dwordx4 v[180:183], v[178:179], off
	s_ashr_i32 s7, s6, 31
	v_lshlrev_b32_e32 v11, 3, v10
	s_waitcnt vmcnt(1)
	ds_write2_b32 v8, v2, v3 offset1:1
	ds_write2_b32 v8, v4, v5 offset0:2 offset1:3
	v_ashrrev_i32_e32 v4, 4, v12
	v_mad_u64_u32 v[6:7], s[8:9], v4, s5, v[0:1]
	s_lshl_b64 s[6:7], s[6:7], 1
	s_add_u32 s6, s12, s6
	s_addc_u32 s7, s13, s7
	v_ashrrev_i32_e32 v8, 3, v10
	s_mov_b32 s5, 0x5040100
	s_waitcnt vmcnt(0)
	ds_write2_b32 v6, v180, v181 offset1:1
	ds_write2_b32 v6, v182, v183 offset0:2 offset1:3
	v_and_b32_e32 v2, 56, v11
	v_lshlrev_b32_e32 v0, 1, v2
	v_lshl_add_u64 v[6:7], s[6:7], 0, v[0:1]
	v_mul_u32_u24_e32 v0, 0x104, v2
	v_lshl_add_u32 v2, v8, 1, v0
	s_waitcnt lgkmcnt(0)
	s_barrier
	ds_read_u16 v9, v2
	ds_read_u16 v10, v2 offset:260
	ds_read_u16 v3, v2 offset:520
	ds_read_u16 v11, v2 offset:780
	ds_read_u16 v4, v2 offset:1040
	ds_read_u16 v13, v2 offset:1300
	ds_read_u16 v5, v2 offset:1560
	ds_read_u16 v2, v2 offset:1820
	v_add_u32_e32 v8, s4, v8
	s_waitcnt lgkmcnt(4)
	v_perm_b32 v3, v11, v3, s5
	s_waitcnt lgkmcnt(2)
	v_perm_b32 v4, v13, v4, s5
	s_waitcnt lgkmcnt(0)
	v_perm_b32 v5, v2, v5, s5
	v_perm_b32 v2, v10, v9, s5
	v_ashrrev_i32_e32 v9, 31, v8
	v_lshlrev_b64 v[8:9], 11, v[8:9]
	v_lshl_add_u64 v[8:9], v[6:7], 0, v[8:9]
	global_store_dwordx4 v[8:9], v[2:5], off
	v_ashrrev_i32_e32 v8, 3, v12
	v_lshl_add_u32 v0, v8, 1, v0
	ds_read_u16 v2, v0
	ds_read_u16 v9, v0 offset:260
	ds_read_u16 v3, v0 offset:520
	ds_read_u16 v10, v0 offset:780
	ds_read_u16 v4, v0 offset:1040
	ds_read_u16 v11, v0 offset:1300
	ds_read_u16 v5, v0 offset:1560
	ds_read_u16 v0, v0 offset:1820
	v_add_u32_e32 v8, s4, v8
	s_waitcnt lgkmcnt(6)
	v_perm_b32 v2, v9, v2, s5
	v_ashrrev_i32_e32 v9, 31, v8
	v_lshlrev_b64 v[8:9], 11, v[8:9]
	s_waitcnt lgkmcnt(0)
	v_perm_b32 v5, v0, v5, s5
	v_perm_b32 v4, v11, v4, s5
	v_perm_b32 v3, v10, v3, s5
	v_lshl_add_u64 v[6:7], v[6:7], 0, v[8:9]
	global_store_dwordx4 v[6:7], v[2:5], off
	s_barrier
	s_mov_b64 s[4:5], 0
